# hand-pipelined LayerNorm phases (loads two rows ahead, DPP reductions, gamma/beta via LDS)
# speedup vs baseline: 1.0511x; 1.0511x over previous
.LBB0_1083:
	s_or_b64 exec, exec, s[2:3]
	v_readlane_b32 s2, v241, 9
	v_readlane_b32 s3, v241, 10
	v_readlane_b32 s3, v241, 0
	s_waitcnt lgkmcnt(0)
	s_barrier
	v_mov_b32_e32 v0, v178
	v_readlane_b32 s2, v239, 2
	v_ashrrev_i32_e32 v1, 6, v0
	s_nop 0
	v_add_u32_e32 v32, s2, v1
	s_movk_i32 s2, 0x2400
	v_cmp_gt_i32_e32 vcc, s2, v32
	s_and_saveexec_b64 s[2:3], vcc
	s_cbranch_execz .LBB0_1118
	v_readlane_b32 s30, v241, 9
	s_cmpk_lg_i32 s30, 0x100
	s_cbranch_scc1 .Lln1_old
	v_readlane_b32 s38, v241, 0
	v_readlane_b32 s12, v239, 42
	v_readlane_b32 s13, v239, 43
	v_readlane_b32 s30, v239, 37
	s_add_u32 s4, s12, 0xc700000
	s_addc_u32 s5, s13, 0
	s_add_u32 s6, s12, 0x1d080000
	s_addc_u32 s7, s13, 0
	s_add_u32 s8, s12, 0x33ac0000
	s_addc_u32 s9, s13, 0
	s_lshl_b32 s30, s30, 13
	v_readlane_b32 s40, v241, 33
	v_readlane_b32 s41, v241, 34
	v_readlane_b32 s42, v241, 35
	v_readlane_b32 s43, v241, 36
	s_add_u32 s40, s40, s30
	s_addc_u32 s41, s41, 0
	s_add_u32 s42, s42, s30
	s_addc_u32 s43, s43, 0
	v_lshlrev_b32_e32 v252, 4, v178
	global_load_dwordx4 v[0:3], v252, s[40:41]
	global_load_dwordx4 v[4:7], v252, s[42:43]
	v_lshrrev_b32_e32 v253, 7, v178
	v_lshlrev_b32_e32 v253, 11, v253
	v_and_b32_e32 v254, 1, v178
	v_lshl_or_b32 v253, v254, 10, v253
	v_bfe_u32 v254, v178, 1, 6
	v_lshl_or_b32 v253, v254, 3, v253
	v_readfirstlane_b32 s36, v178
	v_and_b32_e32 v168, 63, v178
	s_lshr_b32 s36, s36, 6
	s_lshl_b32 s30, s38, 3
	s_add_i32 s30, s30, s36
	s_lshl_b32 s30, s30, 12
	v_lshl_add_u32 v90, v168, 4, s30
	v_lshlrev_b32_e32 v168, 3, v168
	s_waitcnt vmcnt(0)
	ds_write_b64 v253, v[0:1]
	ds_write_b64 v253, v[2:3] offset:512
	ds_write_b64 v253, v[4:5] offset:8192
	ds_write_b64 v253, v[6:7] offset:8704
	s_waitcnt lgkmcnt(0)
	s_barrier
	global_load_dwordx4 v[0:3], v90, s[4:5]
	global_load_dwordx4 v[4:7], v90, s[4:5] offset:1024
	global_load_dwordx4 v[8:11], v90, s[4:5] offset:2048
	global_load_dwordx4 v[12:15], v90, s[4:5] offset:3072
	global_load_dwordx4 v[16:19], v90, s[6:7]
	global_load_dwordx4 v[20:23], v90, s[6:7] offset:1024
	global_load_dwordx4 v[24:27], v90, s[6:7] offset:2048
	global_load_dwordx4 v[28:31], v90, s[6:7] offset:3072
	s_add_u32 s12, s4, 0x800000
	s_addc_u32 s13, s5, 0
	global_load_dwordx4 v[32:35], v90, s[12:13]
	global_load_dwordx4 v[36:39], v90, s[12:13] offset:1024
	global_load_dwordx4 v[40:43], v90, s[12:13] offset:2048
	global_load_dwordx4 v[44:47], v90, s[12:13] offset:3072
	s_add_u32 s12, s6, 0x800000
	s_addc_u32 s13, s7, 0
	global_load_dwordx4 v[48:51], v90, s[12:13]
	global_load_dwordx4 v[52:55], v90, s[12:13] offset:1024
	global_load_dwordx4 v[56:59], v90, s[12:13] offset:2048
	global_load_dwordx4 v[60:63], v90, s[12:13] offset:3072
	s_waitcnt vmcnt(8)
	v_lshlrev_b32_e32 v64, 16, v16
	v_and_b32_e32 v65, 0xffff0000, v16
	v_and_b32_e32 v252, 0xffff0000, v0
	v_lshlrev_b32_e32 v0, 16, v0
	v_fmac_f32_e32 v64, 0x3fb504f3, v0
	v_fmac_f32_e32 v65, 0x3fb504f3, v252
	v_lshlrev_b32_e32 v66, 16, v17
	v_and_b32_e32 v67, 0xffff0000, v17
	v_and_b32_e32 v252, 0xffff0000, v1
	v_lshlrev_b32_e32 v1, 16, v1
	v_fmac_f32_e32 v66, 0x3fb504f3, v1
	v_fmac_f32_e32 v67, 0x3fb504f3, v252
	v_add_f32_e32 v252, v64, v65
	v_add_f32_e32 v253, v66, v67
	v_add_f32_e32 v254, v252, v253
	v_lshlrev_b32_e32 v68, 16, v18
	v_and_b32_e32 v69, 0xffff0000, v18
	v_and_b32_e32 v252, 0xffff0000, v2
	v_lshlrev_b32_e32 v2, 16, v2
	v_fmac_f32_e32 v68, 0x3fb504f3, v2
	v_fmac_f32_e32 v69, 0x3fb504f3, v252
	v_lshlrev_b32_e32 v70, 16, v19
	v_and_b32_e32 v71, 0xffff0000, v19
	v_and_b32_e32 v252, 0xffff0000, v3
	v_lshlrev_b32_e32 v3, 16, v3
	v_fmac_f32_e32 v70, 0x3fb504f3, v3
	v_fmac_f32_e32 v71, 0x3fb504f3, v252
	v_add_f32_e32 v252, v68, v69
	v_add_f32_e32 v253, v70, v71
	v_add_f32_e32 v252, v252, v253
	v_add_f32_e32 v254, v254, v252
	v_lshlrev_b32_e32 v72, 16, v20
	v_and_b32_e32 v73, 0xffff0000, v20
	v_and_b32_e32 v252, 0xffff0000, v4
	v_lshlrev_b32_e32 v4, 16, v4
	v_fmac_f32_e32 v72, 0x3fb504f3, v4
	v_fmac_f32_e32 v73, 0x3fb504f3, v252
	v_lshlrev_b32_e32 v74, 16, v21
	v_and_b32_e32 v75, 0xffff0000, v21
	v_and_b32_e32 v252, 0xffff0000, v5
	v_lshlrev_b32_e32 v5, 16, v5
	v_fmac_f32_e32 v74, 0x3fb504f3, v5
	v_fmac_f32_e32 v75, 0x3fb504f3, v252
	v_add_f32_e32 v252, v72, v73
	v_add_f32_e32 v253, v74, v75
	v_add_f32_e32 v252, v252, v253
	v_add_f32_e32 v254, v254, v252
	v_lshlrev_b32_e32 v76, 16, v22
	v_and_b32_e32 v77, 0xffff0000, v22
	v_and_b32_e32 v252, 0xffff0000, v6
	v_lshlrev_b32_e32 v6, 16, v6
	v_fmac_f32_e32 v76, 0x3fb504f3, v6
	v_fmac_f32_e32 v77, 0x3fb504f3, v252
	v_lshlrev_b32_e32 v78, 16, v23
	v_and_b32_e32 v79, 0xffff0000, v23
	v_and_b32_e32 v252, 0xffff0000, v7
	v_lshlrev_b32_e32 v7, 16, v7
	v_fmac_f32_e32 v78, 0x3fb504f3, v7
	v_fmac_f32_e32 v79, 0x3fb504f3, v252
	v_add_f32_e32 v252, v76, v77
	v_add_f32_e32 v253, v78, v79
	v_add_f32_e32 v252, v252, v253
	v_add_f32_e32 v254, v254, v252
	v_lshlrev_b32_e32 v80, 16, v24
	v_and_b32_e32 v81, 0xffff0000, v24
	v_and_b32_e32 v252, 0xffff0000, v8
	v_lshlrev_b32_e32 v8, 16, v8
	v_fmac_f32_e32 v80, 0x3fb504f3, v8
	v_fmac_f32_e32 v81, 0x3fb504f3, v252
	v_lshlrev_b32_e32 v82, 16, v25
	v_and_b32_e32 v83, 0xffff0000, v25
	v_and_b32_e32 v252, 0xffff0000, v9
	v_lshlrev_b32_e32 v9, 16, v9
	v_fmac_f32_e32 v82, 0x3fb504f3, v9
	v_fmac_f32_e32 v83, 0x3fb504f3, v252
	v_add_f32_e32 v252, v80, v81
	v_add_f32_e32 v253, v82, v83
	v_add_f32_e32 v252, v252, v253
	v_add_f32_e32 v254, v254, v252
	v_lshlrev_b32_e32 v84, 16, v26
	v_and_b32_e32 v85, 0xffff0000, v26
	v_and_b32_e32 v252, 0xffff0000, v10
	v_lshlrev_b32_e32 v10, 16, v10
	v_fmac_f32_e32 v84, 0x3fb504f3, v10
	v_fmac_f32_e32 v85, 0x3fb504f3, v252
	v_lshlrev_b32_e32 v86, 16, v27
	v_and_b32_e32 v87, 0xffff0000, v27
	v_and_b32_e32 v252, 0xffff0000, v11
	v_lshlrev_b32_e32 v11, 16, v11
	v_fmac_f32_e32 v86, 0x3fb504f3, v11
	v_fmac_f32_e32 v87, 0x3fb504f3, v252
	v_add_f32_e32 v252, v84, v85
	v_add_f32_e32 v253, v86, v87
	v_add_f32_e32 v252, v252, v253
	v_add_f32_e32 v254, v254, v252
	v_lshlrev_b32_e32 v244, 16, v28
	v_and_b32_e32 v245, 0xffff0000, v28
	v_and_b32_e32 v252, 0xffff0000, v12
	v_lshlrev_b32_e32 v12, 16, v12
	v_fmac_f32_e32 v244, 0x3fb504f3, v12
	v_fmac_f32_e32 v245, 0x3fb504f3, v252
	v_lshlrev_b32_e32 v246, 16, v29
	v_and_b32_e32 v247, 0xffff0000, v29
	v_and_b32_e32 v252, 0xffff0000, v13
	v_lshlrev_b32_e32 v13, 16, v13
	v_fmac_f32_e32 v246, 0x3fb504f3, v13
	v_fmac_f32_e32 v247, 0x3fb504f3, v252
	v_add_f32_e32 v252, v244, v245
	v_add_f32_e32 v253, v246, v247
	v_add_f32_e32 v252, v252, v253
	v_add_f32_e32 v254, v254, v252
	v_lshlrev_b32_e32 v248, 16, v30
	v_and_b32_e32 v249, 0xffff0000, v30
	v_and_b32_e32 v252, 0xffff0000, v14
	v_lshlrev_b32_e32 v14, 16, v14
	v_fmac_f32_e32 v248, 0x3fb504f3, v14
	v_fmac_f32_e32 v249, 0x3fb504f3, v252
	v_lshlrev_b32_e32 v250, 16, v31
	v_and_b32_e32 v251, 0xffff0000, v31
	v_and_b32_e32 v252, 0xffff0000, v15
	v_lshlrev_b32_e32 v15, 16, v15
	v_fmac_f32_e32 v250, 0x3fb504f3, v15
	v_fmac_f32_e32 v251, 0x3fb504f3, v252
	v_add_f32_e32 v252, v248, v249
	v_add_f32_e32 v253, v250, v251
	v_add_f32_e32 v252, v252, v253
	v_add_f32_e32 v254, v254, v252
	s_add_u32 s12, s4, 0x1000000
	s_addc_u32 s13, s5, 0
	global_load_dwordx4 v[0:3], v90, s[12:13]
	global_load_dwordx4 v[4:7], v90, s[12:13] offset:1024
	global_load_dwordx4 v[8:11], v90, s[12:13] offset:2048
	global_load_dwordx4 v[12:15], v90, s[12:13] offset:3072
	s_add_u32 s12, s6, 0x1000000
	s_addc_u32 s13, s7, 0
	global_load_dwordx4 v[16:19], v90, s[12:13]
	global_load_dwordx4 v[20:23], v90, s[12:13] offset:1024
	global_load_dwordx4 v[24:27], v90, s[12:13] offset:2048
	global_load_dwordx4 v[28:31], v90, s[12:13] offset:3072
	s_nop 1
	v_add_f32_dpp v252, v254, v254 quad_perm:[1,0,3,2] row_mask:0xf bank_mask:0xf
	s_nop 1
	v_add_f32_dpp v252, v252, v252 quad_perm:[2,3,0,1] row_mask:0xf bank_mask:0xf
	s_nop 1
	v_add_f32_dpp v252, v252, v252 row_half_mirror row_mask:0xf bank_mask:0xf
	s_nop 1
	v_add_f32_dpp v252, v252, v252 row_mirror row_mask:0xf bank_mask:0xf
	s_nop 1
	v_readlane_b32 s40, v252, 0
	v_readlane_b32 s41, v252, 16
	v_readlane_b32 s42, v252, 32
	v_readlane_b32 s43, v252, 48
	s_nop 1
	v_mov_b32_e32 v253, s40
	v_add_f32_e32 v253, s41, v253
	v_add_f32_e32 v253, s42, v253
	v_add_f32_e32 v253, s43, v253
	v_mul_f32_e32 v253, 0x3a000000, v253
	s_nop 0
	v_readfirstlane_b32 s37, v253
	s_nop 1
	v_subrev_f32_e32 v64, s37, v64
	v_subrev_f32_e32 v65, s37, v65
	v_subrev_f32_e32 v66, s37, v66
	v_subrev_f32_e32 v67, s37, v67
	v_subrev_f32_e32 v68, s37, v68
	v_subrev_f32_e32 v69, s37, v69
	v_subrev_f32_e32 v70, s37, v70
	v_subrev_f32_e32 v71, s37, v71
	v_mul_f32_e32 v252, v64, v64
	v_fmac_f32_e32 v252, v65, v65
	v_mul_f32_e32 v253, v66, v66
	v_fmac_f32_e32 v253, v67, v67
	v_add_f32_e32 v254, v252, v253
	v_mul_f32_e32 v252, v68, v68
	v_fmac_f32_e32 v252, v69, v69
	v_mul_f32_e32 v253, v70, v70
	v_fmac_f32_e32 v253, v71, v71
	v_add_f32_e32 v252, v252, v253
	v_add_f32_e32 v254, v254, v252
	v_subrev_f32_e32 v72, s37, v72
	v_subrev_f32_e32 v73, s37, v73
	v_subrev_f32_e32 v74, s37, v74
	v_subrev_f32_e32 v75, s37, v75
	v_subrev_f32_e32 v76, s37, v76
	v_subrev_f32_e32 v77, s37, v77
	v_subrev_f32_e32 v78, s37, v78
	v_subrev_f32_e32 v79, s37, v79
	v_mul_f32_e32 v252, v72, v72
	v_fmac_f32_e32 v252, v73, v73
	v_mul_f32_e32 v253, v74, v74
	v_fmac_f32_e32 v253, v75, v75
	v_add_f32_e32 v252, v252, v253
	v_add_f32_e32 v254, v254, v252
	v_mul_f32_e32 v252, v76, v76
	v_fmac_f32_e32 v252, v77, v77
	v_mul_f32_e32 v253, v78, v78
	v_fmac_f32_e32 v253, v79, v79
	v_add_f32_e32 v252, v252, v253
	v_add_f32_e32 v254, v254, v252
	v_subrev_f32_e32 v80, s37, v80
	v_subrev_f32_e32 v81, s37, v81
	v_subrev_f32_e32 v82, s37, v82
	v_subrev_f32_e32 v83, s37, v83
	v_subrev_f32_e32 v84, s37, v84
	v_subrev_f32_e32 v85, s37, v85
	v_subrev_f32_e32 v86, s37, v86
	v_subrev_f32_e32 v87, s37, v87
	v_mul_f32_e32 v252, v80, v80
	v_fmac_f32_e32 v252, v81, v81
	v_mul_f32_e32 v253, v82, v82
	v_fmac_f32_e32 v253, v83, v83
	v_add_f32_e32 v252, v252, v253
	v_add_f32_e32 v254, v254, v252
	v_mul_f32_e32 v252, v84, v84
	v_fmac_f32_e32 v252, v85, v85
	v_mul_f32_e32 v253, v86, v86
	v_fmac_f32_e32 v253, v87, v87
	v_add_f32_e32 v252, v252, v253
	v_add_f32_e32 v254, v254, v252
	v_subrev_f32_e32 v244, s37, v244
	v_subrev_f32_e32 v245, s37, v245
	v_subrev_f32_e32 v246, s37, v246
	v_subrev_f32_e32 v247, s37, v247
	v_subrev_f32_e32 v248, s37, v248
	v_subrev_f32_e32 v249, s37, v249
	v_subrev_f32_e32 v250, s37, v250
	v_subrev_f32_e32 v251, s37, v251
	v_mul_f32_e32 v252, v244, v244
	v_fmac_f32_e32 v252, v245, v245
	v_mul_f32_e32 v253, v246, v246
	v_fmac_f32_e32 v253, v247, v247
	v_add_f32_e32 v252, v252, v253
	v_add_f32_e32 v254, v254, v252
	v_mul_f32_e32 v252, v248, v248
	v_fmac_f32_e32 v252, v249, v249
	v_mul_f32_e32 v253, v250, v250
	v_fmac_f32_e32 v253, v251, v251
	v_add_f32_e32 v252, v252, v253
	v_add_f32_e32 v254, v254, v252
	s_nop 1
	v_add_f32_dpp v252, v254, v254 quad_perm:[1,0,3,2] row_mask:0xf bank_mask:0xf
	s_nop 1
	v_add_f32_dpp v252, v252, v252 quad_perm:[2,3,0,1] row_mask:0xf bank_mask:0xf
	s_nop 1
	v_add_f32_dpp v252, v252, v252 row_half_mirror row_mask:0xf bank_mask:0xf
	s_nop 1
	v_add_f32_dpp v252, v252, v252 row_mirror row_mask:0xf bank_mask:0xf
	s_nop 1
	v_readlane_b32 s40, v252, 0
	v_readlane_b32 s41, v252, 16
	v_readlane_b32 s42, v252, 32
	v_readlane_b32 s43, v252, 48
	s_nop 1
	v_mov_b32_e32 v253, s40
	v_add_f32_e32 v253, s41, v253
	v_add_f32_e32 v253, s42, v253
	v_add_f32_e32 v253, s43, v253
	v_mov_b32_e32 v252, 0x3a000000
	v_fmaak_f32 v253, v253, v252, 0x3727c5ac
	v_rsq_f32_e32 v253, v253
	s_nop 1
	v_readfirstlane_b32 s37, v253
	s_mov_b32 s12, s4
	s_mov_b32 s13, s5
	ds_read_b64 v[252:253], v168
	ds_read_b64 v[254:255], v168 offset:8192
	ds_read_b64 v[88:89], v168 offset:512
	ds_read_b64 v[242:243], v168 offset:8704
	s_waitcnt lgkmcnt(2)
	v_mul_f32_e32 v64, s37, v64
	v_mul_f32_e32 v65, s37, v65
	v_fma_f32 v64, v64, v252, v254
	v_fma_f32 v65, v65, v253, v255
	ds_read_b64 v[252:253], v168 offset:1024
	ds_read_b64 v[254:255], v168 offset:9216
	s_waitcnt lgkmcnt(2)
	v_mul_f32_e32 v66, s37, v66
	v_mul_f32_e32 v67, s37, v67
	v_fma_f32 v66, v66, v88, v242
	v_fma_f32 v67, v67, v89, v243
	ds_read_b64 v[88:89], v168 offset:1536
	ds_read_b64 v[242:243], v168 offset:9728
	s_waitcnt lgkmcnt(2)
	v_mul_f32_e32 v68, s37, v68
	v_mul_f32_e32 v69, s37, v69
	v_fma_f32 v68, v68, v252, v254
	v_fma_f32 v69, v69, v253, v255
	ds_read_b64 v[252:253], v168 offset:2048
	ds_read_b64 v[254:255], v168 offset:10240
	s_waitcnt lgkmcnt(2)
	v_mul_f32_e32 v70, s37, v70
	v_mul_f32_e32 v71, s37, v71
	v_fma_f32 v70, v70, v88, v242
	v_fma_f32 v71, v71, v89, v243
	v_cvt_pk_bf16_f32 v64, v64, v65
	v_cvt_pk_bf16_f32 v65, v66, v67
	v_cvt_pk_bf16_f32 v66, v68, v69
	v_cvt_pk_bf16_f32 v67, v70, v71
	global_store_dwordx4 v90, v[64:67], s[12:13]
	ds_read_b64 v[88:89], v168 offset:2560
	ds_read_b64 v[242:243], v168 offset:10752
	s_waitcnt lgkmcnt(2)
	v_mul_f32_e32 v72, s37, v72
	v_mul_f32_e32 v73, s37, v73
	v_fma_f32 v72, v72, v252, v254
	v_fma_f32 v73, v73, v253, v255
	ds_read_b64 v[252:253], v168 offset:3072
	ds_read_b64 v[254:255], v168 offset:11264
	s_waitcnt lgkmcnt(2)
	v_mul_f32_e32 v74, s37, v74
	v_mul_f32_e32 v75, s37, v75
	v_fma_f32 v74, v74, v88, v242
	v_fma_f32 v75, v75, v89, v243
	ds_read_b64 v[88:89], v168 offset:3584
	ds_read_b64 v[242:243], v168 offset:11776
	s_waitcnt lgkmcnt(2)
	v_mul_f32_e32 v76, s37, v76
	v_mul_f32_e32 v77, s37, v77
	v_fma_f32 v76, v76, v252, v254
	v_fma_f32 v77, v77, v253, v255
	ds_read_b64 v[252:253], v168 offset:4096
	ds_read_b64 v[254:255], v168 offset:12288
	s_waitcnt lgkmcnt(2)
	v_mul_f32_e32 v78, s37, v78
	v_mul_f32_e32 v79, s37, v79
	v_fma_f32 v78, v78, v88, v242
	v_fma_f32 v79, v79, v89, v243
	v_cvt_pk_bf16_f32 v72, v72, v73
	v_cvt_pk_bf16_f32 v73, v74, v75
	v_cvt_pk_bf16_f32 v74, v76, v77
	v_cvt_pk_bf16_f32 v75, v78, v79
	global_store_dwordx4 v90, v[72:75], s[12:13] offset:1024
	ds_read_b64 v[88:89], v168 offset:4608
	ds_read_b64 v[242:243], v168 offset:12800
	s_waitcnt lgkmcnt(2)
	v_mul_f32_e32 v80, s37, v80
	v_mul_f32_e32 v81, s37, v81
	v_fma_f32 v80, v80, v252, v254
	v_fma_f32 v81, v81, v253, v255
	ds_read_b64 v[252:253], v168 offset:5120
	ds_read_b64 v[254:255], v168 offset:13312
	s_waitcnt lgkmcnt(2)
	v_mul_f32_e32 v82, s37, v82
	v_mul_f32_e32 v83, s37, v83
	v_fma_f32 v82, v82, v88, v242
	v_fma_f32 v83, v83, v89, v243
	ds_read_b64 v[88:89], v168 offset:5632
	ds_read_b64 v[242:243], v168 offset:13824
	s_waitcnt lgkmcnt(2)
	v_mul_f32_e32 v84, s37, v84
	v_mul_f32_e32 v85, s37, v85
	v_fma_f32 v84, v84, v252, v254
	v_fma_f32 v85, v85, v253, v255
	ds_read_b64 v[252:253], v168 offset:6144
	ds_read_b64 v[254:255], v168 offset:14336
	s_waitcnt lgkmcnt(2)
	v_mul_f32_e32 v86, s37, v86
	v_mul_f32_e32 v87, s37, v87
	v_fma_f32 v86, v86, v88, v242
	v_fma_f32 v87, v87, v89, v243
	v_cvt_pk_bf16_f32 v80, v80, v81
	v_cvt_pk_bf16_f32 v81, v82, v83
	v_cvt_pk_bf16_f32 v82, v84, v85
	v_cvt_pk_bf16_f32 v83, v86, v87
	global_store_dwordx4 v90, v[80:83], s[12:13] offset:2048
	ds_read_b64 v[88:89], v168 offset:6656
	ds_read_b64 v[242:243], v168 offset:14848
	s_waitcnt lgkmcnt(2)
	v_mul_f32_e32 v244, s37, v244
	v_mul_f32_e32 v245, s37, v245
	v_fma_f32 v244, v244, v252, v254
	v_fma_f32 v245, v245, v253, v255
	ds_read_b64 v[252:253], v168 offset:7168
	ds_read_b64 v[254:255], v168 offset:15360
	s_waitcnt lgkmcnt(2)
	v_mul_f32_e32 v246, s37, v246
	v_mul_f32_e32 v247, s37, v247
	v_fma_f32 v246, v246, v88, v242
	v_fma_f32 v247, v247, v89, v243
	ds_read_b64 v[88:89], v168 offset:7680
	ds_read_b64 v[242:243], v168 offset:15872
	s_waitcnt lgkmcnt(2)
	v_mul_f32_e32 v248, s37, v248
	v_mul_f32_e32 v249, s37, v249
	v_fma_f32 v248, v248, v252, v254
	v_fma_f32 v249, v249, v253, v255
	s_waitcnt lgkmcnt(0)
	v_mul_f32_e32 v250, s37, v250
	v_mul_f32_e32 v251, s37, v251
	v_fma_f32 v250, v250, v88, v242
	v_fma_f32 v251, v251, v89, v243
	v_cvt_pk_bf16_f32 v244, v244, v245
	v_cvt_pk_bf16_f32 v245, v246, v247
	v_cvt_pk_bf16_f32 v246, v248, v249
	v_cvt_pk_bf16_f32 v247, v250, v251
	global_store_dwordx4 v90, v[244:247], s[12:13] offset:3072
	s_waitcnt vmcnt(12)
	v_lshlrev_b32_e32 v64, 16, v48
	v_and_b32_e32 v65, 0xffff0000, v48
	v_and_b32_e32 v252, 0xffff0000, v32
	v_lshlrev_b32_e32 v32, 16, v32
	v_fmac_f32_e32 v64, 0x3fb504f3, v32
	v_fmac_f32_e32 v65, 0x3fb504f3, v252
	v_lshlrev_b32_e32 v66, 16, v49
	v_and_b32_e32 v67, 0xffff0000, v49
	v_and_b32_e32 v252, 0xffff0000, v33
	v_lshlrev_b32_e32 v33, 16, v33
	v_fmac_f32_e32 v66, 0x3fb504f3, v33
	v_fmac_f32_e32 v67, 0x3fb504f3, v252
	v_add_f32_e32 v252, v64, v65
	v_add_f32_e32 v253, v66, v67
	v_add_f32_e32 v254, v252, v253
	v_lshlrev_b32_e32 v68, 16, v50
	v_and_b32_e32 v69, 0xffff0000, v50
	v_and_b32_e32 v252, 0xffff0000, v34
	v_lshlrev_b32_e32 v34, 16, v34
	v_fmac_f32_e32 v68, 0x3fb504f3, v34
	v_fmac_f32_e32 v69, 0x3fb504f3, v252
	v_lshlrev_b32_e32 v70, 16, v51
	v_and_b32_e32 v71, 0xffff0000, v51
	v_and_b32_e32 v252, 0xffff0000, v35
	v_lshlrev_b32_e32 v35, 16, v35
	v_fmac_f32_e32 v70, 0x3fb504f3, v35
	v_fmac_f32_e32 v71, 0x3fb504f3, v252
	v_add_f32_e32 v252, v68, v69
	v_add_f32_e32 v253, v70, v71
	v_add_f32_e32 v252, v252, v253
	v_add_f32_e32 v254, v254, v252
	v_lshlrev_b32_e32 v72, 16, v52
	v_and_b32_e32 v73, 0xffff0000, v52
	v_and_b32_e32 v252, 0xffff0000, v36
	v_lshlrev_b32_e32 v36, 16, v36
	v_fmac_f32_e32 v72, 0x3fb504f3, v36
	v_fmac_f32_e32 v73, 0x3fb504f3, v252
	v_lshlrev_b32_e32 v74, 16, v53
	v_and_b32_e32 v75, 0xffff0000, v53
	v_and_b32_e32 v252, 0xffff0000, v37
	v_lshlrev_b32_e32 v37, 16, v37
	v_fmac_f32_e32 v74, 0x3fb504f3, v37
	v_fmac_f32_e32 v75, 0x3fb504f3, v252
	v_add_f32_e32 v252, v72, v73
	v_add_f32_e32 v253, v74, v75
	v_add_f32_e32 v252, v252, v253
	v_add_f32_e32 v254, v254, v252
	v_lshlrev_b32_e32 v76, 16, v54
	v_and_b32_e32 v77, 0xffff0000, v54
	v_and_b32_e32 v252, 0xffff0000, v38
	v_lshlrev_b32_e32 v38, 16, v38
	v_fmac_f32_e32 v76, 0x3fb504f3, v38
	v_fmac_f32_e32 v77, 0x3fb504f3, v252
	v_lshlrev_b32_e32 v78, 16, v55
	v_and_b32_e32 v79, 0xffff0000, v55
	v_and_b32_e32 v252, 0xffff0000, v39
	v_lshlrev_b32_e32 v39, 16, v39
	v_fmac_f32_e32 v78, 0x3fb504f3, v39
	v_fmac_f32_e32 v79, 0x3fb504f3, v252
	v_add_f32_e32 v252, v76, v77
	v_add_f32_e32 v253, v78, v79
	v_add_f32_e32 v252, v252, v253
	v_add_f32_e32 v254, v254, v252
	v_lshlrev_b32_e32 v80, 16, v56
	v_and_b32_e32 v81, 0xffff0000, v56
	v_and_b32_e32 v252, 0xffff0000, v40
	v_lshlrev_b32_e32 v40, 16, v40
	v_fmac_f32_e32 v80, 0x3fb504f3, v40
	v_fmac_f32_e32 v81, 0x3fb504f3, v252
	v_lshlrev_b32_e32 v82, 16, v57
	v_and_b32_e32 v83, 0xffff0000, v57
	v_and_b32_e32 v252, 0xffff0000, v41
	v_lshlrev_b32_e32 v41, 16, v41
	v_fmac_f32_e32 v82, 0x3fb504f3, v41
	v_fmac_f32_e32 v83, 0x3fb504f3, v252
	v_add_f32_e32 v252, v80, v81
	v_add_f32_e32 v253, v82, v83
	v_add_f32_e32 v252, v252, v253
	v_add_f32_e32 v254, v254, v252
	v_lshlrev_b32_e32 v84, 16, v58
	v_and_b32_e32 v85, 0xffff0000, v58
	v_and_b32_e32 v252, 0xffff0000, v42
	v_lshlrev_b32_e32 v42, 16, v42
	v_fmac_f32_e32 v84, 0x3fb504f3, v42
	v_fmac_f32_e32 v85, 0x3fb504f3, v252
	v_lshlrev_b32_e32 v86, 16, v59
	v_and_b32_e32 v87, 0xffff0000, v59
	v_and_b32_e32 v252, 0xffff0000, v43
	v_lshlrev_b32_e32 v43, 16, v43
	v_fmac_f32_e32 v86, 0x3fb504f3, v43
	v_fmac_f32_e32 v87, 0x3fb504f3, v252
	v_add_f32_e32 v252, v84, v85
	v_add_f32_e32 v253, v86, v87
	v_add_f32_e32 v252, v252, v253
	v_add_f32_e32 v254, v254, v252
	v_lshlrev_b32_e32 v244, 16, v60
	v_and_b32_e32 v245, 0xffff0000, v60
	v_and_b32_e32 v252, 0xffff0000, v44
	v_lshlrev_b32_e32 v44, 16, v44
	v_fmac_f32_e32 v244, 0x3fb504f3, v44
	v_fmac_f32_e32 v245, 0x3fb504f3, v252
	v_lshlrev_b32_e32 v246, 16, v61
	v_and_b32_e32 v247, 0xffff0000, v61
	v_and_b32_e32 v252, 0xffff0000, v45
	v_lshlrev_b32_e32 v45, 16, v45
	v_fmac_f32_e32 v246, 0x3fb504f3, v45
	v_fmac_f32_e32 v247, 0x3fb504f3, v252
	v_add_f32_e32 v252, v244, v245
	v_add_f32_e32 v253, v246, v247
	v_add_f32_e32 v252, v252, v253
	v_add_f32_e32 v254, v254, v252
	v_lshlrev_b32_e32 v248, 16, v62
	v_and_b32_e32 v249, 0xffff0000, v62
	v_and_b32_e32 v252, 0xffff0000, v46
	v_lshlrev_b32_e32 v46, 16, v46
	v_fmac_f32_e32 v248, 0x3fb504f3, v46
	v_fmac_f32_e32 v249, 0x3fb504f3, v252
	v_lshlrev_b32_e32 v250, 16, v63
	v_and_b32_e32 v251, 0xffff0000, v63
	v_and_b32_e32 v252, 0xffff0000, v47
	v_lshlrev_b32_e32 v47, 16, v47
	v_fmac_f32_e32 v250, 0x3fb504f3, v47
	v_fmac_f32_e32 v251, 0x3fb504f3, v252
	v_add_f32_e32 v252, v248, v249
	v_add_f32_e32 v253, v250, v251
	v_add_f32_e32 v252, v252, v253
	v_add_f32_e32 v254, v254, v252
	s_add_u32 s12, s4, 0x1800000
	s_addc_u32 s13, s5, 0
	global_load_dwordx4 v[32:35], v90, s[12:13]
	global_load_dwordx4 v[36:39], v90, s[12:13] offset:1024
	global_load_dwordx4 v[40:43], v90, s[12:13] offset:2048
	global_load_dwordx4 v[44:47], v90, s[12:13] offset:3072
	s_add_u32 s12, s6, 0x1800000
	s_addc_u32 s13, s7, 0
	global_load_dwordx4 v[48:51], v90, s[12:13]
	global_load_dwordx4 v[52:55], v90, s[12:13] offset:1024
	global_load_dwordx4 v[56:59], v90, s[12:13] offset:2048
	global_load_dwordx4 v[60:63], v90, s[12:13] offset:3072
	s_nop 1
	v_add_f32_dpp v252, v254, v254 quad_perm:[1,0,3,2] row_mask:0xf bank_mask:0xf
	s_nop 1
	v_add_f32_dpp v252, v252, v252 quad_perm:[2,3,0,1] row_mask:0xf bank_mask:0xf
	s_nop 1
	v_add_f32_dpp v252, v252, v252 row_half_mirror row_mask:0xf bank_mask:0xf
	s_nop 1
	v_add_f32_dpp v252, v252, v252 row_mirror row_mask:0xf bank_mask:0xf
	s_nop 1
	v_readlane_b32 s40, v252, 0
	v_readlane_b32 s41, v252, 16
	v_readlane_b32 s42, v252, 32
	v_readlane_b32 s43, v252, 48
	s_nop 1
	v_mov_b32_e32 v253, s40
	v_add_f32_e32 v253, s41, v253
	v_add_f32_e32 v253, s42, v253
	v_add_f32_e32 v253, s43, v253
	v_mul_f32_e32 v253, 0x3a000000, v253
	s_nop 0
	v_readfirstlane_b32 s37, v253
	s_nop 1
	v_subrev_f32_e32 v64, s37, v64
	v_subrev_f32_e32 v65, s37, v65
	v_subrev_f32_e32 v66, s37, v66
	v_subrev_f32_e32 v67, s37, v67
	v_subrev_f32_e32 v68, s37, v68
	v_subrev_f32_e32 v69, s37, v69
	v_subrev_f32_e32 v70, s37, v70
	v_subrev_f32_e32 v71, s37, v71
	v_mul_f32_e32 v252, v64, v64
	v_fmac_f32_e32 v252, v65, v65
	v_mul_f32_e32 v253, v66, v66
	v_fmac_f32_e32 v253, v67, v67
	v_add_f32_e32 v254, v252, v253
	v_mul_f32_e32 v252, v68, v68
	v_fmac_f32_e32 v252, v69, v69
	v_mul_f32_e32 v253, v70, v70
	v_fmac_f32_e32 v253, v71, v71
	v_add_f32_e32 v252, v252, v253
	v_add_f32_e32 v254, v254, v252
	v_subrev_f32_e32 v72, s37, v72
	v_subrev_f32_e32 v73, s37, v73
	v_subrev_f32_e32 v74, s37, v74
	v_subrev_f32_e32 v75, s37, v75
	v_subrev_f32_e32 v76, s37, v76
	v_subrev_f32_e32 v77, s37, v77
	v_subrev_f32_e32 v78, s37, v78
	v_subrev_f32_e32 v79, s37, v79
	v_mul_f32_e32 v252, v72, v72
	v_fmac_f32_e32 v252, v73, v73
	v_mul_f32_e32 v253, v74, v74
	v_fmac_f32_e32 v253, v75, v75
	v_add_f32_e32 v252, v252, v253
	v_add_f32_e32 v254, v254, v252
	v_mul_f32_e32 v252, v76, v76
	v_fmac_f32_e32 v252, v77, v77
	v_mul_f32_e32 v253, v78, v78
	v_fmac_f32_e32 v253, v79, v79
	v_add_f32_e32 v252, v252, v253
	v_add_f32_e32 v254, v254, v252
	v_subrev_f32_e32 v80, s37, v80
	v_subrev_f32_e32 v81, s37, v81
	v_subrev_f32_e32 v82, s37, v82
	v_subrev_f32_e32 v83, s37, v83
	v_subrev_f32_e32 v84, s37, v84
	v_subrev_f32_e32 v85, s37, v85
	v_subrev_f32_e32 v86, s37, v86
	v_subrev_f32_e32 v87, s37, v87
	v_mul_f32_e32 v252, v80, v80
	v_fmac_f32_e32 v252, v81, v81
	v_mul_f32_e32 v253, v82, v82
	v_fmac_f32_e32 v253, v83, v83
	v_add_f32_e32 v252, v252, v253
	v_add_f32_e32 v254, v254, v252
	v_mul_f32_e32 v252, v84, v84
	v_fmac_f32_e32 v252, v85, v85
	v_mul_f32_e32 v253, v86, v86
	v_fmac_f32_e32 v253, v87, v87
	v_add_f32_e32 v252, v252, v253
	v_add_f32_e32 v254, v254, v252
	v_subrev_f32_e32 v244, s37, v244
	v_subrev_f32_e32 v245, s37, v245
	v_subrev_f32_e32 v246, s37, v246
	v_subrev_f32_e32 v247, s37, v247
	v_subrev_f32_e32 v248, s37, v248
	v_subrev_f32_e32 v249, s37, v249
	v_subrev_f32_e32 v250, s37, v250
	v_subrev_f32_e32 v251, s37, v251
	v_mul_f32_e32 v252, v244, v244
	v_fmac_f32_e32 v252, v245, v245
	v_mul_f32_e32 v253, v246, v246
	v_fmac_f32_e32 v253, v247, v247
	v_add_f32_e32 v252, v252, v253
	v_add_f32_e32 v254, v254, v252
	v_mul_f32_e32 v252, v248, v248
	v_fmac_f32_e32 v252, v249, v249
	v_mul_f32_e32 v253, v250, v250
	v_fmac_f32_e32 v253, v251, v251
	v_add_f32_e32 v252, v252, v253
	v_add_f32_e32 v254, v254, v252
	s_nop 1
	v_add_f32_dpp v252, v254, v254 quad_perm:[1,0,3,2] row_mask:0xf bank_mask:0xf
	s_nop 1
	v_add_f32_dpp v252, v252, v252 quad_perm:[2,3,0,1] row_mask:0xf bank_mask:0xf
	s_nop 1
	v_add_f32_dpp v252, v252, v252 row_half_mirror row_mask:0xf bank_mask:0xf
	s_nop 1
	v_add_f32_dpp v252, v252, v252 row_mirror row_mask:0xf bank_mask:0xf
	s_nop 1
	v_readlane_b32 s40, v252, 0
	v_readlane_b32 s41, v252, 16
	v_readlane_b32 s42, v252, 32
	v_readlane_b32 s43, v252, 48
	s_nop 1
	v_mov_b32_e32 v253, s40
	v_add_f32_e32 v253, s41, v253
	v_add_f32_e32 v253, s42, v253
	v_add_f32_e32 v253, s43, v253
	v_mov_b32_e32 v252, 0x3a000000
	v_fmaak_f32 v253, v253, v252, 0x3727c5ac
	v_rsq_f32_e32 v253, v253
	s_nop 1
	v_readfirstlane_b32 s37, v253
	s_add_u32 s12, s4, 0x800000
	s_addc_u32 s13, s5, 0
	ds_read_b64 v[252:253], v168
	ds_read_b64 v[254:255], v168 offset:8192
	ds_read_b64 v[88:89], v168 offset:512
	ds_read_b64 v[242:243], v168 offset:8704
	s_waitcnt lgkmcnt(2)
	v_mul_f32_e32 v64, s37, v64
	v_mul_f32_e32 v65, s37, v65
	v_fma_f32 v64, v64, v252, v254
	v_fma_f32 v65, v65, v253, v255
	ds_read_b64 v[252:253], v168 offset:1024
	ds_read_b64 v[254:255], v168 offset:9216
	s_waitcnt lgkmcnt(2)
	v_mul_f32_e32 v66, s37, v66
	v_mul_f32_e32 v67, s37, v67
	v_fma_f32 v66, v66, v88, v242
	v_fma_f32 v67, v67, v89, v243
	ds_read_b64 v[88:89], v168 offset:1536
	ds_read_b64 v[242:243], v168 offset:9728
	s_waitcnt lgkmcnt(2)
	v_mul_f32_e32 v68, s37, v68
	v_mul_f32_e32 v69, s37, v69
	v_fma_f32 v68, v68, v252, v254
	v_fma_f32 v69, v69, v253, v255
	ds_read_b64 v[252:253], v168 offset:2048
	ds_read_b64 v[254:255], v168 offset:10240
	s_waitcnt lgkmcnt(2)
	v_mul_f32_e32 v70, s37, v70
	v_mul_f32_e32 v71, s37, v71
	v_fma_f32 v70, v70, v88, v242
	v_fma_f32 v71, v71, v89, v243
	v_cvt_pk_bf16_f32 v64, v64, v65
	v_cvt_pk_bf16_f32 v65, v66, v67
	v_cvt_pk_bf16_f32 v66, v68, v69
	v_cvt_pk_bf16_f32 v67, v70, v71
	global_store_dwordx4 v90, v[64:67], s[12:13]
	ds_read_b64 v[88:89], v168 offset:2560
	ds_read_b64 v[242:243], v168 offset:10752
	s_waitcnt lgkmcnt(2)
	v_mul_f32_e32 v72, s37, v72
	v_mul_f32_e32 v73, s37, v73
	v_fma_f32 v72, v72, v252, v254
	v_fma_f32 v73, v73, v253, v255
	ds_read_b64 v[252:253], v168 offset:3072
	ds_read_b64 v[254:255], v168 offset:11264
	s_waitcnt lgkmcnt(2)
	v_mul_f32_e32 v74, s37, v74
	v_mul_f32_e32 v75, s37, v75
	v_fma_f32 v74, v74, v88, v242
	v_fma_f32 v75, v75, v89, v243
	ds_read_b64 v[88:89], v168 offset:3584
	ds_read_b64 v[242:243], v168 offset:11776
	s_waitcnt lgkmcnt(2)
	v_mul_f32_e32 v76, s37, v76
	v_mul_f32_e32 v77, s37, v77
	v_fma_f32 v76, v76, v252, v254
	v_fma_f32 v77, v77, v253, v255
	ds_read_b64 v[252:253], v168 offset:4096
	ds_read_b64 v[254:255], v168 offset:12288
	s_waitcnt lgkmcnt(2)
	v_mul_f32_e32 v78, s37, v78
	v_mul_f32_e32 v79, s37, v79
	v_fma_f32 v78, v78, v88, v242
	v_fma_f32 v79, v79, v89, v243
	v_cvt_pk_bf16_f32 v72, v72, v73
	v_cvt_pk_bf16_f32 v73, v74, v75
	v_cvt_pk_bf16_f32 v74, v76, v77
	v_cvt_pk_bf16_f32 v75, v78, v79
	global_store_dwordx4 v90, v[72:75], s[12:13] offset:1024
	ds_read_b64 v[88:89], v168 offset:4608
	ds_read_b64 v[242:243], v168 offset:12800
	s_waitcnt lgkmcnt(2)
	v_mul_f32_e32 v80, s37, v80
	v_mul_f32_e32 v81, s37, v81
	v_fma_f32 v80, v80, v252, v254
	v_fma_f32 v81, v81, v253, v255
	ds_read_b64 v[252:253], v168 offset:5120
	ds_read_b64 v[254:255], v168 offset:13312
	s_waitcnt lgkmcnt(2)
	v_mul_f32_e32 v82, s37, v82
	v_mul_f32_e32 v83, s37, v83
	v_fma_f32 v82, v82, v88, v242
	v_fma_f32 v83, v83, v89, v243
	ds_read_b64 v[88:89], v168 offset:5632
	ds_read_b64 v[242:243], v168 offset:13824
	s_waitcnt lgkmcnt(2)
	v_mul_f32_e32 v84, s37, v84
	v_mul_f32_e32 v85, s37, v85
	v_fma_f32 v84, v84, v252, v254
	v_fma_f32 v85, v85, v253, v255
	ds_read_b64 v[252:253], v168 offset:6144
	ds_read_b64 v[254:255], v168 offset:14336
	s_waitcnt lgkmcnt(2)
	v_mul_f32_e32 v86, s37, v86
	v_mul_f32_e32 v87, s37, v87
	v_fma_f32 v86, v86, v88, v242
	v_fma_f32 v87, v87, v89, v243
	v_cvt_pk_bf16_f32 v80, v80, v81
	v_cvt_pk_bf16_f32 v81, v82, v83
	v_cvt_pk_bf16_f32 v82, v84, v85
	v_cvt_pk_bf16_f32 v83, v86, v87
	global_store_dwordx4 v90, v[80:83], s[12:13] offset:2048
	ds_read_b64 v[88:89], v168 offset:6656
	ds_read_b64 v[242:243], v168 offset:14848
	s_waitcnt lgkmcnt(2)
	v_mul_f32_e32 v244, s37, v244
	v_mul_f32_e32 v245, s37, v245
	v_fma_f32 v244, v244, v252, v254
	v_fma_f32 v245, v245, v253, v255
	ds_read_b64 v[252:253], v168 offset:7168
	ds_read_b64 v[254:255], v168 offset:15360
	s_waitcnt lgkmcnt(2)
	v_mul_f32_e32 v246, s37, v246
	v_mul_f32_e32 v247, s37, v247
	v_fma_f32 v246, v246, v88, v242
	v_fma_f32 v247, v247, v89, v243
	ds_read_b64 v[88:89], v168 offset:7680
	ds_read_b64 v[242:243], v168 offset:15872
	s_waitcnt lgkmcnt(2)
	v_mul_f32_e32 v248, s37, v248
	v_mul_f32_e32 v249, s37, v249
	v_fma_f32 v248, v248, v252, v254
	v_fma_f32 v249, v249, v253, v255
	s_waitcnt lgkmcnt(0)
	v_mul_f32_e32 v250, s37, v250
	v_mul_f32_e32 v251, s37, v251
	v_fma_f32 v250, v250, v88, v242
	v_fma_f32 v251, v251, v89, v243
	v_cvt_pk_bf16_f32 v244, v244, v245
	v_cvt_pk_bf16_f32 v245, v246, v247
	v_cvt_pk_bf16_f32 v246, v248, v249
	v_cvt_pk_bf16_f32 v247, v250, v251
	global_store_dwordx4 v90, v[244:247], s[12:13] offset:3072
	s_waitcnt vmcnt(16)
	v_lshlrev_b32_e32 v64, 16, v16
	v_and_b32_e32 v65, 0xffff0000, v16
	v_and_b32_e32 v252, 0xffff0000, v0
	v_lshlrev_b32_e32 v0, 16, v0
	v_fmac_f32_e32 v64, 0x3fb504f3, v0
	v_fmac_f32_e32 v65, 0x3fb504f3, v252
	v_lshlrev_b32_e32 v66, 16, v17
	v_and_b32_e32 v67, 0xffff0000, v17
	v_and_b32_e32 v252, 0xffff0000, v1
	v_lshlrev_b32_e32 v1, 16, v1
	v_fmac_f32_e32 v66, 0x3fb504f3, v1
	v_fmac_f32_e32 v67, 0x3fb504f3, v252
	v_add_f32_e32 v252, v64, v65
	v_add_f32_e32 v253, v66, v67
	v_add_f32_e32 v254, v252, v253
	v_lshlrev_b32_e32 v68, 16, v18
	v_and_b32_e32 v69, 0xffff0000, v18
	v_and_b32_e32 v252, 0xffff0000, v2
	v_lshlrev_b32_e32 v2, 16, v2
	v_fmac_f32_e32 v68, 0x3fb504f3, v2
	v_fmac_f32_e32 v69, 0x3fb504f3, v252
	v_lshlrev_b32_e32 v70, 16, v19
	v_and_b32_e32 v71, 0xffff0000, v19
	v_and_b32_e32 v252, 0xffff0000, v3
	v_lshlrev_b32_e32 v3, 16, v3
	v_fmac_f32_e32 v70, 0x3fb504f3, v3
	v_fmac_f32_e32 v71, 0x3fb504f3, v252
	v_add_f32_e32 v252, v68, v69
	v_add_f32_e32 v253, v70, v71
	v_add_f32_e32 v252, v252, v253
	v_add_f32_e32 v254, v254, v252
	v_lshlrev_b32_e32 v72, 16, v20
	v_and_b32_e32 v73, 0xffff0000, v20
	v_and_b32_e32 v252, 0xffff0000, v4
	v_lshlrev_b32_e32 v4, 16, v4
	v_fmac_f32_e32 v72, 0x3fb504f3, v4
	v_fmac_f32_e32 v73, 0x3fb504f3, v252
	v_lshlrev_b32_e32 v74, 16, v21
	v_and_b32_e32 v75, 0xffff0000, v21
	v_and_b32_e32 v252, 0xffff0000, v5
	v_lshlrev_b32_e32 v5, 16, v5
	v_fmac_f32_e32 v74, 0x3fb504f3, v5
	v_fmac_f32_e32 v75, 0x3fb504f3, v252
	v_add_f32_e32 v252, v72, v73
	v_add_f32_e32 v253, v74, v75
	v_add_f32_e32 v252, v252, v253
	v_add_f32_e32 v254, v254, v252
	v_lshlrev_b32_e32 v76, 16, v22
	v_and_b32_e32 v77, 0xffff0000, v22
	v_and_b32_e32 v252, 0xffff0000, v6
	v_lshlrev_b32_e32 v6, 16, v6
	v_fmac_f32_e32 v76, 0x3fb504f3, v6
	v_fmac_f32_e32 v77, 0x3fb504f3, v252
	v_lshlrev_b32_e32 v78, 16, v23
	v_and_b32_e32 v79, 0xffff0000, v23
	v_and_b32_e32 v252, 0xffff0000, v7
	v_lshlrev_b32_e32 v7, 16, v7
	v_fmac_f32_e32 v78, 0x3fb504f3, v7
	v_fmac_f32_e32 v79, 0x3fb504f3, v252
	v_add_f32_e32 v252, v76, v77
	v_add_f32_e32 v253, v78, v79
	v_add_f32_e32 v252, v252, v253
	v_add_f32_e32 v254, v254, v252
	v_lshlrev_b32_e32 v80, 16, v24
	v_and_b32_e32 v81, 0xffff0000, v24
	v_and_b32_e32 v252, 0xffff0000, v8
	v_lshlrev_b32_e32 v8, 16, v8
	v_fmac_f32_e32 v80, 0x3fb504f3, v8
	v_fmac_f32_e32 v81, 0x3fb504f3, v252
	v_lshlrev_b32_e32 v82, 16, v25
	v_and_b32_e32 v83, 0xffff0000, v25
	v_and_b32_e32 v252, 0xffff0000, v9
	v_lshlrev_b32_e32 v9, 16, v9
	v_fmac_f32_e32 v82, 0x3fb504f3, v9
	v_fmac_f32_e32 v83, 0x3fb504f3, v252
	v_add_f32_e32 v252, v80, v81
	v_add_f32_e32 v253, v82, v83
	v_add_f32_e32 v252, v252, v253
	v_add_f32_e32 v254, v254, v252
	v_lshlrev_b32_e32 v84, 16, v26
	v_and_b32_e32 v85, 0xffff0000, v26
	v_and_b32_e32 v252, 0xffff0000, v10
	v_lshlrev_b32_e32 v10, 16, v10
	v_fmac_f32_e32 v84, 0x3fb504f3, v10
	v_fmac_f32_e32 v85, 0x3fb504f3, v252
	v_lshlrev_b32_e32 v86, 16, v27
	v_and_b32_e32 v87, 0xffff0000, v27
	v_and_b32_e32 v252, 0xffff0000, v11
	v_lshlrev_b32_e32 v11, 16, v11
	v_fmac_f32_e32 v86, 0x3fb504f3, v11
	v_fmac_f32_e32 v87, 0x3fb504f3, v252
	v_add_f32_e32 v252, v84, v85
	v_add_f32_e32 v253, v86, v87
	v_add_f32_e32 v252, v252, v253
	v_add_f32_e32 v254, v254, v252
	v_lshlrev_b32_e32 v244, 16, v28
	v_and_b32_e32 v245, 0xffff0000, v28
	v_and_b32_e32 v252, 0xffff0000, v12
	v_lshlrev_b32_e32 v12, 16, v12
	v_fmac_f32_e32 v244, 0x3fb504f3, v12
	v_fmac_f32_e32 v245, 0x3fb504f3, v252
	v_lshlrev_b32_e32 v246, 16, v29
	v_and_b32_e32 v247, 0xffff0000, v29
	v_and_b32_e32 v252, 0xffff0000, v13
	v_lshlrev_b32_e32 v13, 16, v13
	v_fmac_f32_e32 v246, 0x3fb504f3, v13
	v_fmac_f32_e32 v247, 0x3fb504f3, v252
	v_add_f32_e32 v252, v244, v245
	v_add_f32_e32 v253, v246, v247
	v_add_f32_e32 v252, v252, v253
	v_add_f32_e32 v254, v254, v252
	v_lshlrev_b32_e32 v248, 16, v30
	v_and_b32_e32 v249, 0xffff0000, v30
	v_and_b32_e32 v252, 0xffff0000, v14
	v_lshlrev_b32_e32 v14, 16, v14
	v_fmac_f32_e32 v248, 0x3fb504f3, v14
	v_fmac_f32_e32 v249, 0x3fb504f3, v252
	v_lshlrev_b32_e32 v250, 16, v31
	v_and_b32_e32 v251, 0xffff0000, v31
	v_and_b32_e32 v252, 0xffff0000, v15
	v_lshlrev_b32_e32 v15, 16, v15
	v_fmac_f32_e32 v250, 0x3fb504f3, v15
	v_fmac_f32_e32 v251, 0x3fb504f3, v252
	v_add_f32_e32 v252, v248, v249
	v_add_f32_e32 v253, v250, v251
	v_add_f32_e32 v252, v252, v253
	v_add_f32_e32 v254, v254, v252
	s_cmp_lt_u32 s36, 4
	s_cbranch_scc0 .Lln1_nos_1
	v_readlane_b32 s38, v241, 0
	s_lshl_b32 s30, s38, 14
	v_subrev_u32_e32 v88, s30, v90
	s_add_u32 s12, s4, 0x2000000
	s_addc_u32 s13, s5, 0
	global_load_dwordx4 v[0:3], v88, s[12:13]
	global_load_dwordx4 v[4:7], v88, s[12:13] offset:1024
	global_load_dwordx4 v[8:11], v88, s[12:13] offset:2048
	global_load_dwordx4 v[12:15], v88, s[12:13] offset:3072
	global_load_dwordx4 v[16:19], v88, s[8:9]
	global_load_dwordx4 v[20:23], v88, s[8:9] offset:1024
	global_load_dwordx4 v[24:27], v88, s[8:9] offset:2048
	global_load_dwordx4 v[28:31], v88, s[8:9] offset:3072
.Lln1_nos_1:
	s_nop 1
	v_add_f32_dpp v252, v254, v254 quad_perm:[1,0,3,2] row_mask:0xf bank_mask:0xf
	s_nop 1
	v_add_f32_dpp v252, v252, v252 quad_perm:[2,3,0,1] row_mask:0xf bank_mask:0xf
	s_nop 1
	v_add_f32_dpp v252, v252, v252 row_half_mirror row_mask:0xf bank_mask:0xf
	s_nop 1
	v_add_f32_dpp v252, v252, v252 row_mirror row_mask:0xf bank_mask:0xf
	s_nop 1
	v_readlane_b32 s40, v252, 0
	v_readlane_b32 s41, v252, 16
	v_readlane_b32 s42, v252, 32
	v_readlane_b32 s43, v252, 48
	s_nop 1
	v_mov_b32_e32 v253, s40
	v_add_f32_e32 v253, s41, v253
	v_add_f32_e32 v253, s42, v253
	v_add_f32_e32 v253, s43, v253
	v_mul_f32_e32 v253, 0x3a000000, v253
	s_nop 0
	v_readfirstlane_b32 s37, v253
	s_nop 1
	v_subrev_f32_e32 v64, s37, v64
	v_subrev_f32_e32 v65, s37, v65
	v_subrev_f32_e32 v66, s37, v66
	v_subrev_f32_e32 v67, s37, v67
	v_subrev_f32_e32 v68, s37, v68
	v_subrev_f32_e32 v69, s37, v69
	v_subrev_f32_e32 v70, s37, v70
	v_subrev_f32_e32 v71, s37, v71
	v_mul_f32_e32 v252, v64, v64
	v_fmac_f32_e32 v252, v65, v65
	v_mul_f32_e32 v253, v66, v66
	v_fmac_f32_e32 v253, v67, v67
	v_add_f32_e32 v254, v252, v253
	v_mul_f32_e32 v252, v68, v68
	v_fmac_f32_e32 v252, v69, v69
	v_mul_f32_e32 v253, v70, v70
	v_fmac_f32_e32 v253, v71, v71
	v_add_f32_e32 v252, v252, v253
	v_add_f32_e32 v254, v254, v252
	v_subrev_f32_e32 v72, s37, v72
	v_subrev_f32_e32 v73, s37, v73
	v_subrev_f32_e32 v74, s37, v74
	v_subrev_f32_e32 v75, s37, v75
	v_subrev_f32_e32 v76, s37, v76
	v_subrev_f32_e32 v77, s37, v77
	v_subrev_f32_e32 v78, s37, v78
	v_subrev_f32_e32 v79, s37, v79
	v_mul_f32_e32 v252, v72, v72
	v_fmac_f32_e32 v252, v73, v73
	v_mul_f32_e32 v253, v74, v74
	v_fmac_f32_e32 v253, v75, v75
	v_add_f32_e32 v252, v252, v253
	v_add_f32_e32 v254, v254, v252
	v_mul_f32_e32 v252, v76, v76
	v_fmac_f32_e32 v252, v77, v77
	v_mul_f32_e32 v253, v78, v78
	v_fmac_f32_e32 v253, v79, v79
	v_add_f32_e32 v252, v252, v253
	v_add_f32_e32 v254, v254, v252
	v_subrev_f32_e32 v80, s37, v80
	v_subrev_f32_e32 v81, s37, v81
	v_subrev_f32_e32 v82, s37, v82
	v_subrev_f32_e32 v83, s37, v83
	v_subrev_f32_e32 v84, s37, v84
	v_subrev_f32_e32 v85, s37, v85
	v_subrev_f32_e32 v86, s37, v86
	v_subrev_f32_e32 v87, s37, v87
	v_mul_f32_e32 v252, v80, v80
	v_fmac_f32_e32 v252, v81, v81
	v_mul_f32_e32 v253, v82, v82
	v_fmac_f32_e32 v253, v83, v83
	v_add_f32_e32 v252, v252, v253
	v_add_f32_e32 v254, v254, v252
	v_mul_f32_e32 v252, v84, v84
	v_fmac_f32_e32 v252, v85, v85
	v_mul_f32_e32 v253, v86, v86
	v_fmac_f32_e32 v253, v87, v87
	v_add_f32_e32 v252, v252, v253
	v_add_f32_e32 v254, v254, v252
	v_subrev_f32_e32 v244, s37, v244
	v_subrev_f32_e32 v245, s37, v245
	v_subrev_f32_e32 v246, s37, v246
	v_subrev_f32_e32 v247, s37, v247
	v_subrev_f32_e32 v248, s37, v248
	v_subrev_f32_e32 v249, s37, v249
	v_subrev_f32_e32 v250, s37, v250
	v_subrev_f32_e32 v251, s37, v251
	v_mul_f32_e32 v252, v244, v244
	v_fmac_f32_e32 v252, v245, v245
	v_mul_f32_e32 v253, v246, v246
	v_fmac_f32_e32 v253, v247, v247
	v_add_f32_e32 v252, v252, v253
	v_add_f32_e32 v254, v254, v252
	v_mul_f32_e32 v252, v248, v248
	v_fmac_f32_e32 v252, v249, v249
	v_mul_f32_e32 v253, v250, v250
	v_fmac_f32_e32 v253, v251, v251
	v_add_f32_e32 v252, v252, v253
	v_add_f32_e32 v254, v254, v252
	s_nop 1
	v_add_f32_dpp v252, v254, v254 quad_perm:[1,0,3,2] row_mask:0xf bank_mask:0xf
	s_nop 1
	v_add_f32_dpp v252, v252, v252 quad_perm:[2,3,0,1] row_mask:0xf bank_mask:0xf
	s_nop 1
	v_add_f32_dpp v252, v252, v252 row_half_mirror row_mask:0xf bank_mask:0xf
	s_nop 1
	v_add_f32_dpp v252, v252, v252 row_mirror row_mask:0xf bank_mask:0xf
	s_nop 1
	v_readlane_b32 s40, v252, 0
	v_readlane_b32 s41, v252, 16
	v_readlane_b32 s42, v252, 32
	v_readlane_b32 s43, v252, 48
	s_nop 1
	v_mov_b32_e32 v253, s40
	v_add_f32_e32 v253, s41, v253
	v_add_f32_e32 v253, s42, v253
	v_add_f32_e32 v253, s43, v253
	v_mov_b32_e32 v252, 0x3a000000
	v_fmaak_f32 v253, v253, v252, 0x3727c5ac
	v_rsq_f32_e32 v253, v253
	s_nop 1
	v_readfirstlane_b32 s37, v253
	s_add_u32 s12, s4, 0x1000000
	s_addc_u32 s13, s5, 0
	ds_read_b64 v[252:253], v168
	ds_read_b64 v[254:255], v168 offset:8192
	ds_read_b64 v[88:89], v168 offset:512
	ds_read_b64 v[242:243], v168 offset:8704
	s_waitcnt lgkmcnt(2)
	v_mul_f32_e32 v64, s37, v64
	v_mul_f32_e32 v65, s37, v65
	v_fma_f32 v64, v64, v252, v254
	v_fma_f32 v65, v65, v253, v255
	ds_read_b64 v[252:253], v168 offset:1024
	ds_read_b64 v[254:255], v168 offset:9216
	s_waitcnt lgkmcnt(2)
	v_mul_f32_e32 v66, s37, v66
	v_mul_f32_e32 v67, s37, v67
	v_fma_f32 v66, v66, v88, v242
	v_fma_f32 v67, v67, v89, v243
	ds_read_b64 v[88:89], v168 offset:1536
	ds_read_b64 v[242:243], v168 offset:9728
	s_waitcnt lgkmcnt(2)
	v_mul_f32_e32 v68, s37, v68
	v_mul_f32_e32 v69, s37, v69
	v_fma_f32 v68, v68, v252, v254
	v_fma_f32 v69, v69, v253, v255
	ds_read_b64 v[252:253], v168 offset:2048
	ds_read_b64 v[254:255], v168 offset:10240
	s_waitcnt lgkmcnt(2)
	v_mul_f32_e32 v70, s37, v70
	v_mul_f32_e32 v71, s37, v71
	v_fma_f32 v70, v70, v88, v242
	v_fma_f32 v71, v71, v89, v243
	v_cvt_pk_bf16_f32 v64, v64, v65
	v_cvt_pk_bf16_f32 v65, v66, v67
	v_cvt_pk_bf16_f32 v66, v68, v69
	v_cvt_pk_bf16_f32 v67, v70, v71
	global_store_dwordx4 v90, v[64:67], s[12:13]
	ds_read_b64 v[88:89], v168 offset:2560
	ds_read_b64 v[242:243], v168 offset:10752
	s_waitcnt lgkmcnt(2)
	v_mul_f32_e32 v72, s37, v72
	v_mul_f32_e32 v73, s37, v73
	v_fma_f32 v72, v72, v252, v254
	v_fma_f32 v73, v73, v253, v255
	ds_read_b64 v[252:253], v168 offset:3072
	ds_read_b64 v[254:255], v168 offset:11264
	s_waitcnt lgkmcnt(2)
	v_mul_f32_e32 v74, s37, v74
	v_mul_f32_e32 v75, s37, v75
	v_fma_f32 v74, v74, v88, v242
	v_fma_f32 v75, v75, v89, v243
	ds_read_b64 v[88:89], v168 offset:3584
	ds_read_b64 v[242:243], v168 offset:11776
	s_waitcnt lgkmcnt(2)
	v_mul_f32_e32 v76, s37, v76
	v_mul_f32_e32 v77, s37, v77
	v_fma_f32 v76, v76, v252, v254
	v_fma_f32 v77, v77, v253, v255
	ds_read_b64 v[252:253], v168 offset:4096
	ds_read_b64 v[254:255], v168 offset:12288
	s_waitcnt lgkmcnt(2)
	v_mul_f32_e32 v78, s37, v78
	v_mul_f32_e32 v79, s37, v79
	v_fma_f32 v78, v78, v88, v242
	v_fma_f32 v79, v79, v89, v243
	v_cvt_pk_bf16_f32 v72, v72, v73
	v_cvt_pk_bf16_f32 v73, v74, v75
	v_cvt_pk_bf16_f32 v74, v76, v77
	v_cvt_pk_bf16_f32 v75, v78, v79
	global_store_dwordx4 v90, v[72:75], s[12:13] offset:1024
	ds_read_b64 v[88:89], v168 offset:4608
	ds_read_b64 v[242:243], v168 offset:12800
	s_waitcnt lgkmcnt(2)
	v_mul_f32_e32 v80, s37, v80
	v_mul_f32_e32 v81, s37, v81
	v_fma_f32 v80, v80, v252, v254
	v_fma_f32 v81, v81, v253, v255
	ds_read_b64 v[252:253], v168 offset:5120
	ds_read_b64 v[254:255], v168 offset:13312
	s_waitcnt lgkmcnt(2)
	v_mul_f32_e32 v82, s37, v82
	v_mul_f32_e32 v83, s37, v83
	v_fma_f32 v82, v82, v88, v242
	v_fma_f32 v83, v83, v89, v243
	ds_read_b64 v[88:89], v168 offset:5632
	ds_read_b64 v[242:243], v168 offset:13824
	s_waitcnt lgkmcnt(2)
	v_mul_f32_e32 v84, s37, v84
	v_mul_f32_e32 v85, s37, v85
	v_fma_f32 v84, v84, v252, v254
	v_fma_f32 v85, v85, v253, v255
	ds_read_b64 v[252:253], v168 offset:6144
	ds_read_b64 v[254:255], v168 offset:14336
	s_waitcnt lgkmcnt(2)
	v_mul_f32_e32 v86, s37, v86
	v_mul_f32_e32 v87, s37, v87
	v_fma_f32 v86, v86, v88, v242
	v_fma_f32 v87, v87, v89, v243
	v_cvt_pk_bf16_f32 v80, v80, v81
	v_cvt_pk_bf16_f32 v81, v82, v83
	v_cvt_pk_bf16_f32 v82, v84, v85
	v_cvt_pk_bf16_f32 v83, v86, v87
	global_store_dwordx4 v90, v[80:83], s[12:13] offset:2048
	ds_read_b64 v[88:89], v168 offset:6656
	ds_read_b64 v[242:243], v168 offset:14848
	s_waitcnt lgkmcnt(2)
	v_mul_f32_e32 v244, s37, v244
	v_mul_f32_e32 v245, s37, v245
	v_fma_f32 v244, v244, v252, v254
	v_fma_f32 v245, v245, v253, v255
	ds_read_b64 v[252:253], v168 offset:7168
	ds_read_b64 v[254:255], v168 offset:15360
	s_waitcnt lgkmcnt(2)
	v_mul_f32_e32 v246, s37, v246
	v_mul_f32_e32 v247, s37, v247
	v_fma_f32 v246, v246, v88, v242
	v_fma_f32 v247, v247, v89, v243
	ds_read_b64 v[88:89], v168 offset:7680
	ds_read_b64 v[242:243], v168 offset:15872
	s_waitcnt lgkmcnt(2)
	v_mul_f32_e32 v248, s37, v248
	v_mul_f32_e32 v249, s37, v249
	v_fma_f32 v248, v248, v252, v254
	v_fma_f32 v249, v249, v253, v255
	s_waitcnt lgkmcnt(0)
	v_mul_f32_e32 v250, s37, v250
	v_mul_f32_e32 v251, s37, v251
	v_fma_f32 v250, v250, v88, v242
	v_fma_f32 v251, v251, v89, v243
	v_cvt_pk_bf16_f32 v244, v244, v245
	v_cvt_pk_bf16_f32 v245, v246, v247
	v_cvt_pk_bf16_f32 v246, v248, v249
	v_cvt_pk_bf16_f32 v247, v250, v251
	global_store_dwordx4 v90, v[244:247], s[12:13] offset:3072
	s_waitcnt vmcnt(8)
	v_lshlrev_b32_e32 v64, 16, v48
	v_and_b32_e32 v65, 0xffff0000, v48
	v_and_b32_e32 v252, 0xffff0000, v32
	v_lshlrev_b32_e32 v32, 16, v32
	v_fmac_f32_e32 v64, 0x3fb504f3, v32
	v_fmac_f32_e32 v65, 0x3fb504f3, v252
	v_lshlrev_b32_e32 v66, 16, v49
	v_and_b32_e32 v67, 0xffff0000, v49
	v_and_b32_e32 v252, 0xffff0000, v33
	v_lshlrev_b32_e32 v33, 16, v33
	v_fmac_f32_e32 v66, 0x3fb504f3, v33
	v_fmac_f32_e32 v67, 0x3fb504f3, v252
	v_add_f32_e32 v252, v64, v65
	v_add_f32_e32 v253, v66, v67
	v_add_f32_e32 v254, v252, v253
	v_lshlrev_b32_e32 v68, 16, v50
	v_and_b32_e32 v69, 0xffff0000, v50
	v_and_b32_e32 v252, 0xffff0000, v34
	v_lshlrev_b32_e32 v34, 16, v34
	v_fmac_f32_e32 v68, 0x3fb504f3, v34
	v_fmac_f32_e32 v69, 0x3fb504f3, v252
	v_lshlrev_b32_e32 v70, 16, v51
	v_and_b32_e32 v71, 0xffff0000, v51
	v_and_b32_e32 v252, 0xffff0000, v35
	v_lshlrev_b32_e32 v35, 16, v35
	v_fmac_f32_e32 v70, 0x3fb504f3, v35
	v_fmac_f32_e32 v71, 0x3fb504f3, v252
	v_add_f32_e32 v252, v68, v69
	v_add_f32_e32 v253, v70, v71
	v_add_f32_e32 v252, v252, v253
	v_add_f32_e32 v254, v254, v252
	v_lshlrev_b32_e32 v72, 16, v52
	v_and_b32_e32 v73, 0xffff0000, v52
	v_and_b32_e32 v252, 0xffff0000, v36
	v_lshlrev_b32_e32 v36, 16, v36
	v_fmac_f32_e32 v72, 0x3fb504f3, v36
	v_fmac_f32_e32 v73, 0x3fb504f3, v252
	v_lshlrev_b32_e32 v74, 16, v53
	v_and_b32_e32 v75, 0xffff0000, v53
	v_and_b32_e32 v252, 0xffff0000, v37
	v_lshlrev_b32_e32 v37, 16, v37
	v_fmac_f32_e32 v74, 0x3fb504f3, v37
	v_fmac_f32_e32 v75, 0x3fb504f3, v252
	v_add_f32_e32 v252, v72, v73
	v_add_f32_e32 v253, v74, v75
	v_add_f32_e32 v252, v252, v253
	v_add_f32_e32 v254, v254, v252
	v_lshlrev_b32_e32 v76, 16, v54
	v_and_b32_e32 v77, 0xffff0000, v54
	v_and_b32_e32 v252, 0xffff0000, v38
	v_lshlrev_b32_e32 v38, 16, v38
	v_fmac_f32_e32 v76, 0x3fb504f3, v38
	v_fmac_f32_e32 v77, 0x3fb504f3, v252
	v_lshlrev_b32_e32 v78, 16, v55
	v_and_b32_e32 v79, 0xffff0000, v55
	v_and_b32_e32 v252, 0xffff0000, v39
	v_lshlrev_b32_e32 v39, 16, v39
	v_fmac_f32_e32 v78, 0x3fb504f3, v39
	v_fmac_f32_e32 v79, 0x3fb504f3, v252
	v_add_f32_e32 v252, v76, v77
	v_add_f32_e32 v253, v78, v79
	v_add_f32_e32 v252, v252, v253
	v_add_f32_e32 v254, v254, v252
	v_lshlrev_b32_e32 v80, 16, v56
	v_and_b32_e32 v81, 0xffff0000, v56
	v_and_b32_e32 v252, 0xffff0000, v40
	v_lshlrev_b32_e32 v40, 16, v40
	v_fmac_f32_e32 v80, 0x3fb504f3, v40
	v_fmac_f32_e32 v81, 0x3fb504f3, v252
	v_lshlrev_b32_e32 v82, 16, v57
	v_and_b32_e32 v83, 0xffff0000, v57
	v_and_b32_e32 v252, 0xffff0000, v41
	v_lshlrev_b32_e32 v41, 16, v41
	v_fmac_f32_e32 v82, 0x3fb504f3, v41
	v_fmac_f32_e32 v83, 0x3fb504f3, v252
	v_add_f32_e32 v252, v80, v81
	v_add_f32_e32 v253, v82, v83
	v_add_f32_e32 v252, v252, v253
	v_add_f32_e32 v254, v254, v252
	v_lshlrev_b32_e32 v84, 16, v58
	v_and_b32_e32 v85, 0xffff0000, v58
	v_and_b32_e32 v252, 0xffff0000, v42
	v_lshlrev_b32_e32 v42, 16, v42
	v_fmac_f32_e32 v84, 0x3fb504f3, v42
	v_fmac_f32_e32 v85, 0x3fb504f3, v252
	v_lshlrev_b32_e32 v86, 16, v59
	v_and_b32_e32 v87, 0xffff0000, v59
	v_and_b32_e32 v252, 0xffff0000, v43
	v_lshlrev_b32_e32 v43, 16, v43
	v_fmac_f32_e32 v86, 0x3fb504f3, v43
	v_fmac_f32_e32 v87, 0x3fb504f3, v252
	v_add_f32_e32 v252, v84, v85
	v_add_f32_e32 v253, v86, v87
	v_add_f32_e32 v252, v252, v253
	v_add_f32_e32 v254, v254, v252
	v_lshlrev_b32_e32 v244, 16, v60
	v_and_b32_e32 v245, 0xffff0000, v60
	v_and_b32_e32 v252, 0xffff0000, v44
	v_lshlrev_b32_e32 v44, 16, v44
	v_fmac_f32_e32 v244, 0x3fb504f3, v44
	v_fmac_f32_e32 v245, 0x3fb504f3, v252
	v_lshlrev_b32_e32 v246, 16, v61
	v_and_b32_e32 v247, 0xffff0000, v61
	v_and_b32_e32 v252, 0xffff0000, v45
	v_lshlrev_b32_e32 v45, 16, v45
	v_fmac_f32_e32 v246, 0x3fb504f3, v45
	v_fmac_f32_e32 v247, 0x3fb504f3, v252
	v_add_f32_e32 v252, v244, v245
	v_add_f32_e32 v253, v246, v247
	v_add_f32_e32 v252, v252, v253
	v_add_f32_e32 v254, v254, v252
	v_lshlrev_b32_e32 v248, 16, v62
	v_and_b32_e32 v249, 0xffff0000, v62
	v_and_b32_e32 v252, 0xffff0000, v46
	v_lshlrev_b32_e32 v46, 16, v46
	v_fmac_f32_e32 v248, 0x3fb504f3, v46
	v_fmac_f32_e32 v249, 0x3fb504f3, v252
	v_lshlrev_b32_e32 v250, 16, v63
	v_and_b32_e32 v251, 0xffff0000, v63
	v_and_b32_e32 v252, 0xffff0000, v47
	v_lshlrev_b32_e32 v47, 16, v47
	v_fmac_f32_e32 v250, 0x3fb504f3, v47
	v_fmac_f32_e32 v251, 0x3fb504f3, v252
	v_add_f32_e32 v252, v248, v249
	v_add_f32_e32 v253, v250, v251
	v_add_f32_e32 v252, v252, v253
	v_add_f32_e32 v254, v254, v252
	s_cmp_lt_u32 s36, 4
	s_cbranch_scc0 .Lln1_nos_2
	v_readlane_b32 s38, v241, 0
	s_lshl_b32 s30, s38, 14
	v_subrev_u32_e32 v88, s30, v90
	s_add_u32 s12, s8, 0x400000
	s_addc_u32 s13, s9, 0
	global_load_dwordx4 v[32:35], v88, s[12:13]
	global_load_dwordx4 v[36:39], v88, s[12:13] offset:1024
	global_load_dwordx4 v[40:43], v88, s[12:13] offset:2048
	global_load_dwordx4 v[44:47], v88, s[12:13] offset:3072
	s_add_u32 s12, s8, 0x800000
	s_addc_u32 s13, s9, 0
	global_load_dwordx4 v[48:51], v88, s[12:13]
	global_load_dwordx4 v[52:55], v88, s[12:13] offset:1024
	global_load_dwordx4 v[56:59], v88, s[12:13] offset:2048
	global_load_dwordx4 v[60:63], v88, s[12:13] offset:3072
.Lln1_nos_2:
	s_nop 1
	v_add_f32_dpp v252, v254, v254 quad_perm:[1,0,3,2] row_mask:0xf bank_mask:0xf
	s_nop 1
	v_add_f32_dpp v252, v252, v252 quad_perm:[2,3,0,1] row_mask:0xf bank_mask:0xf
	s_nop 1
	v_add_f32_dpp v252, v252, v252 row_half_mirror row_mask:0xf bank_mask:0xf
	s_nop 1
	v_add_f32_dpp v252, v252, v252 row_mirror row_mask:0xf bank_mask:0xf
	s_nop 1
	v_readlane_b32 s40, v252, 0
	v_readlane_b32 s41, v252, 16
	v_readlane_b32 s42, v252, 32
	v_readlane_b32 s43, v252, 48
	s_nop 1
	v_mov_b32_e32 v253, s40
	v_add_f32_e32 v253, s41, v253
	v_add_f32_e32 v253, s42, v253
	v_add_f32_e32 v253, s43, v253
	v_mul_f32_e32 v253, 0x3a000000, v253
	s_nop 0
	v_readfirstlane_b32 s37, v253
	s_nop 1
	v_subrev_f32_e32 v64, s37, v64
	v_subrev_f32_e32 v65, s37, v65
	v_subrev_f32_e32 v66, s37, v66
	v_subrev_f32_e32 v67, s37, v67
	v_subrev_f32_e32 v68, s37, v68
	v_subrev_f32_e32 v69, s37, v69
	v_subrev_f32_e32 v70, s37, v70
	v_subrev_f32_e32 v71, s37, v71
	v_mul_f32_e32 v252, v64, v64
	v_fmac_f32_e32 v252, v65, v65
	v_mul_f32_e32 v253, v66, v66
	v_fmac_f32_e32 v253, v67, v67
	v_add_f32_e32 v254, v252, v253
	v_mul_f32_e32 v252, v68, v68
	v_fmac_f32_e32 v252, v69, v69
	v_mul_f32_e32 v253, v70, v70
	v_fmac_f32_e32 v253, v71, v71
	v_add_f32_e32 v252, v252, v253
	v_add_f32_e32 v254, v254, v252
	v_subrev_f32_e32 v72, s37, v72
	v_subrev_f32_e32 v73, s37, v73
	v_subrev_f32_e32 v74, s37, v74
	v_subrev_f32_e32 v75, s37, v75
	v_subrev_f32_e32 v76, s37, v76
	v_subrev_f32_e32 v77, s37, v77
	v_subrev_f32_e32 v78, s37, v78
	v_subrev_f32_e32 v79, s37, v79
	v_mul_f32_e32 v252, v72, v72
	v_fmac_f32_e32 v252, v73, v73
	v_mul_f32_e32 v253, v74, v74
	v_fmac_f32_e32 v253, v75, v75
	v_add_f32_e32 v252, v252, v253
	v_add_f32_e32 v254, v254, v252
	v_mul_f32_e32 v252, v76, v76
	v_fmac_f32_e32 v252, v77, v77
	v_mul_f32_e32 v253, v78, v78
	v_fmac_f32_e32 v253, v79, v79
	v_add_f32_e32 v252, v252, v253
	v_add_f32_e32 v254, v254, v252
	v_subrev_f32_e32 v80, s37, v80
	v_subrev_f32_e32 v81, s37, v81
	v_subrev_f32_e32 v82, s37, v82
	v_subrev_f32_e32 v83, s37, v83
	v_subrev_f32_e32 v84, s37, v84
	v_subrev_f32_e32 v85, s37, v85
	v_subrev_f32_e32 v86, s37, v86
	v_subrev_f32_e32 v87, s37, v87
	v_mul_f32_e32 v252, v80, v80
	v_fmac_f32_e32 v252, v81, v81
	v_mul_f32_e32 v253, v82, v82
	v_fmac_f32_e32 v253, v83, v83
	v_add_f32_e32 v252, v252, v253
	v_add_f32_e32 v254, v254, v252
	v_mul_f32_e32 v252, v84, v84
	v_fmac_f32_e32 v252, v85, v85
	v_mul_f32_e32 v253, v86, v86
	v_fmac_f32_e32 v253, v87, v87
	v_add_f32_e32 v252, v252, v253
	v_add_f32_e32 v254, v254, v252
	v_subrev_f32_e32 v244, s37, v244
	v_subrev_f32_e32 v245, s37, v245
	v_subrev_f32_e32 v246, s37, v246
	v_subrev_f32_e32 v247, s37, v247
	v_subrev_f32_e32 v248, s37, v248
	v_subrev_f32_e32 v249, s37, v249
	v_subrev_f32_e32 v250, s37, v250
	v_subrev_f32_e32 v251, s37, v251
	v_mul_f32_e32 v252, v244, v244
	v_fmac_f32_e32 v252, v245, v245
	v_mul_f32_e32 v253, v246, v246
	v_fmac_f32_e32 v253, v247, v247
	v_add_f32_e32 v252, v252, v253
	v_add_f32_e32 v254, v254, v252
	v_mul_f32_e32 v252, v248, v248
	v_fmac_f32_e32 v252, v249, v249
	v_mul_f32_e32 v253, v250, v250
	v_fmac_f32_e32 v253, v251, v251
	v_add_f32_e32 v252, v252, v253
	v_add_f32_e32 v254, v254, v252
	s_nop 1
	v_add_f32_dpp v252, v254, v254 quad_perm:[1,0,3,2] row_mask:0xf bank_mask:0xf
	s_nop 1
	v_add_f32_dpp v252, v252, v252 quad_perm:[2,3,0,1] row_mask:0xf bank_mask:0xf
	s_nop 1
	v_add_f32_dpp v252, v252, v252 row_half_mirror row_mask:0xf bank_mask:0xf
	s_nop 1
	v_add_f32_dpp v252, v252, v252 row_mirror row_mask:0xf bank_mask:0xf
	s_nop 1
	v_readlane_b32 s40, v252, 0
	v_readlane_b32 s41, v252, 16
	v_readlane_b32 s42, v252, 32
	v_readlane_b32 s43, v252, 48
	s_nop 1
	v_mov_b32_e32 v253, s40
	v_add_f32_e32 v253, s41, v253
	v_add_f32_e32 v253, s42, v253
	v_add_f32_e32 v253, s43, v253
	v_mov_b32_e32 v252, 0x3a000000
	v_fmaak_f32 v253, v253, v252, 0x3727c5ac
	v_rsq_f32_e32 v253, v253
	s_nop 1
	v_readfirstlane_b32 s37, v253
	s_add_u32 s12, s4, 0x1800000
	s_addc_u32 s13, s5, 0
	ds_read_b64 v[252:253], v168
	ds_read_b64 v[254:255], v168 offset:8192
	ds_read_b64 v[88:89], v168 offset:512
	ds_read_b64 v[242:243], v168 offset:8704
	s_waitcnt lgkmcnt(2)
	v_mul_f32_e32 v64, s37, v64
	v_mul_f32_e32 v65, s37, v65
	v_fma_f32 v64, v64, v252, v254
	v_fma_f32 v65, v65, v253, v255
	ds_read_b64 v[252:253], v168 offset:1024
	ds_read_b64 v[254:255], v168 offset:9216
	s_waitcnt lgkmcnt(2)
	v_mul_f32_e32 v66, s37, v66
	v_mul_f32_e32 v67, s37, v67
	v_fma_f32 v66, v66, v88, v242
	v_fma_f32 v67, v67, v89, v243
	ds_read_b64 v[88:89], v168 offset:1536
	ds_read_b64 v[242:243], v168 offset:9728
	s_waitcnt lgkmcnt(2)
	v_mul_f32_e32 v68, s37, v68
	v_mul_f32_e32 v69, s37, v69
	v_fma_f32 v68, v68, v252, v254
	v_fma_f32 v69, v69, v253, v255
	ds_read_b64 v[252:253], v168 offset:2048
	ds_read_b64 v[254:255], v168 offset:10240
	s_waitcnt lgkmcnt(2)
	v_mul_f32_e32 v70, s37, v70
	v_mul_f32_e32 v71, s37, v71
	v_fma_f32 v70, v70, v88, v242
	v_fma_f32 v71, v71, v89, v243
	v_cvt_pk_bf16_f32 v64, v64, v65
	v_cvt_pk_bf16_f32 v65, v66, v67
	v_cvt_pk_bf16_f32 v66, v68, v69
	v_cvt_pk_bf16_f32 v67, v70, v71
	global_store_dwordx4 v90, v[64:67], s[12:13]
	ds_read_b64 v[88:89], v168 offset:2560
	ds_read_b64 v[242:243], v168 offset:10752
	s_waitcnt lgkmcnt(2)
	v_mul_f32_e32 v72, s37, v72
	v_mul_f32_e32 v73, s37, v73
	v_fma_f32 v72, v72, v252, v254
	v_fma_f32 v73, v73, v253, v255
	ds_read_b64 v[252:253], v168 offset:3072
	ds_read_b64 v[254:255], v168 offset:11264
	s_waitcnt lgkmcnt(2)
	v_mul_f32_e32 v74, s37, v74
	v_mul_f32_e32 v75, s37, v75
	v_fma_f32 v74, v74, v88, v242
	v_fma_f32 v75, v75, v89, v243
	ds_read_b64 v[88:89], v168 offset:3584
	ds_read_b64 v[242:243], v168 offset:11776
	s_waitcnt lgkmcnt(2)
	v_mul_f32_e32 v76, s37, v76
	v_mul_f32_e32 v77, s37, v77
	v_fma_f32 v76, v76, v252, v254
	v_fma_f32 v77, v77, v253, v255
	ds_read_b64 v[252:253], v168 offset:4096
	ds_read_b64 v[254:255], v168 offset:12288
	s_waitcnt lgkmcnt(2)
	v_mul_f32_e32 v78, s37, v78
	v_mul_f32_e32 v79, s37, v79
	v_fma_f32 v78, v78, v88, v242
	v_fma_f32 v79, v79, v89, v243
	v_cvt_pk_bf16_f32 v72, v72, v73
	v_cvt_pk_bf16_f32 v73, v74, v75
	v_cvt_pk_bf16_f32 v74, v76, v77
	v_cvt_pk_bf16_f32 v75, v78, v79
	global_store_dwordx4 v90, v[72:75], s[12:13] offset:1024
	ds_read_b64 v[88:89], v168 offset:4608
	ds_read_b64 v[242:243], v168 offset:12800
	s_waitcnt lgkmcnt(2)
	v_mul_f32_e32 v80, s37, v80
	v_mul_f32_e32 v81, s37, v81
	v_fma_f32 v80, v80, v252, v254
	v_fma_f32 v81, v81, v253, v255
	ds_read_b64 v[252:253], v168 offset:5120
	ds_read_b64 v[254:255], v168 offset:13312
	s_waitcnt lgkmcnt(2)
	v_mul_f32_e32 v82, s37, v82
	v_mul_f32_e32 v83, s37, v83
	v_fma_f32 v82, v82, v88, v242
	v_fma_f32 v83, v83, v89, v243
	ds_read_b64 v[88:89], v168 offset:5632
	ds_read_b64 v[242:243], v168 offset:13824
	s_waitcnt lgkmcnt(2)
	v_mul_f32_e32 v84, s37, v84
	v_mul_f32_e32 v85, s37, v85
	v_fma_f32 v84, v84, v252, v254
	v_fma_f32 v85, v85, v253, v255
	ds_read_b64 v[252:253], v168 offset:6144
	ds_read_b64 v[254:255], v168 offset:14336
	s_waitcnt lgkmcnt(2)
	v_mul_f32_e32 v86, s37, v86
	v_mul_f32_e32 v87, s37, v87
	v_fma_f32 v86, v86, v88, v242
	v_fma_f32 v87, v87, v89, v243
	v_cvt_pk_bf16_f32 v80, v80, v81
	v_cvt_pk_bf16_f32 v81, v82, v83
	v_cvt_pk_bf16_f32 v82, v84, v85
	v_cvt_pk_bf16_f32 v83, v86, v87
	global_store_dwordx4 v90, v[80:83], s[12:13] offset:2048
	ds_read_b64 v[88:89], v168 offset:6656
	ds_read_b64 v[242:243], v168 offset:14848
	s_waitcnt lgkmcnt(2)
	v_mul_f32_e32 v244, s37, v244
	v_mul_f32_e32 v245, s37, v245
	v_fma_f32 v244, v244, v252, v254
	v_fma_f32 v245, v245, v253, v255
	ds_read_b64 v[252:253], v168 offset:7168
	ds_read_b64 v[254:255], v168 offset:15360
	s_waitcnt lgkmcnt(2)
	v_mul_f32_e32 v246, s37, v246
	v_mul_f32_e32 v247, s37, v247
	v_fma_f32 v246, v246, v88, v242
	v_fma_f32 v247, v247, v89, v243
	ds_read_b64 v[88:89], v168 offset:7680
	ds_read_b64 v[242:243], v168 offset:15872
	s_waitcnt lgkmcnt(2)
	v_mul_f32_e32 v248, s37, v248
	v_mul_f32_e32 v249, s37, v249
	v_fma_f32 v248, v248, v252, v254
	v_fma_f32 v249, v249, v253, v255
	s_waitcnt lgkmcnt(0)
	v_mul_f32_e32 v250, s37, v250
	v_mul_f32_e32 v251, s37, v251
	v_fma_f32 v250, v250, v88, v242
	v_fma_f32 v251, v251, v89, v243
	v_cvt_pk_bf16_f32 v244, v244, v245
	v_cvt_pk_bf16_f32 v245, v246, v247
	v_cvt_pk_bf16_f32 v246, v248, v249
	v_cvt_pk_bf16_f32 v247, v250, v251
	global_store_dwordx4 v90, v[244:247], s[12:13] offset:3072
	s_cmp_lt_u32 s36, 4
	s_cbranch_scc0 .LBB0_1118
	v_readlane_b32 s38, v241, 0
	s_lshl_b32 s30, s38, 14
	v_subrev_u32_e32 v90, s30, v90
	s_waitcnt vmcnt(12)
	v_lshlrev_b32_e32 v64, 16, v16
	v_and_b32_e32 v65, 0xffff0000, v16
	v_lshlrev_b32_e32 v66, 16, v17
	v_and_b32_e32 v67, 0xffff0000, v17
	v_lshlrev_b32_e32 v68, 16, v18
	v_and_b32_e32 v69, 0xffff0000, v18
	v_lshlrev_b32_e32 v70, 16, v19
	v_and_b32_e32 v71, 0xffff0000, v19
	v_lshlrev_b32_e32 v72, 16, v20
	v_and_b32_e32 v73, 0xffff0000, v20
	v_lshlrev_b32_e32 v74, 16, v21
	v_and_b32_e32 v75, 0xffff0000, v21
	v_lshlrev_b32_e32 v76, 16, v22
	v_and_b32_e32 v77, 0xffff0000, v22
	v_lshlrev_b32_e32 v78, 16, v23
	v_and_b32_e32 v79, 0xffff0000, v23
	v_lshlrev_b32_e32 v80, 16, v24
	v_and_b32_e32 v81, 0xffff0000, v24
	v_lshlrev_b32_e32 v82, 16, v25
	v_and_b32_e32 v83, 0xffff0000, v25
	v_lshlrev_b32_e32 v84, 16, v26
	v_and_b32_e32 v85, 0xffff0000, v26
	v_lshlrev_b32_e32 v86, 16, v27
	v_and_b32_e32 v87, 0xffff0000, v27
	v_lshlrev_b32_e32 v244, 16, v28
	v_and_b32_e32 v245, 0xffff0000, v28
	v_lshlrev_b32_e32 v246, 16, v29
	v_and_b32_e32 v247, 0xffff0000, v29
	v_lshlrev_b32_e32 v248, 16, v30
	v_and_b32_e32 v249, 0xffff0000, v30
	v_lshlrev_b32_e32 v250, 16, v31
	v_and_b32_e32 v251, 0xffff0000, v31
	s_add_u32 s12, s8, 0xc00000
	s_addc_u32 s13, s9, 0
	global_load_dwordx4 v[16:19], v90, s[12:13]
	global_load_dwordx4 v[20:23], v90, s[12:13] offset:1024
	global_load_dwordx4 v[24:27], v90, s[12:13] offset:2048
	global_load_dwordx4 v[28:31], v90, s[12:13] offset:3072
	s_waitcnt vmcnt(12)
	v_lshlrev_b32_e32 v252, 16, v32
	v_and_b32_e32 v253, 0xffff0000, v32
	v_add_f32_e32 v64, v64, v252
	v_add_f32_e32 v65, v65, v253
	v_lshlrev_b32_e32 v252, 16, v33
	v_and_b32_e32 v253, 0xffff0000, v33
	v_add_f32_e32 v66, v66, v252
	v_add_f32_e32 v67, v67, v253
	v_lshlrev_b32_e32 v252, 16, v34
	v_and_b32_e32 v253, 0xffff0000, v34
	v_add_f32_e32 v68, v68, v252
	v_add_f32_e32 v69, v69, v253
	v_lshlrev_b32_e32 v252, 16, v35
	v_and_b32_e32 v253, 0xffff0000, v35
	v_add_f32_e32 v70, v70, v252
	v_add_f32_e32 v71, v71, v253
	v_lshlrev_b32_e32 v252, 16, v36
	v_and_b32_e32 v253, 0xffff0000, v36
	v_add_f32_e32 v72, v72, v252
	v_add_f32_e32 v73, v73, v253
	v_lshlrev_b32_e32 v252, 16, v37
	v_and_b32_e32 v253, 0xffff0000, v37
	v_add_f32_e32 v74, v74, v252
	v_add_f32_e32 v75, v75, v253
	v_lshlrev_b32_e32 v252, 16, v38
	v_and_b32_e32 v253, 0xffff0000, v38
	v_add_f32_e32 v76, v76, v252
	v_add_f32_e32 v77, v77, v253
	v_lshlrev_b32_e32 v252, 16, v39
	v_and_b32_e32 v253, 0xffff0000, v39
	v_add_f32_e32 v78, v78, v252
	v_add_f32_e32 v79, v79, v253
	v_lshlrev_b32_e32 v252, 16, v40
	v_and_b32_e32 v253, 0xffff0000, v40
	v_add_f32_e32 v80, v80, v252
	v_add_f32_e32 v81, v81, v253
	v_lshlrev_b32_e32 v252, 16, v41
	v_and_b32_e32 v253, 0xffff0000, v41
	v_add_f32_e32 v82, v82, v252
	v_add_f32_e32 v83, v83, v253
	v_lshlrev_b32_e32 v252, 16, v42
	v_and_b32_e32 v253, 0xffff0000, v42
	v_add_f32_e32 v84, v84, v252
	v_add_f32_e32 v85, v85, v253
	v_lshlrev_b32_e32 v252, 16, v43
	v_and_b32_e32 v253, 0xffff0000, v43
	v_add_f32_e32 v86, v86, v252
	v_add_f32_e32 v87, v87, v253
	v_lshlrev_b32_e32 v252, 16, v44
	v_and_b32_e32 v253, 0xffff0000, v44
	v_add_f32_e32 v244, v244, v252
	v_add_f32_e32 v245, v245, v253
	v_lshlrev_b32_e32 v252, 16, v45
	v_and_b32_e32 v253, 0xffff0000, v45
	v_add_f32_e32 v246, v246, v252
	v_add_f32_e32 v247, v247, v253
	v_lshlrev_b32_e32 v252, 16, v46
	v_and_b32_e32 v253, 0xffff0000, v46
	v_add_f32_e32 v248, v248, v252
	v_add_f32_e32 v249, v249, v253
	v_lshlrev_b32_e32 v252, 16, v47
	v_and_b32_e32 v253, 0xffff0000, v47
	v_add_f32_e32 v250, v250, v252
	v_add_f32_e32 v251, v251, v253
	s_add_u32 s12, s8, 0x1000000
	s_addc_u32 s13, s9, 0
	global_load_dwordx4 v[32:35], v90, s[12:13]
	global_load_dwordx4 v[36:39], v90, s[12:13] offset:1024
	global_load_dwordx4 v[40:43], v90, s[12:13] offset:2048
	global_load_dwordx4 v[44:47], v90, s[12:13] offset:3072
	s_waitcnt vmcnt(8)
	v_lshlrev_b32_e32 v252, 16, v48
	v_and_b32_e32 v253, 0xffff0000, v48
	v_add_f32_e32 v64, v64, v252
	v_add_f32_e32 v65, v65, v253
	v_lshlrev_b32_e32 v252, 16, v49
	v_and_b32_e32 v253, 0xffff0000, v49
	v_add_f32_e32 v66, v66, v252
	v_add_f32_e32 v67, v67, v253
	v_lshlrev_b32_e32 v252, 16, v50
	v_and_b32_e32 v253, 0xffff0000, v50
	v_add_f32_e32 v68, v68, v252
	v_add_f32_e32 v69, v69, v253
	v_lshlrev_b32_e32 v252, 16, v51
	v_and_b32_e32 v253, 0xffff0000, v51
	v_add_f32_e32 v70, v70, v252
	v_add_f32_e32 v71, v71, v253
	v_lshlrev_b32_e32 v252, 16, v52
	v_and_b32_e32 v253, 0xffff0000, v52
	v_add_f32_e32 v72, v72, v252
	v_add_f32_e32 v73, v73, v253
	v_lshlrev_b32_e32 v252, 16, v53
	v_and_b32_e32 v253, 0xffff0000, v53
	v_add_f32_e32 v74, v74, v252
	v_add_f32_e32 v75, v75, v253
	v_lshlrev_b32_e32 v252, 16, v54
	v_and_b32_e32 v253, 0xffff0000, v54
	v_add_f32_e32 v76, v76, v252
	v_add_f32_e32 v77, v77, v253
	v_lshlrev_b32_e32 v252, 16, v55
	v_and_b32_e32 v253, 0xffff0000, v55
	v_add_f32_e32 v78, v78, v252
	v_add_f32_e32 v79, v79, v253
	v_lshlrev_b32_e32 v252, 16, v56
	v_and_b32_e32 v253, 0xffff0000, v56
	v_add_f32_e32 v80, v80, v252
	v_add_f32_e32 v81, v81, v253
	v_lshlrev_b32_e32 v252, 16, v57
	v_and_b32_e32 v253, 0xffff0000, v57
	v_add_f32_e32 v82, v82, v252
	v_add_f32_e32 v83, v83, v253
	v_lshlrev_b32_e32 v252, 16, v58
	v_and_b32_e32 v253, 0xffff0000, v58
	v_add_f32_e32 v84, v84, v252
	v_add_f32_e32 v85, v85, v253
	v_lshlrev_b32_e32 v252, 16, v59
	v_and_b32_e32 v253, 0xffff0000, v59
	v_add_f32_e32 v86, v86, v252
	v_add_f32_e32 v87, v87, v253
	v_lshlrev_b32_e32 v252, 16, v60
	v_and_b32_e32 v253, 0xffff0000, v60
	v_add_f32_e32 v244, v244, v252
	v_add_f32_e32 v245, v245, v253
	v_lshlrev_b32_e32 v252, 16, v61
	v_and_b32_e32 v253, 0xffff0000, v61
	v_add_f32_e32 v246, v246, v252
	v_add_f32_e32 v247, v247, v253
	v_lshlrev_b32_e32 v252, 16, v62
	v_and_b32_e32 v253, 0xffff0000, v62
	v_add_f32_e32 v248, v248, v252
	v_add_f32_e32 v249, v249, v253
	v_lshlrev_b32_e32 v252, 16, v63
	v_and_b32_e32 v253, 0xffff0000, v63
	v_add_f32_e32 v250, v250, v252
	v_add_f32_e32 v251, v251, v253
	s_add_u32 s12, s8, 0x1400000
	s_addc_u32 s13, s9, 0
	global_load_dwordx4 v[48:51], v90, s[12:13]
	global_load_dwordx4 v[52:55], v90, s[12:13] offset:1024
	global_load_dwordx4 v[56:59], v90, s[12:13] offset:2048
	global_load_dwordx4 v[60:63], v90, s[12:13] offset:3072
	s_waitcnt vmcnt(8)
	v_lshlrev_b32_e32 v252, 16, v16
	v_and_b32_e32 v253, 0xffff0000, v16
	v_add_f32_e32 v64, v64, v252
	v_add_f32_e32 v65, v65, v253
	v_lshlrev_b32_e32 v252, 16, v17
	v_and_b32_e32 v253, 0xffff0000, v17
	v_add_f32_e32 v66, v66, v252
	v_add_f32_e32 v67, v67, v253
	v_lshlrev_b32_e32 v252, 16, v18
	v_and_b32_e32 v253, 0xffff0000, v18
	v_add_f32_e32 v68, v68, v252
	v_add_f32_e32 v69, v69, v253
	v_lshlrev_b32_e32 v252, 16, v19
	v_and_b32_e32 v253, 0xffff0000, v19
	v_add_f32_e32 v70, v70, v252
	v_add_f32_e32 v71, v71, v253
	v_lshlrev_b32_e32 v252, 16, v20
	v_and_b32_e32 v253, 0xffff0000, v20
	v_add_f32_e32 v72, v72, v252
	v_add_f32_e32 v73, v73, v253
	v_lshlrev_b32_e32 v252, 16, v21
	v_and_b32_e32 v253, 0xffff0000, v21
	v_add_f32_e32 v74, v74, v252
	v_add_f32_e32 v75, v75, v253
	v_lshlrev_b32_e32 v252, 16, v22
	v_and_b32_e32 v253, 0xffff0000, v22
	v_add_f32_e32 v76, v76, v252
	v_add_f32_e32 v77, v77, v253
	v_lshlrev_b32_e32 v252, 16, v23
	v_and_b32_e32 v253, 0xffff0000, v23
	v_add_f32_e32 v78, v78, v252
	v_add_f32_e32 v79, v79, v253
	v_lshlrev_b32_e32 v252, 16, v24
	v_and_b32_e32 v253, 0xffff0000, v24
	v_add_f32_e32 v80, v80, v252
	v_add_f32_e32 v81, v81, v253
	v_lshlrev_b32_e32 v252, 16, v25
	v_and_b32_e32 v253, 0xffff0000, v25
	v_add_f32_e32 v82, v82, v252
	v_add_f32_e32 v83, v83, v253
	v_lshlrev_b32_e32 v252, 16, v26
	v_and_b32_e32 v253, 0xffff0000, v26
	v_add_f32_e32 v84, v84, v252
	v_add_f32_e32 v85, v85, v253
	v_lshlrev_b32_e32 v252, 16, v27
	v_and_b32_e32 v253, 0xffff0000, v27
	v_add_f32_e32 v86, v86, v252
	v_add_f32_e32 v87, v87, v253
	v_lshlrev_b32_e32 v252, 16, v28
	v_and_b32_e32 v253, 0xffff0000, v28
	v_add_f32_e32 v244, v244, v252
	v_add_f32_e32 v245, v245, v253
	v_lshlrev_b32_e32 v252, 16, v29
	v_and_b32_e32 v253, 0xffff0000, v29
	v_add_f32_e32 v246, v246, v252
	v_add_f32_e32 v247, v247, v253
	v_lshlrev_b32_e32 v252, 16, v30
	v_and_b32_e32 v253, 0xffff0000, v30
	v_add_f32_e32 v248, v248, v252
	v_add_f32_e32 v249, v249, v253
	v_lshlrev_b32_e32 v252, 16, v31
	v_and_b32_e32 v253, 0xffff0000, v31
	v_add_f32_e32 v250, v250, v252
	v_add_f32_e32 v251, v251, v253
	s_add_u32 s12, s8, 0x1800000
	s_addc_u32 s13, s9, 0
	global_load_dwordx4 v[16:19], v90, s[12:13]
	global_load_dwordx4 v[20:23], v90, s[12:13] offset:1024
	global_load_dwordx4 v[24:27], v90, s[12:13] offset:2048
	global_load_dwordx4 v[28:31], v90, s[12:13] offset:3072
	s_waitcnt vmcnt(8)
	v_lshlrev_b32_e32 v252, 16, v32
	v_and_b32_e32 v253, 0xffff0000, v32
	v_add_f32_e32 v64, v64, v252
	v_add_f32_e32 v65, v65, v253
	v_lshlrev_b32_e32 v252, 16, v33
	v_and_b32_e32 v253, 0xffff0000, v33
	v_add_f32_e32 v66, v66, v252
	v_add_f32_e32 v67, v67, v253
	v_lshlrev_b32_e32 v252, 16, v34
	v_and_b32_e32 v253, 0xffff0000, v34
	v_add_f32_e32 v68, v68, v252
	v_add_f32_e32 v69, v69, v253
	v_lshlrev_b32_e32 v252, 16, v35
	v_and_b32_e32 v253, 0xffff0000, v35
	v_add_f32_e32 v70, v70, v252
	v_add_f32_e32 v71, v71, v253
	v_lshlrev_b32_e32 v252, 16, v36
	v_and_b32_e32 v253, 0xffff0000, v36
	v_add_f32_e32 v72, v72, v252
	v_add_f32_e32 v73, v73, v253
	v_lshlrev_b32_e32 v252, 16, v37
	v_and_b32_e32 v253, 0xffff0000, v37
	v_add_f32_e32 v74, v74, v252
	v_add_f32_e32 v75, v75, v253
	v_lshlrev_b32_e32 v252, 16, v38
	v_and_b32_e32 v253, 0xffff0000, v38
	v_add_f32_e32 v76, v76, v252
	v_add_f32_e32 v77, v77, v253
	v_lshlrev_b32_e32 v252, 16, v39
	v_and_b32_e32 v253, 0xffff0000, v39
	v_add_f32_e32 v78, v78, v252
	v_add_f32_e32 v79, v79, v253
	v_lshlrev_b32_e32 v252, 16, v40
	v_and_b32_e32 v253, 0xffff0000, v40
	v_add_f32_e32 v80, v80, v252
	v_add_f32_e32 v81, v81, v253
	v_lshlrev_b32_e32 v252, 16, v41
	v_and_b32_e32 v253, 0xffff0000, v41
	v_add_f32_e32 v82, v82, v252
	v_add_f32_e32 v83, v83, v253
	v_lshlrev_b32_e32 v252, 16, v42
	v_and_b32_e32 v253, 0xffff0000, v42
	v_add_f32_e32 v84, v84, v252
	v_add_f32_e32 v85, v85, v253
	v_lshlrev_b32_e32 v252, 16, v43
	v_and_b32_e32 v253, 0xffff0000, v43
	v_add_f32_e32 v86, v86, v252
	v_add_f32_e32 v87, v87, v253
	v_lshlrev_b32_e32 v252, 16, v44
	v_and_b32_e32 v253, 0xffff0000, v44
	v_add_f32_e32 v244, v244, v252
	v_add_f32_e32 v245, v245, v253
	v_lshlrev_b32_e32 v252, 16, v45
	v_and_b32_e32 v253, 0xffff0000, v45
	v_add_f32_e32 v246, v246, v252
	v_add_f32_e32 v247, v247, v253
	v_lshlrev_b32_e32 v252, 16, v46
	v_and_b32_e32 v253, 0xffff0000, v46
	v_add_f32_e32 v248, v248, v252
	v_add_f32_e32 v249, v249, v253
	v_lshlrev_b32_e32 v252, 16, v47
	v_and_b32_e32 v253, 0xffff0000, v47
	v_add_f32_e32 v250, v250, v252
	v_add_f32_e32 v251, v251, v253
	s_add_u32 s12, s8, 0x1c00000
	s_addc_u32 s13, s9, 0
	global_load_dwordx4 v[32:35], v90, s[12:13]
	global_load_dwordx4 v[36:39], v90, s[12:13] offset:1024
	global_load_dwordx4 v[40:43], v90, s[12:13] offset:2048
	global_load_dwordx4 v[44:47], v90, s[12:13] offset:3072
	s_waitcnt vmcnt(8)
	v_lshlrev_b32_e32 v252, 16, v48
	v_and_b32_e32 v253, 0xffff0000, v48
	v_add_f32_e32 v64, v64, v252
	v_add_f32_e32 v65, v65, v253
	v_lshlrev_b32_e32 v252, 16, v49
	v_and_b32_e32 v253, 0xffff0000, v49
	v_add_f32_e32 v66, v66, v252
	v_add_f32_e32 v67, v67, v253
	v_lshlrev_b32_e32 v252, 16, v50
	v_and_b32_e32 v253, 0xffff0000, v50
	v_add_f32_e32 v68, v68, v252
	v_add_f32_e32 v69, v69, v253
	v_lshlrev_b32_e32 v252, 16, v51
	v_and_b32_e32 v253, 0xffff0000, v51
	v_add_f32_e32 v70, v70, v252
	v_add_f32_e32 v71, v71, v253
	v_lshlrev_b32_e32 v252, 16, v52
	v_and_b32_e32 v253, 0xffff0000, v52
	v_add_f32_e32 v72, v72, v252
	v_add_f32_e32 v73, v73, v253
	v_lshlrev_b32_e32 v252, 16, v53
	v_and_b32_e32 v253, 0xffff0000, v53
	v_add_f32_e32 v74, v74, v252
	v_add_f32_e32 v75, v75, v253
	v_lshlrev_b32_e32 v252, 16, v54
	v_and_b32_e32 v253, 0xffff0000, v54
	v_add_f32_e32 v76, v76, v252
	v_add_f32_e32 v77, v77, v253
	v_lshlrev_b32_e32 v252, 16, v55
	v_and_b32_e32 v253, 0xffff0000, v55
	v_add_f32_e32 v78, v78, v252
	v_add_f32_e32 v79, v79, v253
	v_lshlrev_b32_e32 v252, 16, v56
	v_and_b32_e32 v253, 0xffff0000, v56
	v_add_f32_e32 v80, v80, v252
	v_add_f32_e32 v81, v81, v253
	v_lshlrev_b32_e32 v252, 16, v57
	v_and_b32_e32 v253, 0xffff0000, v57
	v_add_f32_e32 v82, v82, v252
	v_add_f32_e32 v83, v83, v253
	v_lshlrev_b32_e32 v252, 16, v58
	v_and_b32_e32 v253, 0xffff0000, v58
	v_add_f32_e32 v84, v84, v252
	v_add_f32_e32 v85, v85, v253
	v_lshlrev_b32_e32 v252, 16, v59
	v_and_b32_e32 v253, 0xffff0000, v59
	v_add_f32_e32 v86, v86, v252
	v_add_f32_e32 v87, v87, v253
	v_lshlrev_b32_e32 v252, 16, v60
	v_and_b32_e32 v253, 0xffff0000, v60
	v_add_f32_e32 v244, v244, v252
	v_add_f32_e32 v245, v245, v253
	v_lshlrev_b32_e32 v252, 16, v61
	v_and_b32_e32 v253, 0xffff0000, v61
	v_add_f32_e32 v246, v246, v252
	v_add_f32_e32 v247, v247, v253
	v_lshlrev_b32_e32 v252, 16, v62
	v_and_b32_e32 v253, 0xffff0000, v62
	v_add_f32_e32 v248, v248, v252
	v_add_f32_e32 v249, v249, v253
	v_lshlrev_b32_e32 v252, 16, v63
	v_and_b32_e32 v253, 0xffff0000, v63
	v_add_f32_e32 v250, v250, v252
	v_add_f32_e32 v251, v251, v253
	s_waitcnt vmcnt(4)
	v_lshlrev_b32_e32 v252, 16, v16
	v_and_b32_e32 v253, 0xffff0000, v16
	v_add_f32_e32 v64, v64, v252
	v_add_f32_e32 v65, v65, v253
	v_lshlrev_b32_e32 v252, 16, v17
	v_and_b32_e32 v253, 0xffff0000, v17
	v_add_f32_e32 v66, v66, v252
	v_add_f32_e32 v67, v67, v253
	v_lshlrev_b32_e32 v252, 16, v18
	v_and_b32_e32 v253, 0xffff0000, v18
	v_add_f32_e32 v68, v68, v252
	v_add_f32_e32 v69, v69, v253
	v_lshlrev_b32_e32 v252, 16, v19
	v_and_b32_e32 v253, 0xffff0000, v19
	v_add_f32_e32 v70, v70, v252
	v_add_f32_e32 v71, v71, v253
	v_lshlrev_b32_e32 v252, 16, v20
	v_and_b32_e32 v253, 0xffff0000, v20
	v_add_f32_e32 v72, v72, v252
	v_add_f32_e32 v73, v73, v253
	v_lshlrev_b32_e32 v252, 16, v21
	v_and_b32_e32 v253, 0xffff0000, v21
	v_add_f32_e32 v74, v74, v252
	v_add_f32_e32 v75, v75, v253
	v_lshlrev_b32_e32 v252, 16, v22
	v_and_b32_e32 v253, 0xffff0000, v22
	v_add_f32_e32 v76, v76, v252
	v_add_f32_e32 v77, v77, v253
	v_lshlrev_b32_e32 v252, 16, v23
	v_and_b32_e32 v253, 0xffff0000, v23
	v_add_f32_e32 v78, v78, v252
	v_add_f32_e32 v79, v79, v253
	v_lshlrev_b32_e32 v252, 16, v24
	v_and_b32_e32 v253, 0xffff0000, v24
	v_add_f32_e32 v80, v80, v252
	v_add_f32_e32 v81, v81, v253
	v_lshlrev_b32_e32 v252, 16, v25
	v_and_b32_e32 v253, 0xffff0000, v25
	v_add_f32_e32 v82, v82, v252
	v_add_f32_e32 v83, v83, v253
	v_lshlrev_b32_e32 v252, 16, v26
	v_and_b32_e32 v253, 0xffff0000, v26
	v_add_f32_e32 v84, v84, v252
	v_add_f32_e32 v85, v85, v253
	v_lshlrev_b32_e32 v252, 16, v27
	v_and_b32_e32 v253, 0xffff0000, v27
	v_add_f32_e32 v86, v86, v252
	v_add_f32_e32 v87, v87, v253
	v_lshlrev_b32_e32 v252, 16, v28
	v_and_b32_e32 v253, 0xffff0000, v28
	v_add_f32_e32 v244, v244, v252
	v_add_f32_e32 v245, v245, v253
	v_lshlrev_b32_e32 v252, 16, v29
	v_and_b32_e32 v253, 0xffff0000, v29
	v_add_f32_e32 v246, v246, v252
	v_add_f32_e32 v247, v247, v253
	v_lshlrev_b32_e32 v252, 16, v30
	v_and_b32_e32 v253, 0xffff0000, v30
	v_add_f32_e32 v248, v248, v252
	v_add_f32_e32 v249, v249, v253
	v_lshlrev_b32_e32 v252, 16, v31
	v_and_b32_e32 v253, 0xffff0000, v31
	v_add_f32_e32 v250, v250, v252
	v_add_f32_e32 v251, v251, v253
	s_waitcnt vmcnt(0)
	v_lshlrev_b32_e32 v252, 16, v32
	v_and_b32_e32 v253, 0xffff0000, v32
	v_add_f32_e32 v64, v64, v252
	v_add_f32_e32 v65, v65, v253
	v_lshlrev_b32_e32 v252, 16, v33
	v_and_b32_e32 v253, 0xffff0000, v33
	v_add_f32_e32 v66, v66, v252
	v_add_f32_e32 v67, v67, v253
	v_lshlrev_b32_e32 v252, 16, v34
	v_and_b32_e32 v253, 0xffff0000, v34
	v_add_f32_e32 v68, v68, v252
	v_add_f32_e32 v69, v69, v253
	v_lshlrev_b32_e32 v252, 16, v35
	v_and_b32_e32 v253, 0xffff0000, v35
	v_add_f32_e32 v70, v70, v252
	v_add_f32_e32 v71, v71, v253
	v_lshlrev_b32_e32 v252, 16, v36
	v_and_b32_e32 v253, 0xffff0000, v36
	v_add_f32_e32 v72, v72, v252
	v_add_f32_e32 v73, v73, v253
	v_lshlrev_b32_e32 v252, 16, v37
	v_and_b32_e32 v253, 0xffff0000, v37
	v_add_f32_e32 v74, v74, v252
	v_add_f32_e32 v75, v75, v253
	v_lshlrev_b32_e32 v252, 16, v38
	v_and_b32_e32 v253, 0xffff0000, v38
	v_add_f32_e32 v76, v76, v252
	v_add_f32_e32 v77, v77, v253
	v_lshlrev_b32_e32 v252, 16, v39
	v_and_b32_e32 v253, 0xffff0000, v39
	v_add_f32_e32 v78, v78, v252
	v_add_f32_e32 v79, v79, v253
	v_lshlrev_b32_e32 v252, 16, v40
	v_and_b32_e32 v253, 0xffff0000, v40
	v_add_f32_e32 v80, v80, v252
	v_add_f32_e32 v81, v81, v253
	v_lshlrev_b32_e32 v252, 16, v41
	v_and_b32_e32 v253, 0xffff0000, v41
	v_add_f32_e32 v82, v82, v252
	v_add_f32_e32 v83, v83, v253
	v_lshlrev_b32_e32 v252, 16, v42
	v_and_b32_e32 v253, 0xffff0000, v42
	v_add_f32_e32 v84, v84, v252
	v_add_f32_e32 v85, v85, v253
	v_lshlrev_b32_e32 v252, 16, v43
	v_and_b32_e32 v253, 0xffff0000, v43
	v_add_f32_e32 v86, v86, v252
	v_add_f32_e32 v87, v87, v253
	v_lshlrev_b32_e32 v252, 16, v44
	v_and_b32_e32 v253, 0xffff0000, v44
	v_add_f32_e32 v244, v244, v252
	v_add_f32_e32 v245, v245, v253
	v_lshlrev_b32_e32 v252, 16, v45
	v_and_b32_e32 v253, 0xffff0000, v45
	v_add_f32_e32 v246, v246, v252
	v_add_f32_e32 v247, v247, v253
	v_lshlrev_b32_e32 v252, 16, v46
	v_and_b32_e32 v253, 0xffff0000, v46
	v_add_f32_e32 v248, v248, v252
	v_add_f32_e32 v249, v249, v253
	v_lshlrev_b32_e32 v252, 16, v47
	v_and_b32_e32 v253, 0xffff0000, v47
	v_add_f32_e32 v250, v250, v252
	v_add_f32_e32 v251, v251, v253
	v_and_b32_e32 v252, 0xffff0000, v0
	v_lshlrev_b32_e32 v0, 16, v0
	v_fmac_f32_e32 v64, 0x3fb504f3, v0
	v_fmac_f32_e32 v65, 0x3fb504f3, v252
	v_and_b32_e32 v252, 0xffff0000, v1
	v_lshlrev_b32_e32 v1, 16, v1
	v_fmac_f32_e32 v66, 0x3fb504f3, v1
	v_fmac_f32_e32 v67, 0x3fb504f3, v252
	v_add_f32_e32 v252, v64, v65
	v_add_f32_e32 v253, v66, v67
	v_add_f32_e32 v254, v252, v253
	v_and_b32_e32 v252, 0xffff0000, v2
	v_lshlrev_b32_e32 v2, 16, v2
	v_fmac_f32_e32 v68, 0x3fb504f3, v2
	v_fmac_f32_e32 v69, 0x3fb504f3, v252
	v_and_b32_e32 v252, 0xffff0000, v3
	v_lshlrev_b32_e32 v3, 16, v3
	v_fmac_f32_e32 v70, 0x3fb504f3, v3
	v_fmac_f32_e32 v71, 0x3fb504f3, v252
	v_add_f32_e32 v252, v68, v69
	v_add_f32_e32 v253, v70, v71
	v_add_f32_e32 v252, v252, v253
	v_add_f32_e32 v254, v254, v252
	v_and_b32_e32 v252, 0xffff0000, v4
	v_lshlrev_b32_e32 v4, 16, v4
	v_fmac_f32_e32 v72, 0x3fb504f3, v4
	v_fmac_f32_e32 v73, 0x3fb504f3, v252
	v_and_b32_e32 v252, 0xffff0000, v5
	v_lshlrev_b32_e32 v5, 16, v5
	v_fmac_f32_e32 v74, 0x3fb504f3, v5
	v_fmac_f32_e32 v75, 0x3fb504f3, v252
	v_add_f32_e32 v252, v72, v73
	v_add_f32_e32 v253, v74, v75
	v_add_f32_e32 v252, v252, v253
	v_add_f32_e32 v254, v254, v252
	v_and_b32_e32 v252, 0xffff0000, v6
	v_lshlrev_b32_e32 v6, 16, v6
	v_fmac_f32_e32 v76, 0x3fb504f3, v6
	v_fmac_f32_e32 v77, 0x3fb504f3, v252
	v_and_b32_e32 v252, 0xffff0000, v7
	v_lshlrev_b32_e32 v7, 16, v7
	v_fmac_f32_e32 v78, 0x3fb504f3, v7
	v_fmac_f32_e32 v79, 0x3fb504f3, v252
	v_add_f32_e32 v252, v76, v77
	v_add_f32_e32 v253, v78, v79
	v_add_f32_e32 v252, v252, v253
	v_add_f32_e32 v254, v254, v252
	v_and_b32_e32 v252, 0xffff0000, v8
	v_lshlrev_b32_e32 v8, 16, v8
	v_fmac_f32_e32 v80, 0x3fb504f3, v8
	v_fmac_f32_e32 v81, 0x3fb504f3, v252
	v_and_b32_e32 v252, 0xffff0000, v9
	v_lshlrev_b32_e32 v9, 16, v9
	v_fmac_f32_e32 v82, 0x3fb504f3, v9
	v_fmac_f32_e32 v83, 0x3fb504f3, v252
	v_add_f32_e32 v252, v80, v81
	v_add_f32_e32 v253, v82, v83
	v_add_f32_e32 v252, v252, v253
	v_add_f32_e32 v254, v254, v252
	v_and_b32_e32 v252, 0xffff0000, v10
	v_lshlrev_b32_e32 v10, 16, v10
	v_fmac_f32_e32 v84, 0x3fb504f3, v10
	v_fmac_f32_e32 v85, 0x3fb504f3, v252
	v_and_b32_e32 v252, 0xffff0000, v11
	v_lshlrev_b32_e32 v11, 16, v11
	v_fmac_f32_e32 v86, 0x3fb504f3, v11
	v_fmac_f32_e32 v87, 0x3fb504f3, v252
	v_add_f32_e32 v252, v84, v85
	v_add_f32_e32 v253, v86, v87
	v_add_f32_e32 v252, v252, v253
	v_add_f32_e32 v254, v254, v252
	v_and_b32_e32 v252, 0xffff0000, v12
	v_lshlrev_b32_e32 v12, 16, v12
	v_fmac_f32_e32 v244, 0x3fb504f3, v12
	v_fmac_f32_e32 v245, 0x3fb504f3, v252
	v_and_b32_e32 v252, 0xffff0000, v13
	v_lshlrev_b32_e32 v13, 16, v13
	v_fmac_f32_e32 v246, 0x3fb504f3, v13
	v_fmac_f32_e32 v247, 0x3fb504f3, v252
	v_add_f32_e32 v252, v244, v245
	v_add_f32_e32 v253, v246, v247
	v_add_f32_e32 v252, v252, v253
	v_add_f32_e32 v254, v254, v252
	v_and_b32_e32 v252, 0xffff0000, v14
	v_lshlrev_b32_e32 v14, 16, v14
	v_fmac_f32_e32 v248, 0x3fb504f3, v14
	v_fmac_f32_e32 v249, 0x3fb504f3, v252
	v_and_b32_e32 v252, 0xffff0000, v15
	v_lshlrev_b32_e32 v15, 16, v15
	v_fmac_f32_e32 v250, 0x3fb504f3, v15
	v_fmac_f32_e32 v251, 0x3fb504f3, v252
	v_add_f32_e32 v252, v248, v249
	v_add_f32_e32 v253, v250, v251
	v_add_f32_e32 v252, v252, v253
	v_add_f32_e32 v254, v254, v252
	s_nop 1
	v_add_f32_dpp v252, v254, v254 quad_perm:[1,0,3,2] row_mask:0xf bank_mask:0xf
	s_nop 1
	v_add_f32_dpp v252, v252, v252 quad_perm:[2,3,0,1] row_mask:0xf bank_mask:0xf
	s_nop 1
	v_add_f32_dpp v252, v252, v252 row_half_mirror row_mask:0xf bank_mask:0xf
	s_nop 1
	v_add_f32_dpp v252, v252, v252 row_mirror row_mask:0xf bank_mask:0xf
	s_nop 1
	v_readlane_b32 s40, v252, 0
	v_readlane_b32 s41, v252, 16
	v_readlane_b32 s42, v252, 32
	v_readlane_b32 s43, v252, 48
	s_nop 1
	v_mov_b32_e32 v253, s40
	v_add_f32_e32 v253, s41, v253
	v_add_f32_e32 v253, s42, v253
	v_add_f32_e32 v253, s43, v253
	v_mul_f32_e32 v253, 0x3a000000, v253
	s_nop 0
	v_readfirstlane_b32 s37, v253
	s_nop 1
	v_subrev_f32_e32 v64, s37, v64
	v_subrev_f32_e32 v65, s37, v65
	v_subrev_f32_e32 v66, s37, v66
	v_subrev_f32_e32 v67, s37, v67
	v_subrev_f32_e32 v68, s37, v68
	v_subrev_f32_e32 v69, s37, v69
	v_subrev_f32_e32 v70, s37, v70
	v_subrev_f32_e32 v71, s37, v71
	v_mul_f32_e32 v252, v64, v64
	v_fmac_f32_e32 v252, v65, v65
	v_mul_f32_e32 v253, v66, v66
	v_fmac_f32_e32 v253, v67, v67
	v_add_f32_e32 v254, v252, v253
	v_mul_f32_e32 v252, v68, v68
	v_fmac_f32_e32 v252, v69, v69
	v_mul_f32_e32 v253, v70, v70
	v_fmac_f32_e32 v253, v71, v71
	v_add_f32_e32 v252, v252, v253
	v_add_f32_e32 v254, v254, v252
	v_subrev_f32_e32 v72, s37, v72
	v_subrev_f32_e32 v73, s37, v73
	v_subrev_f32_e32 v74, s37, v74
	v_subrev_f32_e32 v75, s37, v75
	v_subrev_f32_e32 v76, s37, v76
	v_subrev_f32_e32 v77, s37, v77
	v_subrev_f32_e32 v78, s37, v78
	v_subrev_f32_e32 v79, s37, v79
	v_mul_f32_e32 v252, v72, v72
	v_fmac_f32_e32 v252, v73, v73
	v_mul_f32_e32 v253, v74, v74
	v_fmac_f32_e32 v253, v75, v75
	v_add_f32_e32 v252, v252, v253
	v_add_f32_e32 v254, v254, v252
	v_mul_f32_e32 v252, v76, v76
	v_fmac_f32_e32 v252, v77, v77
	v_mul_f32_e32 v253, v78, v78
	v_fmac_f32_e32 v253, v79, v79
	v_add_f32_e32 v252, v252, v253
	v_add_f32_e32 v254, v254, v252
	v_subrev_f32_e32 v80, s37, v80
	v_subrev_f32_e32 v81, s37, v81
	v_subrev_f32_e32 v82, s37, v82
	v_subrev_f32_e32 v83, s37, v83
	v_subrev_f32_e32 v84, s37, v84
	v_subrev_f32_e32 v85, s37, v85
	v_subrev_f32_e32 v86, s37, v86
	v_subrev_f32_e32 v87, s37, v87
	v_mul_f32_e32 v252, v80, v80
	v_fmac_f32_e32 v252, v81, v81
	v_mul_f32_e32 v253, v82, v82
	v_fmac_f32_e32 v253, v83, v83
	v_add_f32_e32 v252, v252, v253
	v_add_f32_e32 v254, v254, v252
	v_mul_f32_e32 v252, v84, v84
	v_fmac_f32_e32 v252, v85, v85
	v_mul_f32_e32 v253, v86, v86
	v_fmac_f32_e32 v253, v87, v87
	v_add_f32_e32 v252, v252, v253
	v_add_f32_e32 v254, v254, v252
	v_subrev_f32_e32 v244, s37, v244
	v_subrev_f32_e32 v245, s37, v245
	v_subrev_f32_e32 v246, s37, v246
	v_subrev_f32_e32 v247, s37, v247
	v_subrev_f32_e32 v248, s37, v248
	v_subrev_f32_e32 v249, s37, v249
	v_subrev_f32_e32 v250, s37, v250
	v_subrev_f32_e32 v251, s37, v251
	v_mul_f32_e32 v252, v244, v244
	v_fmac_f32_e32 v252, v245, v245
	v_mul_f32_e32 v253, v246, v246
	v_fmac_f32_e32 v253, v247, v247
	v_add_f32_e32 v252, v252, v253
	v_add_f32_e32 v254, v254, v252
	v_mul_f32_e32 v252, v248, v248
	v_fmac_f32_e32 v252, v249, v249
	v_mul_f32_e32 v253, v250, v250
	v_fmac_f32_e32 v253, v251, v251
	v_add_f32_e32 v252, v252, v253
	v_add_f32_e32 v254, v254, v252
	s_nop 1
	v_add_f32_dpp v252, v254, v254 quad_perm:[1,0,3,2] row_mask:0xf bank_mask:0xf
	s_nop 1
	v_add_f32_dpp v252, v252, v252 quad_perm:[2,3,0,1] row_mask:0xf bank_mask:0xf
	s_nop 1
	v_add_f32_dpp v252, v252, v252 row_half_mirror row_mask:0xf bank_mask:0xf
	s_nop 1
	v_add_f32_dpp v252, v252, v252 row_mirror row_mask:0xf bank_mask:0xf
	s_nop 1
	v_readlane_b32 s40, v252, 0
	v_readlane_b32 s41, v252, 16
	v_readlane_b32 s42, v252, 32
	v_readlane_b32 s43, v252, 48
	s_nop 1
	v_mov_b32_e32 v253, s40
	v_add_f32_e32 v253, s41, v253
	v_add_f32_e32 v253, s42, v253
	v_add_f32_e32 v253, s43, v253
	v_mov_b32_e32 v252, 0x3a000000
	v_fmaak_f32 v253, v253, v252, 0x3727c5ac
	v_rsq_f32_e32 v253, v253
	s_nop 1
	v_readfirstlane_b32 s37, v253
	s_add_u32 s12, s4, 0x2000000
	s_addc_u32 s13, s5, 0
	ds_read_b64 v[252:253], v168
	ds_read_b64 v[254:255], v168 offset:8192
	ds_read_b64 v[88:89], v168 offset:512
	ds_read_b64 v[242:243], v168 offset:8704
	s_waitcnt lgkmcnt(2)
	v_mul_f32_e32 v64, s37, v64
	v_mul_f32_e32 v65, s37, v65
	v_fma_f32 v64, v64, v252, v254
	v_fma_f32 v65, v65, v253, v255
	ds_read_b64 v[252:253], v168 offset:1024
	ds_read_b64 v[254:255], v168 offset:9216
	s_waitcnt lgkmcnt(2)
	v_mul_f32_e32 v66, s37, v66
	v_mul_f32_e32 v67, s37, v67
	v_fma_f32 v66, v66, v88, v242
	v_fma_f32 v67, v67, v89, v243
	ds_read_b64 v[88:89], v168 offset:1536
	ds_read_b64 v[242:243], v168 offset:9728
	s_waitcnt lgkmcnt(2)
	v_mul_f32_e32 v68, s37, v68
	v_mul_f32_e32 v69, s37, v69
	v_fma_f32 v68, v68, v252, v254
	v_fma_f32 v69, v69, v253, v255
	ds_read_b64 v[252:253], v168 offset:2048
	ds_read_b64 v[254:255], v168 offset:10240
	s_waitcnt lgkmcnt(2)
	v_mul_f32_e32 v70, s37, v70
	v_mul_f32_e32 v71, s37, v71
	v_fma_f32 v70, v70, v88, v242
	v_fma_f32 v71, v71, v89, v243
	v_cvt_pk_bf16_f32 v64, v64, v65
	v_cvt_pk_bf16_f32 v65, v66, v67
	v_cvt_pk_bf16_f32 v66, v68, v69
	v_cvt_pk_bf16_f32 v67, v70, v71
	global_store_dwordx4 v90, v[64:67], s[12:13]
	ds_read_b64 v[88:89], v168 offset:2560
	ds_read_b64 v[242:243], v168 offset:10752
	s_waitcnt lgkmcnt(2)
	v_mul_f32_e32 v72, s37, v72
	v_mul_f32_e32 v73, s37, v73
	v_fma_f32 v72, v72, v252, v254
	v_fma_f32 v73, v73, v253, v255
	ds_read_b64 v[252:253], v168 offset:3072
	ds_read_b64 v[254:255], v168 offset:11264
	s_waitcnt lgkmcnt(2)
	v_mul_f32_e32 v74, s37, v74
	v_mul_f32_e32 v75, s37, v75
	v_fma_f32 v74, v74, v88, v242
	v_fma_f32 v75, v75, v89, v243
	ds_read_b64 v[88:89], v168 offset:3584
	ds_read_b64 v[242:243], v168 offset:11776
	s_waitcnt lgkmcnt(2)
	v_mul_f32_e32 v76, s37, v76
	v_mul_f32_e32 v77, s37, v77
	v_fma_f32 v76, v76, v252, v254
	v_fma_f32 v77, v77, v253, v255
	ds_read_b64 v[252:253], v168 offset:4096
	ds_read_b64 v[254:255], v168 offset:12288
	s_waitcnt lgkmcnt(2)
	v_mul_f32_e32 v78, s37, v78
	v_mul_f32_e32 v79, s37, v79
	v_fma_f32 v78, v78, v88, v242
	v_fma_f32 v79, v79, v89, v243
	v_cvt_pk_bf16_f32 v72, v72, v73
	v_cvt_pk_bf16_f32 v73, v74, v75
	v_cvt_pk_bf16_f32 v74, v76, v77
	v_cvt_pk_bf16_f32 v75, v78, v79
	global_store_dwordx4 v90, v[72:75], s[12:13] offset:1024
	ds_read_b64 v[88:89], v168 offset:4608
	ds_read_b64 v[242:243], v168 offset:12800
	s_waitcnt lgkmcnt(2)
	v_mul_f32_e32 v80, s37, v80
	v_mul_f32_e32 v81, s37, v81
	v_fma_f32 v80, v80, v252, v254
	v_fma_f32 v81, v81, v253, v255
	ds_read_b64 v[252:253], v168 offset:5120
	ds_read_b64 v[254:255], v168 offset:13312
	s_waitcnt lgkmcnt(2)
	v_mul_f32_e32 v82, s37, v82
	v_mul_f32_e32 v83, s37, v83
	v_fma_f32 v82, v82, v88, v242
	v_fma_f32 v83, v83, v89, v243
	ds_read_b64 v[88:89], v168 offset:5632
	ds_read_b64 v[242:243], v168 offset:13824
	s_waitcnt lgkmcnt(2)
	v_mul_f32_e32 v84, s37, v84
	v_mul_f32_e32 v85, s37, v85
	v_fma_f32 v84, v84, v252, v254
	v_fma_f32 v85, v85, v253, v255
	ds_read_b64 v[252:253], v168 offset:6144
	ds_read_b64 v[254:255], v168 offset:14336
	s_waitcnt lgkmcnt(2)
	v_mul_f32_e32 v86, s37, v86
	v_mul_f32_e32 v87, s37, v87
	v_fma_f32 v86, v86, v88, v242
	v_fma_f32 v87, v87, v89, v243
	v_cvt_pk_bf16_f32 v80, v80, v81
	v_cvt_pk_bf16_f32 v81, v82, v83
	v_cvt_pk_bf16_f32 v82, v84, v85
	v_cvt_pk_bf16_f32 v83, v86, v87
	global_store_dwordx4 v90, v[80:83], s[12:13] offset:2048
	ds_read_b64 v[88:89], v168 offset:6656
	ds_read_b64 v[242:243], v168 offset:14848
	s_waitcnt lgkmcnt(2)
	v_mul_f32_e32 v244, s37, v244
	v_mul_f32_e32 v245, s37, v245
	v_fma_f32 v244, v244, v252, v254
	v_fma_f32 v245, v245, v253, v255
	ds_read_b64 v[252:253], v168 offset:7168
	ds_read_b64 v[254:255], v168 offset:15360
	s_waitcnt lgkmcnt(2)
	v_mul_f32_e32 v246, s37, v246
	v_mul_f32_e32 v247, s37, v247
	v_fma_f32 v246, v246, v88, v242
	v_fma_f32 v247, v247, v89, v243
	ds_read_b64 v[88:89], v168 offset:7680
	ds_read_b64 v[242:243], v168 offset:15872
	s_waitcnt lgkmcnt(2)
	v_mul_f32_e32 v248, s37, v248
	v_mul_f32_e32 v249, s37, v249
	v_fma_f32 v248, v248, v252, v254
	v_fma_f32 v249, v249, v253, v255
	s_waitcnt lgkmcnt(0)
	v_mul_f32_e32 v250, s37, v250
	v_mul_f32_e32 v251, s37, v251
	v_fma_f32 v250, v250, v88, v242
	v_fma_f32 v251, v251, v89, v243
	v_cvt_pk_bf16_f32 v244, v244, v245
	v_cvt_pk_bf16_f32 v245, v246, v247
	v_cvt_pk_bf16_f32 v246, v248, v249
	v_cvt_pk_bf16_f32 v247, v250, v251
	global_store_dwordx4 v90, v[244:247], s[12:13] offset:3072
	s_branch .LBB0_1118
.Lln1_old:
	v_lshlrev_b32_e32 v0, 2, v0
	v_and_b32_e32 v34, 0xfc, v0
	v_and_b32_e32 v0, 64, v188
	v_add_u32_e32 v0, 64, v0
	v_xor_b32_e32 v1, 32, v188
	v_cmp_lt_i32_e32 vcc, v1, v0
	v_readlane_b32 s4, v239, 37
	s_lshl_b32 s30, s4, 11
	v_cndmask_b32_e32 v1, v188, v1, vcc
	v_lshlrev_b32_e32 v35, 2, v1
	v_xor_b32_e32 v1, 16, v188
	v_cmp_lt_i32_e32 vcc, v1, v0
	v_readlane_b32 s36, v241, 27
	s_lshl_b64 s[4:5], s[30:31], 2
	v_cndmask_b32_e32 v1, v188, v1, vcc
	v_lshlrev_b32_e32 v86, 2, v1
	v_xor_b32_e32 v1, 8, v188
	v_cmp_lt_i32_e32 vcc, v1, v0
	v_readlane_b32 s44, v241, 35
	v_readlane_b32 s45, v241, 36
	v_cndmask_b32_e32 v1, v188, v1, vcc
	v_lshlrev_b32_e32 v87, 2, v1
	v_xor_b32_e32 v1, 4, v188
	v_cmp_lt_i32_e32 vcc, v1, v0
	s_add_u32 s6, s44, s4
	v_readlane_b32 s42, v241, 33
	v_cndmask_b32_e32 v1, v188, v1, vcc
	v_lshlrev_b32_e32 v88, 2, v1
	v_xor_b32_e32 v1, 2, v188
	v_cmp_lt_i32_e32 vcc, v1, v0
	s_addc_u32 s7, s45, s5
	v_readlane_b32 s43, v241, 34
	v_cndmask_b32_e32 v1, v188, v1, vcc
	v_lshlrev_b32_e32 v89, 2, v1
	v_xor_b32_e32 v1, 1, v188
	v_cmp_lt_i32_e32 vcc, v1, v0
	s_add_u32 s4, s42, s4
	v_lshlrev_b32_e32 v168, 2, v34
	v_cndmask_b32_e32 v0, v188, v1, vcc
	s_addc_u32 s5, s43, s5
	v_lshlrev_b32_e32 v90, 2, v0
	v_or_b32_e32 v0, 0x1000, v168
	v_mov_b32_e32 v1, v169
	v_lshl_add_u64 v[40:41], s[4:5], 0, v[0:1]
	v_lshl_add_u64 v[42:43], s[6:7], 0, v[0:1]
	v_or_b32_e32 v0, 0x1400, v168
	v_lshl_add_u64 v[36:37], s[4:5], 0, v[168:169]
	v_lshl_add_u64 v[38:39], s[6:7], 0, v[168:169]
	v_lshl_add_u64 v[44:45], s[4:5], 0, v[0:1]
	v_lshl_add_u64 v[46:47], s[6:7], 0, v[0:1]
	v_or_b32_e32 v0, 0x1800, v168
	v_or_b32_e32 v168, 0x1c00, v168
	v_lshl_add_u64 v[48:49], s[4:5], 0, v[0:1]
	v_lshl_add_u64 v[52:53], s[4:5], 0, v[168:169]
	v_readlane_b32 s4, v240, 24
	v_lshl_add_u64 v[54:55], s[6:7], 0, v[168:169]
	v_lshlrev_b32_e32 v168, 1, v34
	v_readlane_b32 s5, v240, 25
	v_lshl_add_u64 v[50:51], s[6:7], 0, v[0:1]
	v_readlane_b32 s37, v241, 28
	v_lshl_add_u64 v[56:57], s[4:5], 0, v[168:169]
	s_mov_b64 s[4:5], 0
	v_readlane_b32 s38, v241, 29
	v_readlane_b32 s39, v241, 30
	v_readlane_b32 s40, v241, 31
	v_readlane_b32 s41, v241, 32
	v_readlane_b32 s46, v241, 37
	v_readlane_b32 s47, v241, 38
	v_readlane_b32 s48, v241, 39
	v_readlane_b32 s49, v241, 40
	v_readlane_b32 s50, v241, 41
	v_readlane_b32 s51, v241, 42
	s_branch .LBB0_1086

.Lln2_done:
	s_getpc_b64 s[98:99]

.LBB0_1636:
	v_readlane_b32 s30, v241, 9
	s_cmpk_lg_i32 s30, 0x100
	s_cbranch_scc1 .Lln2_old
	v_readlane_b32 s91, v241, 0
	v_readlane_b32 s12, v239, 42
	v_readlane_b32 s13, v239, 43
	v_readlane_b32 s30, v239, 37
	s_add_u32 s4, s12, 0xc700000
	s_addc_u32 s5, s13, 0
	s_add_u32 s6, s12, 0x1d080000
	s_addc_u32 s7, s13, 0
	s_add_u32 s8, s12, 0x33ac0000
	s_addc_u32 s9, s13, 0
	s_mov_b32 s90, s30
	s_lshl_b32 s30, s30, 13
	v_readlane_b32 s86, v241, 3
	v_readlane_b32 s87, v241, 4
	v_readlane_b32 s88, v241, 5
	v_readlane_b32 s89, v241, 6
	s_add_u32 s86, s86, s30
	s_addc_u32 s87, s87, 0
	s_add_u32 s88, s88, s30
	s_addc_u32 s89, s89, 0
	v_lshlrev_b32_e32 v252, 4, v178
	global_load_dwordx4 v[0:3], v252, s[86:87]
	global_load_dwordx4 v[4:7], v252, s[88:89]
	v_lshrrev_b32_e32 v253, 7, v178
	v_lshlrev_b32_e32 v253, 11, v253
	v_and_b32_e32 v254, 1, v178
	v_lshl_or_b32 v253, v254, 10, v253
	v_bfe_u32 v254, v178, 1, 6
	v_lshl_or_b32 v253, v254, 3, v253
	v_readfirstlane_b32 s84, v178
	v_and_b32_e32 v168, 63, v178
	s_lshr_b32 s84, s84, 6
	s_lshl_b32 s30, s91, 3
	s_add_i32 s30, s30, s84
	s_lshl_b32 s30, s30, 12
	v_lshl_add_u32 v90, v168, 4, s30
	v_lshlrev_b32_e32 v168, 3, v168
	s_waitcnt vmcnt(0)
	ds_write_b64 v253, v[0:1]
	ds_write_b64 v253, v[2:3] offset:512
	ds_write_b64 v253, v[4:5] offset:8192
	ds_write_b64 v253, v[6:7] offset:8704
	s_waitcnt lgkmcnt(0)
	s_barrier
	global_load_dwordx4 v[0:3], v90, s[4:5]
	global_load_dwordx4 v[4:7], v90, s[4:5] offset:1024
	global_load_dwordx4 v[8:11], v90, s[4:5] offset:2048
	global_load_dwordx4 v[12:15], v90, s[4:5] offset:3072
	global_load_dwordx4 v[16:19], v90, s[6:7]
	global_load_dwordx4 v[20:23], v90, s[6:7] offset:1024
	global_load_dwordx4 v[24:27], v90, s[6:7] offset:2048
	global_load_dwordx4 v[28:31], v90, s[6:7] offset:3072
	s_add_u32 s12, s4, 0x800000
	s_addc_u32 s13, s5, 0
	global_load_dwordx4 v[32:35], v90, s[12:13]
	global_load_dwordx4 v[36:39], v90, s[12:13] offset:1024
	global_load_dwordx4 v[40:43], v90, s[12:13] offset:2048
	global_load_dwordx4 v[44:47], v90, s[12:13] offset:3072
	s_add_u32 s12, s6, 0x800000
	s_addc_u32 s13, s7, 0
	global_load_dwordx4 v[48:51], v90, s[12:13]
	global_load_dwordx4 v[52:55], v90, s[12:13] offset:1024
	global_load_dwordx4 v[56:59], v90, s[12:13] offset:2048
	global_load_dwordx4 v[60:63], v90, s[12:13] offset:3072
	s_waitcnt vmcnt(8)
	v_lshlrev_b32_e32 v64, 16, v16
	v_and_b32_e32 v65, 0xffff0000, v16
	v_and_b32_e32 v252, 0xffff0000, v0
	v_lshlrev_b32_e32 v0, 16, v0
	v_fmac_f32_e32 v64, 0x3fb504f3, v0
	v_fmac_f32_e32 v65, 0x3fb504f3, v252
	v_lshlrev_b32_e32 v66, 16, v17
	v_and_b32_e32 v67, 0xffff0000, v17
	v_and_b32_e32 v252, 0xffff0000, v1
	v_lshlrev_b32_e32 v1, 16, v1
	v_fmac_f32_e32 v66, 0x3fb504f3, v1
	v_fmac_f32_e32 v67, 0x3fb504f3, v252
	v_add_f32_e32 v252, v64, v65
	v_add_f32_e32 v253, v66, v67
	v_add_f32_e32 v254, v252, v253
	v_lshlrev_b32_e32 v68, 16, v18
	v_and_b32_e32 v69, 0xffff0000, v18
	v_and_b32_e32 v252, 0xffff0000, v2
	v_lshlrev_b32_e32 v2, 16, v2
	v_fmac_f32_e32 v68, 0x3fb504f3, v2
	v_fmac_f32_e32 v69, 0x3fb504f3, v252
	v_lshlrev_b32_e32 v70, 16, v19
	v_and_b32_e32 v71, 0xffff0000, v19
	v_and_b32_e32 v252, 0xffff0000, v3
	v_lshlrev_b32_e32 v3, 16, v3
	v_fmac_f32_e32 v70, 0x3fb504f3, v3
	v_fmac_f32_e32 v71, 0x3fb504f3, v252
	v_add_f32_e32 v252, v68, v69
	v_add_f32_e32 v253, v70, v71
	v_add_f32_e32 v252, v252, v253
	v_add_f32_e32 v254, v254, v252
	v_lshlrev_b32_e32 v72, 16, v20
	v_and_b32_e32 v73, 0xffff0000, v20
	v_and_b32_e32 v252, 0xffff0000, v4
	v_lshlrev_b32_e32 v4, 16, v4
	v_fmac_f32_e32 v72, 0x3fb504f3, v4
	v_fmac_f32_e32 v73, 0x3fb504f3, v252
	v_lshlrev_b32_e32 v74, 16, v21
	v_and_b32_e32 v75, 0xffff0000, v21
	v_and_b32_e32 v252, 0xffff0000, v5
	v_lshlrev_b32_e32 v5, 16, v5
	v_fmac_f32_e32 v74, 0x3fb504f3, v5
	v_fmac_f32_e32 v75, 0x3fb504f3, v252
	v_add_f32_e32 v252, v72, v73
	v_add_f32_e32 v253, v74, v75
	v_add_f32_e32 v252, v252, v253
	v_add_f32_e32 v254, v254, v252
	v_lshlrev_b32_e32 v76, 16, v22
	v_and_b32_e32 v77, 0xffff0000, v22
	v_and_b32_e32 v252, 0xffff0000, v6
	v_lshlrev_b32_e32 v6, 16, v6
	v_fmac_f32_e32 v76, 0x3fb504f3, v6
	v_fmac_f32_e32 v77, 0x3fb504f3, v252
	v_lshlrev_b32_e32 v78, 16, v23
	v_and_b32_e32 v79, 0xffff0000, v23
	v_and_b32_e32 v252, 0xffff0000, v7
	v_lshlrev_b32_e32 v7, 16, v7
	v_fmac_f32_e32 v78, 0x3fb504f3, v7
	v_fmac_f32_e32 v79, 0x3fb504f3, v252
	v_add_f32_e32 v252, v76, v77
	v_add_f32_e32 v253, v78, v79
	v_add_f32_e32 v252, v252, v253
	v_add_f32_e32 v254, v254, v252
	v_lshlrev_b32_e32 v80, 16, v24
	v_and_b32_e32 v81, 0xffff0000, v24
	v_and_b32_e32 v252, 0xffff0000, v8
	v_lshlrev_b32_e32 v8, 16, v8
	v_fmac_f32_e32 v80, 0x3fb504f3, v8
	v_fmac_f32_e32 v81, 0x3fb504f3, v252
	v_lshlrev_b32_e32 v82, 16, v25
	v_and_b32_e32 v83, 0xffff0000, v25
	v_and_b32_e32 v252, 0xffff0000, v9
	v_lshlrev_b32_e32 v9, 16, v9
	v_fmac_f32_e32 v82, 0x3fb504f3, v9
	v_fmac_f32_e32 v83, 0x3fb504f3, v252
	v_add_f32_e32 v252, v80, v81
	v_add_f32_e32 v253, v82, v83
	v_add_f32_e32 v252, v252, v253
	v_add_f32_e32 v254, v254, v252
	v_lshlrev_b32_e32 v84, 16, v26
	v_and_b32_e32 v85, 0xffff0000, v26
	v_and_b32_e32 v252, 0xffff0000, v10
	v_lshlrev_b32_e32 v10, 16, v10
	v_fmac_f32_e32 v84, 0x3fb504f3, v10
	v_fmac_f32_e32 v85, 0x3fb504f3, v252
	v_lshlrev_b32_e32 v86, 16, v27
	v_and_b32_e32 v87, 0xffff0000, v27
	v_and_b32_e32 v252, 0xffff0000, v11
	v_lshlrev_b32_e32 v11, 16, v11
	v_fmac_f32_e32 v86, 0x3fb504f3, v11
	v_fmac_f32_e32 v87, 0x3fb504f3, v252
	v_add_f32_e32 v252, v84, v85
	v_add_f32_e32 v253, v86, v87
	v_add_f32_e32 v252, v252, v253
	v_add_f32_e32 v254, v254, v252
	v_lshlrev_b32_e32 v244, 16, v28
	v_and_b32_e32 v245, 0xffff0000, v28
	v_and_b32_e32 v252, 0xffff0000, v12
	v_lshlrev_b32_e32 v12, 16, v12
	v_fmac_f32_e32 v244, 0x3fb504f3, v12
	v_fmac_f32_e32 v245, 0x3fb504f3, v252
	v_lshlrev_b32_e32 v246, 16, v29
	v_and_b32_e32 v247, 0xffff0000, v29
	v_and_b32_e32 v252, 0xffff0000, v13
	v_lshlrev_b32_e32 v13, 16, v13
	v_fmac_f32_e32 v246, 0x3fb504f3, v13
	v_fmac_f32_e32 v247, 0x3fb504f3, v252
	v_add_f32_e32 v252, v244, v245
	v_add_f32_e32 v253, v246, v247
	v_add_f32_e32 v252, v252, v253
	v_add_f32_e32 v254, v254, v252
	v_lshlrev_b32_e32 v248, 16, v30
	v_and_b32_e32 v249, 0xffff0000, v30
	v_and_b32_e32 v252, 0xffff0000, v14
	v_lshlrev_b32_e32 v14, 16, v14
	v_fmac_f32_e32 v248, 0x3fb504f3, v14
	v_fmac_f32_e32 v249, 0x3fb504f3, v252
	v_lshlrev_b32_e32 v250, 16, v31
	v_and_b32_e32 v251, 0xffff0000, v31
	v_and_b32_e32 v252, 0xffff0000, v15
	v_lshlrev_b32_e32 v15, 16, v15
	v_fmac_f32_e32 v250, 0x3fb504f3, v15
	v_fmac_f32_e32 v251, 0x3fb504f3, v252
	v_add_f32_e32 v252, v248, v249
	v_add_f32_e32 v253, v250, v251
	v_add_f32_e32 v252, v252, v253
	v_add_f32_e32 v254, v254, v252
	s_add_u32 s12, s4, 0x1000000
	s_addc_u32 s13, s5, 0
	global_load_dwordx4 v[0:3], v90, s[12:13]
	global_load_dwordx4 v[4:7], v90, s[12:13] offset:1024
	global_load_dwordx4 v[8:11], v90, s[12:13] offset:2048
	global_load_dwordx4 v[12:15], v90, s[12:13] offset:3072
	s_add_u32 s12, s6, 0x1000000
	s_addc_u32 s13, s7, 0
	global_load_dwordx4 v[16:19], v90, s[12:13]
	global_load_dwordx4 v[20:23], v90, s[12:13] offset:1024
	global_load_dwordx4 v[24:27], v90, s[12:13] offset:2048
	global_load_dwordx4 v[28:31], v90, s[12:13] offset:3072
	s_nop 1
	v_add_f32_dpp v252, v254, v254 quad_perm:[1,0,3,2] row_mask:0xf bank_mask:0xf
	s_nop 1
	v_add_f32_dpp v252, v252, v252 quad_perm:[2,3,0,1] row_mask:0xf bank_mask:0xf
	s_nop 1
	v_add_f32_dpp v252, v252, v252 row_half_mirror row_mask:0xf bank_mask:0xf
	s_nop 1
	v_add_f32_dpp v252, v252, v252 row_mirror row_mask:0xf bank_mask:0xf
	s_nop 1
	v_readlane_b32 s86, v252, 0
	v_readlane_b32 s87, v252, 16
	v_readlane_b32 s88, v252, 32
	v_readlane_b32 s89, v252, 48
	s_nop 1
	v_mov_b32_e32 v253, s86
	v_add_f32_e32 v253, s87, v253
	v_add_f32_e32 v253, s88, v253
	v_add_f32_e32 v253, s89, v253
	v_mul_f32_e32 v253, 0x3a000000, v253
	s_nop 0
	v_readfirstlane_b32 s85, v253
	s_nop 1
	v_subrev_f32_e32 v64, s85, v64
	v_subrev_f32_e32 v65, s85, v65
	v_subrev_f32_e32 v66, s85, v66
	v_subrev_f32_e32 v67, s85, v67
	v_subrev_f32_e32 v68, s85, v68
	v_subrev_f32_e32 v69, s85, v69
	v_subrev_f32_e32 v70, s85, v70
	v_subrev_f32_e32 v71, s85, v71
	v_mul_f32_e32 v252, v64, v64
	v_fmac_f32_e32 v252, v65, v65
	v_mul_f32_e32 v253, v66, v66
	v_fmac_f32_e32 v253, v67, v67
	v_add_f32_e32 v254, v252, v253
	v_mul_f32_e32 v252, v68, v68
	v_fmac_f32_e32 v252, v69, v69
	v_mul_f32_e32 v253, v70, v70
	v_fmac_f32_e32 v253, v71, v71
	v_add_f32_e32 v252, v252, v253
	v_add_f32_e32 v254, v254, v252
	v_subrev_f32_e32 v72, s85, v72
	v_subrev_f32_e32 v73, s85, v73
	v_subrev_f32_e32 v74, s85, v74
	v_subrev_f32_e32 v75, s85, v75
	v_subrev_f32_e32 v76, s85, v76
	v_subrev_f32_e32 v77, s85, v77
	v_subrev_f32_e32 v78, s85, v78
	v_subrev_f32_e32 v79, s85, v79
	v_mul_f32_e32 v252, v72, v72
	v_fmac_f32_e32 v252, v73, v73
	v_mul_f32_e32 v253, v74, v74
	v_fmac_f32_e32 v253, v75, v75
	v_add_f32_e32 v252, v252, v253
	v_add_f32_e32 v254, v254, v252
	v_mul_f32_e32 v252, v76, v76
	v_fmac_f32_e32 v252, v77, v77
	v_mul_f32_e32 v253, v78, v78
	v_fmac_f32_e32 v253, v79, v79
	v_add_f32_e32 v252, v252, v253
	v_add_f32_e32 v254, v254, v252
	v_subrev_f32_e32 v80, s85, v80
	v_subrev_f32_e32 v81, s85, v81
	v_subrev_f32_e32 v82, s85, v82
	v_subrev_f32_e32 v83, s85, v83
	v_subrev_f32_e32 v84, s85, v84
	v_subrev_f32_e32 v85, s85, v85
	v_subrev_f32_e32 v86, s85, v86
	v_subrev_f32_e32 v87, s85, v87
	v_mul_f32_e32 v252, v80, v80
	v_fmac_f32_e32 v252, v81, v81
	v_mul_f32_e32 v253, v82, v82
	v_fmac_f32_e32 v253, v83, v83
	v_add_f32_e32 v252, v252, v253
	v_add_f32_e32 v254, v254, v252
	v_mul_f32_e32 v252, v84, v84
	v_fmac_f32_e32 v252, v85, v85
	v_mul_f32_e32 v253, v86, v86
	v_fmac_f32_e32 v253, v87, v87
	v_add_f32_e32 v252, v252, v253
	v_add_f32_e32 v254, v254, v252
	v_subrev_f32_e32 v244, s85, v244
	v_subrev_f32_e32 v245, s85, v245
	v_subrev_f32_e32 v246, s85, v246
	v_subrev_f32_e32 v247, s85, v247
	v_subrev_f32_e32 v248, s85, v248
	v_subrev_f32_e32 v249, s85, v249
	v_subrev_f32_e32 v250, s85, v250
	v_subrev_f32_e32 v251, s85, v251
	v_mul_f32_e32 v252, v244, v244
	v_fmac_f32_e32 v252, v245, v245
	v_mul_f32_e32 v253, v246, v246
	v_fmac_f32_e32 v253, v247, v247
	v_add_f32_e32 v252, v252, v253
	v_add_f32_e32 v254, v254, v252
	v_mul_f32_e32 v252, v248, v248
	v_fmac_f32_e32 v252, v249, v249
	v_mul_f32_e32 v253, v250, v250
	v_fmac_f32_e32 v253, v251, v251
	v_add_f32_e32 v252, v252, v253
	v_add_f32_e32 v254, v254, v252
	s_nop 1
	v_add_f32_dpp v252, v254, v254 quad_perm:[1,0,3,2] row_mask:0xf bank_mask:0xf
	s_nop 1
	v_add_f32_dpp v252, v252, v252 quad_perm:[2,3,0,1] row_mask:0xf bank_mask:0xf
	s_nop 1
	v_add_f32_dpp v252, v252, v252 row_half_mirror row_mask:0xf bank_mask:0xf
	s_nop 1
	v_add_f32_dpp v252, v252, v252 row_mirror row_mask:0xf bank_mask:0xf
	s_nop 1
	v_readlane_b32 s86, v252, 0
	v_readlane_b32 s87, v252, 16
	v_readlane_b32 s88, v252, 32
	v_readlane_b32 s89, v252, 48
	s_nop 1
	v_mov_b32_e32 v253, s86
	v_add_f32_e32 v253, s87, v253
	v_add_f32_e32 v253, s88, v253
	v_add_f32_e32 v253, s89, v253
	v_mov_b32_e32 v252, 0x3a000000
	v_fmaak_f32 v253, v253, v252, 0x3727c5ac
	v_rsq_f32_e32 v253, v253
	s_nop 1
	v_readfirstlane_b32 s85, v253
	s_mov_b32 s12, s4
	s_mov_b32 s13, s5
	v_readlane_b32 s86, v241, 7
	v_readlane_b32 s87, v241, 8
	s_add_u32 s86, s86, 0x0
	s_addc_u32 s87, s87, 0
	s_add_u32 s88, s86, 0x1000
	s_addc_u32 s89, s87, 0
	ds_read_b64 v[252:253], v168
	ds_read_b64 v[254:255], v168 offset:8192
	ds_read_b64 v[88:89], v168 offset:512
	ds_read_b64 v[242:243], v168 offset:8704
	s_waitcnt lgkmcnt(2)
	v_mul_f32_e32 v64, s85, v64
	v_mul_f32_e32 v65, s85, v65
	v_fma_f32 v64, v64, v252, v254
	v_fma_f32 v65, v65, v253, v255
	ds_read_b64 v[252:253], v168 offset:1024
	ds_read_b64 v[254:255], v168 offset:9216
	s_waitcnt lgkmcnt(2)
	v_mul_f32_e32 v66, s85, v66
	v_mul_f32_e32 v67, s85, v67
	v_fma_f32 v66, v66, v88, v242
	v_fma_f32 v67, v67, v89, v243
	ds_read_b64 v[88:89], v168 offset:1536
	ds_read_b64 v[242:243], v168 offset:9728
	s_waitcnt lgkmcnt(2)
	v_mul_f32_e32 v68, s85, v68
	v_mul_f32_e32 v69, s85, v69
	v_fma_f32 v68, v68, v252, v254
	v_fma_f32 v69, v69, v253, v255
	ds_read_b64 v[252:253], v168 offset:2048
	ds_read_b64 v[254:255], v168 offset:10240
	s_waitcnt lgkmcnt(2)
	v_mul_f32_e32 v70, s85, v70
	v_mul_f32_e32 v71, s85, v71
	v_fma_f32 v70, v70, v88, v242
	v_fma_f32 v71, v71, v89, v243
	s_cmp_lg_u32 s90, 0
	s_cbranch_scc1 .Lln2_f32_1
	v_cvt_pk_bf16_f32 v64, v64, v65
	v_cvt_pk_bf16_f32 v65, v66, v67
	v_cvt_pk_bf16_f32 v66, v68, v69
	v_cvt_pk_bf16_f32 v67, v70, v71
	global_store_dwordx4 v90, v[64:67], s[12:13]
	s_branch .Lln2_st_2
.Lln2_f32_1:
	v_lshlrev_b32_e32 v88, 1, v90
	global_store_dwordx4 v88, v[64:67], s[86:87]
	global_store_dwordx4 v88, v[68:71], s[86:87] offset:16
.Lln2_st_2:
	ds_read_b64 v[88:89], v168 offset:2560
	ds_read_b64 v[242:243], v168 offset:10752
	s_waitcnt lgkmcnt(2)
	v_mul_f32_e32 v72, s85, v72
	v_mul_f32_e32 v73, s85, v73
	v_fma_f32 v72, v72, v252, v254
	v_fma_f32 v73, v73, v253, v255
	ds_read_b64 v[252:253], v168 offset:3072
	ds_read_b64 v[254:255], v168 offset:11264
	s_waitcnt lgkmcnt(2)
	v_mul_f32_e32 v74, s85, v74
	v_mul_f32_e32 v75, s85, v75
	v_fma_f32 v74, v74, v88, v242
	v_fma_f32 v75, v75, v89, v243
	ds_read_b64 v[88:89], v168 offset:3584
	ds_read_b64 v[242:243], v168 offset:11776
	s_waitcnt lgkmcnt(2)
	v_mul_f32_e32 v76, s85, v76
	v_mul_f32_e32 v77, s85, v77
	v_fma_f32 v76, v76, v252, v254
	v_fma_f32 v77, v77, v253, v255
	ds_read_b64 v[252:253], v168 offset:4096
	ds_read_b64 v[254:255], v168 offset:12288
	s_waitcnt lgkmcnt(2)
	v_mul_f32_e32 v78, s85, v78
	v_mul_f32_e32 v79, s85, v79
	v_fma_f32 v78, v78, v88, v242
	v_fma_f32 v79, v79, v89, v243
	s_cmp_lg_u32 s90, 0
	s_cbranch_scc1 .Lln2_f32_3
	v_cvt_pk_bf16_f32 v72, v72, v73
	v_cvt_pk_bf16_f32 v73, v74, v75
	v_cvt_pk_bf16_f32 v74, v76, v77
	v_cvt_pk_bf16_f32 v75, v78, v79
	global_store_dwordx4 v90, v[72:75], s[12:13] offset:1024
	s_branch .Lln2_st_4
.Lln2_f32_3:
	v_lshlrev_b32_e32 v88, 1, v90
	global_store_dwordx4 v88, v[72:75], s[86:87] offset:2048
	global_store_dwordx4 v88, v[76:79], s[86:87] offset:2064
.Lln2_st_4:
	ds_read_b64 v[88:89], v168 offset:4608
	ds_read_b64 v[242:243], v168 offset:12800
	s_waitcnt lgkmcnt(2)
	v_mul_f32_e32 v80, s85, v80
	v_mul_f32_e32 v81, s85, v81
	v_fma_f32 v80, v80, v252, v254
	v_fma_f32 v81, v81, v253, v255
	ds_read_b64 v[252:253], v168 offset:5120
	ds_read_b64 v[254:255], v168 offset:13312
	s_waitcnt lgkmcnt(2)
	v_mul_f32_e32 v82, s85, v82
	v_mul_f32_e32 v83, s85, v83
	v_fma_f32 v82, v82, v88, v242
	v_fma_f32 v83, v83, v89, v243
	ds_read_b64 v[88:89], v168 offset:5632
	ds_read_b64 v[242:243], v168 offset:13824
	s_waitcnt lgkmcnt(2)
	v_mul_f32_e32 v84, s85, v84
	v_mul_f32_e32 v85, s85, v85
	v_fma_f32 v84, v84, v252, v254
	v_fma_f32 v85, v85, v253, v255
	ds_read_b64 v[252:253], v168 offset:6144
	ds_read_b64 v[254:255], v168 offset:14336
	s_waitcnt lgkmcnt(2)
	v_mul_f32_e32 v86, s85, v86
	v_mul_f32_e32 v87, s85, v87
	v_fma_f32 v86, v86, v88, v242
	v_fma_f32 v87, v87, v89, v243
	s_cmp_lg_u32 s90, 0
	s_cbranch_scc1 .Lln2_f32_5
	v_cvt_pk_bf16_f32 v80, v80, v81
	v_cvt_pk_bf16_f32 v81, v82, v83
	v_cvt_pk_bf16_f32 v82, v84, v85
	v_cvt_pk_bf16_f32 v83, v86, v87
	global_store_dwordx4 v90, v[80:83], s[12:13] offset:2048
	s_branch .Lln2_st_6
.Lln2_f32_5:
	v_lshlrev_b32_e32 v88, 1, v90
	global_store_dwordx4 v88, v[80:83], s[88:89]
	global_store_dwordx4 v88, v[84:87], s[88:89] offset:16
.Lln2_st_6:
	ds_read_b64 v[88:89], v168 offset:6656
	ds_read_b64 v[242:243], v168 offset:14848
	s_waitcnt lgkmcnt(2)
	v_mul_f32_e32 v244, s85, v244
	v_mul_f32_e32 v245, s85, v245
	v_fma_f32 v244, v244, v252, v254
	v_fma_f32 v245, v245, v253, v255
	ds_read_b64 v[252:253], v168 offset:7168
	ds_read_b64 v[254:255], v168 offset:15360
	s_waitcnt lgkmcnt(2)
	v_mul_f32_e32 v246, s85, v246
	v_mul_f32_e32 v247, s85, v247
	v_fma_f32 v246, v246, v88, v242
	v_fma_f32 v247, v247, v89, v243
	ds_read_b64 v[88:89], v168 offset:7680
	ds_read_b64 v[242:243], v168 offset:15872
	s_waitcnt lgkmcnt(2)
	v_mul_f32_e32 v248, s85, v248
	v_mul_f32_e32 v249, s85, v249
	v_fma_f32 v248, v248, v252, v254
	v_fma_f32 v249, v249, v253, v255
	s_waitcnt lgkmcnt(0)
	v_mul_f32_e32 v250, s85, v250
	v_mul_f32_e32 v251, s85, v251
	v_fma_f32 v250, v250, v88, v242
	v_fma_f32 v251, v251, v89, v243
	s_cmp_lg_u32 s90, 0
	s_cbranch_scc1 .Lln2_f32_7
	v_cvt_pk_bf16_f32 v244, v244, v245
	v_cvt_pk_bf16_f32 v245, v246, v247
	v_cvt_pk_bf16_f32 v246, v248, v249
	v_cvt_pk_bf16_f32 v247, v250, v251
	global_store_dwordx4 v90, v[244:247], s[12:13] offset:3072
	s_branch .Lln2_st_8
.Lln2_f32_7:
	v_lshlrev_b32_e32 v88, 1, v90
	global_store_dwordx4 v88, v[244:247], s[88:89] offset:2048
	global_store_dwordx4 v88, v[248:251], s[88:89] offset:2064
.Lln2_st_8:
	s_waitcnt vmcnt(12)
	v_lshlrev_b32_e32 v64, 16, v48
	v_and_b32_e32 v65, 0xffff0000, v48
	v_and_b32_e32 v252, 0xffff0000, v32
	v_lshlrev_b32_e32 v32, 16, v32
	v_fmac_f32_e32 v64, 0x3fb504f3, v32
	v_fmac_f32_e32 v65, 0x3fb504f3, v252
	v_lshlrev_b32_e32 v66, 16, v49
	v_and_b32_e32 v67, 0xffff0000, v49
	v_and_b32_e32 v252, 0xffff0000, v33
	v_lshlrev_b32_e32 v33, 16, v33
	v_fmac_f32_e32 v66, 0x3fb504f3, v33
	v_fmac_f32_e32 v67, 0x3fb504f3, v252
	v_add_f32_e32 v252, v64, v65
	v_add_f32_e32 v253, v66, v67
	v_add_f32_e32 v254, v252, v253
	v_lshlrev_b32_e32 v68, 16, v50
	v_and_b32_e32 v69, 0xffff0000, v50
	v_and_b32_e32 v252, 0xffff0000, v34
	v_lshlrev_b32_e32 v34, 16, v34
	v_fmac_f32_e32 v68, 0x3fb504f3, v34
	v_fmac_f32_e32 v69, 0x3fb504f3, v252
	v_lshlrev_b32_e32 v70, 16, v51
	v_and_b32_e32 v71, 0xffff0000, v51
	v_and_b32_e32 v252, 0xffff0000, v35
	v_lshlrev_b32_e32 v35, 16, v35
	v_fmac_f32_e32 v70, 0x3fb504f3, v35
	v_fmac_f32_e32 v71, 0x3fb504f3, v252
	v_add_f32_e32 v252, v68, v69
	v_add_f32_e32 v253, v70, v71
	v_add_f32_e32 v252, v252, v253
	v_add_f32_e32 v254, v254, v252
	v_lshlrev_b32_e32 v72, 16, v52
	v_and_b32_e32 v73, 0xffff0000, v52
	v_and_b32_e32 v252, 0xffff0000, v36
	v_lshlrev_b32_e32 v36, 16, v36
	v_fmac_f32_e32 v72, 0x3fb504f3, v36
	v_fmac_f32_e32 v73, 0x3fb504f3, v252
	v_lshlrev_b32_e32 v74, 16, v53
	v_and_b32_e32 v75, 0xffff0000, v53
	v_and_b32_e32 v252, 0xffff0000, v37
	v_lshlrev_b32_e32 v37, 16, v37
	v_fmac_f32_e32 v74, 0x3fb504f3, v37
	v_fmac_f32_e32 v75, 0x3fb504f3, v252
	v_add_f32_e32 v252, v72, v73
	v_add_f32_e32 v253, v74, v75
	v_add_f32_e32 v252, v252, v253
	v_add_f32_e32 v254, v254, v252
	v_lshlrev_b32_e32 v76, 16, v54
	v_and_b32_e32 v77, 0xffff0000, v54
	v_and_b32_e32 v252, 0xffff0000, v38
	v_lshlrev_b32_e32 v38, 16, v38
	v_fmac_f32_e32 v76, 0x3fb504f3, v38
	v_fmac_f32_e32 v77, 0x3fb504f3, v252
	v_lshlrev_b32_e32 v78, 16, v55
	v_and_b32_e32 v79, 0xffff0000, v55
	v_and_b32_e32 v252, 0xffff0000, v39
	v_lshlrev_b32_e32 v39, 16, v39
	v_fmac_f32_e32 v78, 0x3fb504f3, v39
	v_fmac_f32_e32 v79, 0x3fb504f3, v252
	v_add_f32_e32 v252, v76, v77
	v_add_f32_e32 v253, v78, v79
	v_add_f32_e32 v252, v252, v253
	v_add_f32_e32 v254, v254, v252
	v_lshlrev_b32_e32 v80, 16, v56
	v_and_b32_e32 v81, 0xffff0000, v56
	v_and_b32_e32 v252, 0xffff0000, v40
	v_lshlrev_b32_e32 v40, 16, v40
	v_fmac_f32_e32 v80, 0x3fb504f3, v40
	v_fmac_f32_e32 v81, 0x3fb504f3, v252
	v_lshlrev_b32_e32 v82, 16, v57
	v_and_b32_e32 v83, 0xffff0000, v57
	v_and_b32_e32 v252, 0xffff0000, v41
	v_lshlrev_b32_e32 v41, 16, v41
	v_fmac_f32_e32 v82, 0x3fb504f3, v41
	v_fmac_f32_e32 v83, 0x3fb504f3, v252
	v_add_f32_e32 v252, v80, v81
	v_add_f32_e32 v253, v82, v83
	v_add_f32_e32 v252, v252, v253
	v_add_f32_e32 v254, v254, v252
	v_lshlrev_b32_e32 v84, 16, v58
	v_and_b32_e32 v85, 0xffff0000, v58
	v_and_b32_e32 v252, 0xffff0000, v42
	v_lshlrev_b32_e32 v42, 16, v42
	v_fmac_f32_e32 v84, 0x3fb504f3, v42
	v_fmac_f32_e32 v85, 0x3fb504f3, v252
	v_lshlrev_b32_e32 v86, 16, v59
	v_and_b32_e32 v87, 0xffff0000, v59
	v_and_b32_e32 v252, 0xffff0000, v43
	v_lshlrev_b32_e32 v43, 16, v43
	v_fmac_f32_e32 v86, 0x3fb504f3, v43
	v_fmac_f32_e32 v87, 0x3fb504f3, v252
	v_add_f32_e32 v252, v84, v85
	v_add_f32_e32 v253, v86, v87
	v_add_f32_e32 v252, v252, v253
	v_add_f32_e32 v254, v254, v252
	v_lshlrev_b32_e32 v244, 16, v60
	v_and_b32_e32 v245, 0xffff0000, v60
	v_and_b32_e32 v252, 0xffff0000, v44
	v_lshlrev_b32_e32 v44, 16, v44
	v_fmac_f32_e32 v244, 0x3fb504f3, v44
	v_fmac_f32_e32 v245, 0x3fb504f3, v252
	v_lshlrev_b32_e32 v246, 16, v61
	v_and_b32_e32 v247, 0xffff0000, v61
	v_and_b32_e32 v252, 0xffff0000, v45
	v_lshlrev_b32_e32 v45, 16, v45
	v_fmac_f32_e32 v246, 0x3fb504f3, v45
	v_fmac_f32_e32 v247, 0x3fb504f3, v252
	v_add_f32_e32 v252, v244, v245
	v_add_f32_e32 v253, v246, v247
	v_add_f32_e32 v252, v252, v253
	v_add_f32_e32 v254, v254, v252
	v_lshlrev_b32_e32 v248, 16, v62
	v_and_b32_e32 v249, 0xffff0000, v62
	v_and_b32_e32 v252, 0xffff0000, v46
	v_lshlrev_b32_e32 v46, 16, v46
	v_fmac_f32_e32 v248, 0x3fb504f3, v46
	v_fmac_f32_e32 v249, 0x3fb504f3, v252
	v_lshlrev_b32_e32 v250, 16, v63
	v_and_b32_e32 v251, 0xffff0000, v63
	v_and_b32_e32 v252, 0xffff0000, v47
	v_lshlrev_b32_e32 v47, 16, v47
	v_fmac_f32_e32 v250, 0x3fb504f3, v47
	v_fmac_f32_e32 v251, 0x3fb504f3, v252
	v_add_f32_e32 v252, v248, v249
	v_add_f32_e32 v253, v250, v251
	v_add_f32_e32 v252, v252, v253
	v_add_f32_e32 v254, v254, v252
	s_add_u32 s12, s4, 0x1800000
	s_addc_u32 s13, s5, 0
	global_load_dwordx4 v[32:35], v90, s[12:13]
	global_load_dwordx4 v[36:39], v90, s[12:13] offset:1024
	global_load_dwordx4 v[40:43], v90, s[12:13] offset:2048
	global_load_dwordx4 v[44:47], v90, s[12:13] offset:3072
	s_add_u32 s12, s6, 0x1800000
	s_addc_u32 s13, s7, 0
	global_load_dwordx4 v[48:51], v90, s[12:13]
	global_load_dwordx4 v[52:55], v90, s[12:13] offset:1024
	global_load_dwordx4 v[56:59], v90, s[12:13] offset:2048
	global_load_dwordx4 v[60:63], v90, s[12:13] offset:3072
	s_nop 1
	v_add_f32_dpp v252, v254, v254 quad_perm:[1,0,3,2] row_mask:0xf bank_mask:0xf
	s_nop 1
	v_add_f32_dpp v252, v252, v252 quad_perm:[2,3,0,1] row_mask:0xf bank_mask:0xf
	s_nop 1
	v_add_f32_dpp v252, v252, v252 row_half_mirror row_mask:0xf bank_mask:0xf
	s_nop 1
	v_add_f32_dpp v252, v252, v252 row_mirror row_mask:0xf bank_mask:0xf
	s_nop 1
	v_readlane_b32 s86, v252, 0
	v_readlane_b32 s87, v252, 16
	v_readlane_b32 s88, v252, 32
	v_readlane_b32 s89, v252, 48
	s_nop 1
	v_mov_b32_e32 v253, s86
	v_add_f32_e32 v253, s87, v253
	v_add_f32_e32 v253, s88, v253
	v_add_f32_e32 v253, s89, v253
	v_mul_f32_e32 v253, 0x3a000000, v253
	s_nop 0
	v_readfirstlane_b32 s85, v253
	s_nop 1
	v_subrev_f32_e32 v64, s85, v64
	v_subrev_f32_e32 v65, s85, v65
	v_subrev_f32_e32 v66, s85, v66
	v_subrev_f32_e32 v67, s85, v67
	v_subrev_f32_e32 v68, s85, v68
	v_subrev_f32_e32 v69, s85, v69
	v_subrev_f32_e32 v70, s85, v70
	v_subrev_f32_e32 v71, s85, v71
	v_mul_f32_e32 v252, v64, v64
	v_fmac_f32_e32 v252, v65, v65
	v_mul_f32_e32 v253, v66, v66
	v_fmac_f32_e32 v253, v67, v67
	v_add_f32_e32 v254, v252, v253
	v_mul_f32_e32 v252, v68, v68
	v_fmac_f32_e32 v252, v69, v69
	v_mul_f32_e32 v253, v70, v70
	v_fmac_f32_e32 v253, v71, v71
	v_add_f32_e32 v252, v252, v253
	v_add_f32_e32 v254, v254, v252
	v_subrev_f32_e32 v72, s85, v72
	v_subrev_f32_e32 v73, s85, v73
	v_subrev_f32_e32 v74, s85, v74
	v_subrev_f32_e32 v75, s85, v75
	v_subrev_f32_e32 v76, s85, v76
	v_subrev_f32_e32 v77, s85, v77
	v_subrev_f32_e32 v78, s85, v78
	v_subrev_f32_e32 v79, s85, v79
	v_mul_f32_e32 v252, v72, v72
	v_fmac_f32_e32 v252, v73, v73
	v_mul_f32_e32 v253, v74, v74
	v_fmac_f32_e32 v253, v75, v75
	v_add_f32_e32 v252, v252, v253
	v_add_f32_e32 v254, v254, v252
	v_mul_f32_e32 v252, v76, v76
	v_fmac_f32_e32 v252, v77, v77
	v_mul_f32_e32 v253, v78, v78
	v_fmac_f32_e32 v253, v79, v79
	v_add_f32_e32 v252, v252, v253
	v_add_f32_e32 v254, v254, v252
	v_subrev_f32_e32 v80, s85, v80
	v_subrev_f32_e32 v81, s85, v81
	v_subrev_f32_e32 v82, s85, v82
	v_subrev_f32_e32 v83, s85, v83
	v_subrev_f32_e32 v84, s85, v84
	v_subrev_f32_e32 v85, s85, v85
	v_subrev_f32_e32 v86, s85, v86
	v_subrev_f32_e32 v87, s85, v87
	v_mul_f32_e32 v252, v80, v80
	v_fmac_f32_e32 v252, v81, v81
	v_mul_f32_e32 v253, v82, v82
	v_fmac_f32_e32 v253, v83, v83
	v_add_f32_e32 v252, v252, v253
	v_add_f32_e32 v254, v254, v252
	v_mul_f32_e32 v252, v84, v84
	v_fmac_f32_e32 v252, v85, v85
	v_mul_f32_e32 v253, v86, v86
	v_fmac_f32_e32 v253, v87, v87
	v_add_f32_e32 v252, v252, v253
	v_add_f32_e32 v254, v254, v252
	v_subrev_f32_e32 v244, s85, v244
	v_subrev_f32_e32 v245, s85, v245
	v_subrev_f32_e32 v246, s85, v246
	v_subrev_f32_e32 v247, s85, v247
	v_subrev_f32_e32 v248, s85, v248
	v_subrev_f32_e32 v249, s85, v249
	v_subrev_f32_e32 v250, s85, v250
	v_subrev_f32_e32 v251, s85, v251
	v_mul_f32_e32 v252, v244, v244
	v_fmac_f32_e32 v252, v245, v245
	v_mul_f32_e32 v253, v246, v246
	v_fmac_f32_e32 v253, v247, v247
	v_add_f32_e32 v252, v252, v253
	v_add_f32_e32 v254, v254, v252
	v_mul_f32_e32 v252, v248, v248
	v_fmac_f32_e32 v252, v249, v249
	v_mul_f32_e32 v253, v250, v250
	v_fmac_f32_e32 v253, v251, v251
	v_add_f32_e32 v252, v252, v253
	v_add_f32_e32 v254, v254, v252
	s_nop 1
	v_add_f32_dpp v252, v254, v254 quad_perm:[1,0,3,2] row_mask:0xf bank_mask:0xf
	s_nop 1
	v_add_f32_dpp v252, v252, v252 quad_perm:[2,3,0,1] row_mask:0xf bank_mask:0xf
	s_nop 1
	v_add_f32_dpp v252, v252, v252 row_half_mirror row_mask:0xf bank_mask:0xf
	s_nop 1
	v_add_f32_dpp v252, v252, v252 row_mirror row_mask:0xf bank_mask:0xf
	s_nop 1
	v_readlane_b32 s86, v252, 0
	v_readlane_b32 s87, v252, 16
	v_readlane_b32 s88, v252, 32
	v_readlane_b32 s89, v252, 48
	s_nop 1
	v_mov_b32_e32 v253, s86
	v_add_f32_e32 v253, s87, v253
	v_add_f32_e32 v253, s88, v253
	v_add_f32_e32 v253, s89, v253
	v_mov_b32_e32 v252, 0x3a000000
	v_fmaak_f32 v253, v253, v252, 0x3727c5ac
	v_rsq_f32_e32 v253, v253
	s_nop 1
	v_readfirstlane_b32 s85, v253
	s_add_u32 s12, s4, 0x800000
	s_addc_u32 s13, s5, 0
	v_readlane_b32 s86, v241, 7
	v_readlane_b32 s87, v241, 8
	s_add_u32 s86, s86, 0x1000000
	s_addc_u32 s87, s87, 0
	s_add_u32 s88, s86, 0x1000
	s_addc_u32 s89, s87, 0
	ds_read_b64 v[252:253], v168
	ds_read_b64 v[254:255], v168 offset:8192
	ds_read_b64 v[88:89], v168 offset:512
	ds_read_b64 v[242:243], v168 offset:8704
	s_waitcnt lgkmcnt(2)
	v_mul_f32_e32 v64, s85, v64
	v_mul_f32_e32 v65, s85, v65
	v_fma_f32 v64, v64, v252, v254
	v_fma_f32 v65, v65, v253, v255
	ds_read_b64 v[252:253], v168 offset:1024
	ds_read_b64 v[254:255], v168 offset:9216
	s_waitcnt lgkmcnt(2)
	v_mul_f32_e32 v66, s85, v66
	v_mul_f32_e32 v67, s85, v67
	v_fma_f32 v66, v66, v88, v242
	v_fma_f32 v67, v67, v89, v243
	ds_read_b64 v[88:89], v168 offset:1536
	ds_read_b64 v[242:243], v168 offset:9728
	s_waitcnt lgkmcnt(2)
	v_mul_f32_e32 v68, s85, v68
	v_mul_f32_e32 v69, s85, v69
	v_fma_f32 v68, v68, v252, v254
	v_fma_f32 v69, v69, v253, v255
	ds_read_b64 v[252:253], v168 offset:2048
	ds_read_b64 v[254:255], v168 offset:10240
	s_waitcnt lgkmcnt(2)
	v_mul_f32_e32 v70, s85, v70
	v_mul_f32_e32 v71, s85, v71
	v_fma_f32 v70, v70, v88, v242
	v_fma_f32 v71, v71, v89, v243
	s_cmp_lg_u32 s90, 0
	s_cbranch_scc1 .Lln2_f32_9
	v_cvt_pk_bf16_f32 v64, v64, v65
	v_cvt_pk_bf16_f32 v65, v66, v67
	v_cvt_pk_bf16_f32 v66, v68, v69
	v_cvt_pk_bf16_f32 v67, v70, v71
	global_store_dwordx4 v90, v[64:67], s[12:13]
	s_branch .Lln2_st_10

.Lln2_st_16:
	s_waitcnt vmcnt(16)
	v_lshlrev_b32_e32 v64, 16, v16
	v_and_b32_e32 v65, 0xffff0000, v16
	v_and_b32_e32 v252, 0xffff0000, v0
	v_lshlrev_b32_e32 v0, 16, v0
	v_fmac_f32_e32 v64, 0x3fb504f3, v0
	v_fmac_f32_e32 v65, 0x3fb504f3, v252
	v_lshlrev_b32_e32 v66, 16, v17
	v_and_b32_e32 v67, 0xffff0000, v17
	v_and_b32_e32 v252, 0xffff0000, v1
	v_lshlrev_b32_e32 v1, 16, v1
	v_fmac_f32_e32 v66, 0x3fb504f3, v1
	v_fmac_f32_e32 v67, 0x3fb504f3, v252
	v_add_f32_e32 v252, v64, v65
	v_add_f32_e32 v253, v66, v67
	v_add_f32_e32 v254, v252, v253
	v_lshlrev_b32_e32 v68, 16, v18
	v_and_b32_e32 v69, 0xffff0000, v18
	v_and_b32_e32 v252, 0xffff0000, v2
	v_lshlrev_b32_e32 v2, 16, v2
	v_fmac_f32_e32 v68, 0x3fb504f3, v2
	v_fmac_f32_e32 v69, 0x3fb504f3, v252
	v_lshlrev_b32_e32 v70, 16, v19
	v_and_b32_e32 v71, 0xffff0000, v19
	v_and_b32_e32 v252, 0xffff0000, v3
	v_lshlrev_b32_e32 v3, 16, v3
	v_fmac_f32_e32 v70, 0x3fb504f3, v3
	v_fmac_f32_e32 v71, 0x3fb504f3, v252
	v_add_f32_e32 v252, v68, v69
	v_add_f32_e32 v253, v70, v71
	v_add_f32_e32 v252, v252, v253
	v_add_f32_e32 v254, v254, v252
	v_lshlrev_b32_e32 v72, 16, v20
	v_and_b32_e32 v73, 0xffff0000, v20
	v_and_b32_e32 v252, 0xffff0000, v4
	v_lshlrev_b32_e32 v4, 16, v4
	v_fmac_f32_e32 v72, 0x3fb504f3, v4
	v_fmac_f32_e32 v73, 0x3fb504f3, v252
	v_lshlrev_b32_e32 v74, 16, v21
	v_and_b32_e32 v75, 0xffff0000, v21
	v_and_b32_e32 v252, 0xffff0000, v5
	v_lshlrev_b32_e32 v5, 16, v5
	v_fmac_f32_e32 v74, 0x3fb504f3, v5
	v_fmac_f32_e32 v75, 0x3fb504f3, v252
	v_add_f32_e32 v252, v72, v73
	v_add_f32_e32 v253, v74, v75
	v_add_f32_e32 v252, v252, v253
	v_add_f32_e32 v254, v254, v252
	v_lshlrev_b32_e32 v76, 16, v22
	v_and_b32_e32 v77, 0xffff0000, v22
	v_and_b32_e32 v252, 0xffff0000, v6
	v_lshlrev_b32_e32 v6, 16, v6
	v_fmac_f32_e32 v76, 0x3fb504f3, v6
	v_fmac_f32_e32 v77, 0x3fb504f3, v252
	v_lshlrev_b32_e32 v78, 16, v23
	v_and_b32_e32 v79, 0xffff0000, v23
	v_and_b32_e32 v252, 0xffff0000, v7
	v_lshlrev_b32_e32 v7, 16, v7
	v_fmac_f32_e32 v78, 0x3fb504f3, v7
	v_fmac_f32_e32 v79, 0x3fb504f3, v252
	v_add_f32_e32 v252, v76, v77
	v_add_f32_e32 v253, v78, v79
	v_add_f32_e32 v252, v252, v253
	v_add_f32_e32 v254, v254, v252
	v_lshlrev_b32_e32 v80, 16, v24
	v_and_b32_e32 v81, 0xffff0000, v24
	v_and_b32_e32 v252, 0xffff0000, v8
	v_lshlrev_b32_e32 v8, 16, v8
	v_fmac_f32_e32 v80, 0x3fb504f3, v8
	v_fmac_f32_e32 v81, 0x3fb504f3, v252
	v_lshlrev_b32_e32 v82, 16, v25
	v_and_b32_e32 v83, 0xffff0000, v25
	v_and_b32_e32 v252, 0xffff0000, v9
	v_lshlrev_b32_e32 v9, 16, v9
	v_fmac_f32_e32 v82, 0x3fb504f3, v9
	v_fmac_f32_e32 v83, 0x3fb504f3, v252
	v_add_f32_e32 v252, v80, v81
	v_add_f32_e32 v253, v82, v83
	v_add_f32_e32 v252, v252, v253
	v_add_f32_e32 v254, v254, v252
	v_lshlrev_b32_e32 v84, 16, v26
	v_and_b32_e32 v85, 0xffff0000, v26
	v_and_b32_e32 v252, 0xffff0000, v10
	v_lshlrev_b32_e32 v10, 16, v10
	v_fmac_f32_e32 v84, 0x3fb504f3, v10
	v_fmac_f32_e32 v85, 0x3fb504f3, v252
	v_lshlrev_b32_e32 v86, 16, v27
	v_and_b32_e32 v87, 0xffff0000, v27
	v_and_b32_e32 v252, 0xffff0000, v11
	v_lshlrev_b32_e32 v11, 16, v11
	v_fmac_f32_e32 v86, 0x3fb504f3, v11
	v_fmac_f32_e32 v87, 0x3fb504f3, v252
	v_add_f32_e32 v252, v84, v85
	v_add_f32_e32 v253, v86, v87
	v_add_f32_e32 v252, v252, v253
	v_add_f32_e32 v254, v254, v252
	v_lshlrev_b32_e32 v244, 16, v28
	v_and_b32_e32 v245, 0xffff0000, v28
	v_and_b32_e32 v252, 0xffff0000, v12
	v_lshlrev_b32_e32 v12, 16, v12
	v_fmac_f32_e32 v244, 0x3fb504f3, v12
	v_fmac_f32_e32 v245, 0x3fb504f3, v252
	v_lshlrev_b32_e32 v246, 16, v29
	v_and_b32_e32 v247, 0xffff0000, v29
	v_and_b32_e32 v252, 0xffff0000, v13
	v_lshlrev_b32_e32 v13, 16, v13
	v_fmac_f32_e32 v246, 0x3fb504f3, v13
	v_fmac_f32_e32 v247, 0x3fb504f3, v252
	v_add_f32_e32 v252, v244, v245
	v_add_f32_e32 v253, v246, v247
	v_add_f32_e32 v252, v252, v253
	v_add_f32_e32 v254, v254, v252
	v_lshlrev_b32_e32 v248, 16, v30
	v_and_b32_e32 v249, 0xffff0000, v30
	v_and_b32_e32 v252, 0xffff0000, v14
	v_lshlrev_b32_e32 v14, 16, v14
	v_fmac_f32_e32 v248, 0x3fb504f3, v14
	v_fmac_f32_e32 v249, 0x3fb504f3, v252
	v_lshlrev_b32_e32 v250, 16, v31
	v_and_b32_e32 v251, 0xffff0000, v31
	v_and_b32_e32 v252, 0xffff0000, v15
	v_lshlrev_b32_e32 v15, 16, v15
	v_fmac_f32_e32 v250, 0x3fb504f3, v15
	v_fmac_f32_e32 v251, 0x3fb504f3, v252
	v_add_f32_e32 v252, v248, v249
	v_add_f32_e32 v253, v250, v251
	v_add_f32_e32 v252, v252, v253
	v_add_f32_e32 v254, v254, v252
	s_cmp_lt_u32 s84, 4
	s_cbranch_scc0 .Lln2_nos_17
	v_readlane_b32 s91, v241, 0
	s_lshl_b32 s30, s91, 14
	v_subrev_u32_e32 v88, s30, v90
	s_add_u32 s12, s4, 0x2000000
	s_addc_u32 s13, s5, 0
	global_load_dwordx4 v[0:3], v88, s[12:13]
	global_load_dwordx4 v[4:7], v88, s[12:13] offset:1024
	global_load_dwordx4 v[8:11], v88, s[12:13] offset:2048
	global_load_dwordx4 v[12:15], v88, s[12:13] offset:3072
	global_load_dwordx4 v[16:19], v88, s[8:9]
	global_load_dwordx4 v[20:23], v88, s[8:9] offset:1024
	global_load_dwordx4 v[24:27], v88, s[8:9] offset:2048
	global_load_dwordx4 v[28:31], v88, s[8:9] offset:3072
.Lln2_nos_17:
	s_nop 1
	v_add_f32_dpp v252, v254, v254 quad_perm:[1,0,3,2] row_mask:0xf bank_mask:0xf
	s_nop 1
	v_add_f32_dpp v252, v252, v252 quad_perm:[2,3,0,1] row_mask:0xf bank_mask:0xf
	s_nop 1
	v_add_f32_dpp v252, v252, v252 row_half_mirror row_mask:0xf bank_mask:0xf
	s_nop 1
	v_add_f32_dpp v252, v252, v252 row_mirror row_mask:0xf bank_mask:0xf
	s_nop 1
	v_readlane_b32 s86, v252, 0
	v_readlane_b32 s87, v252, 16
	v_readlane_b32 s88, v252, 32
	v_readlane_b32 s89, v252, 48
	s_nop 1
	v_mov_b32_e32 v253, s86
	v_add_f32_e32 v253, s87, v253
	v_add_f32_e32 v253, s88, v253
	v_add_f32_e32 v253, s89, v253
	v_mul_f32_e32 v253, 0x3a000000, v253
	s_nop 0
	v_readfirstlane_b32 s85, v253
	s_nop 1
	v_subrev_f32_e32 v64, s85, v64
	v_subrev_f32_e32 v65, s85, v65
	v_subrev_f32_e32 v66, s85, v66
	v_subrev_f32_e32 v67, s85, v67
	v_subrev_f32_e32 v68, s85, v68
	v_subrev_f32_e32 v69, s85, v69
	v_subrev_f32_e32 v70, s85, v70
	v_subrev_f32_e32 v71, s85, v71
	v_mul_f32_e32 v252, v64, v64
	v_fmac_f32_e32 v252, v65, v65
	v_mul_f32_e32 v253, v66, v66
	v_fmac_f32_e32 v253, v67, v67
	v_add_f32_e32 v254, v252, v253
	v_mul_f32_e32 v252, v68, v68
	v_fmac_f32_e32 v252, v69, v69
	v_mul_f32_e32 v253, v70, v70
	v_fmac_f32_e32 v253, v71, v71
	v_add_f32_e32 v252, v252, v253
	v_add_f32_e32 v254, v254, v252
	v_subrev_f32_e32 v72, s85, v72
	v_subrev_f32_e32 v73, s85, v73
	v_subrev_f32_e32 v74, s85, v74
	v_subrev_f32_e32 v75, s85, v75
	v_subrev_f32_e32 v76, s85, v76
	v_subrev_f32_e32 v77, s85, v77
	v_subrev_f32_e32 v78, s85, v78
	v_subrev_f32_e32 v79, s85, v79
	v_mul_f32_e32 v252, v72, v72
	v_fmac_f32_e32 v252, v73, v73
	v_mul_f32_e32 v253, v74, v74
	v_fmac_f32_e32 v253, v75, v75
	v_add_f32_e32 v252, v252, v253
	v_add_f32_e32 v254, v254, v252
	v_mul_f32_e32 v252, v76, v76
	v_fmac_f32_e32 v252, v77, v77
	v_mul_f32_e32 v253, v78, v78
	v_fmac_f32_e32 v253, v79, v79
	v_add_f32_e32 v252, v252, v253
	v_add_f32_e32 v254, v254, v252
	v_subrev_f32_e32 v80, s85, v80
	v_subrev_f32_e32 v81, s85, v81
	v_subrev_f32_e32 v82, s85, v82
	v_subrev_f32_e32 v83, s85, v83
	v_subrev_f32_e32 v84, s85, v84
	v_subrev_f32_e32 v85, s85, v85
	v_subrev_f32_e32 v86, s85, v86
	v_subrev_f32_e32 v87, s85, v87
	v_mul_f32_e32 v252, v80, v80
	v_fmac_f32_e32 v252, v81, v81
	v_mul_f32_e32 v253, v82, v82
	v_fmac_f32_e32 v253, v83, v83
	v_add_f32_e32 v252, v252, v253
	v_add_f32_e32 v254, v254, v252
	v_mul_f32_e32 v252, v84, v84
	v_fmac_f32_e32 v252, v85, v85
	v_mul_f32_e32 v253, v86, v86
	v_fmac_f32_e32 v253, v87, v87
	v_add_f32_e32 v252, v252, v253
	v_add_f32_e32 v254, v254, v252
	v_subrev_f32_e32 v244, s85, v244
	v_subrev_f32_e32 v245, s85, v245
	v_subrev_f32_e32 v246, s85, v246
	v_subrev_f32_e32 v247, s85, v247
	v_subrev_f32_e32 v248, s85, v248
	v_subrev_f32_e32 v249, s85, v249
	v_subrev_f32_e32 v250, s85, v250
	v_subrev_f32_e32 v251, s85, v251
	v_mul_f32_e32 v252, v244, v244
	v_fmac_f32_e32 v252, v245, v245
	v_mul_f32_e32 v253, v246, v246
	v_fmac_f32_e32 v253, v247, v247
	v_add_f32_e32 v252, v252, v253
	v_add_f32_e32 v254, v254, v252
	v_mul_f32_e32 v252, v248, v248
	v_fmac_f32_e32 v252, v249, v249
	v_mul_f32_e32 v253, v250, v250
	v_fmac_f32_e32 v253, v251, v251
	v_add_f32_e32 v252, v252, v253
	v_add_f32_e32 v254, v254, v252
	s_nop 1
	v_add_f32_dpp v252, v254, v254 quad_perm:[1,0,3,2] row_mask:0xf bank_mask:0xf
	s_nop 1
	v_add_f32_dpp v252, v252, v252 quad_perm:[2,3,0,1] row_mask:0xf bank_mask:0xf
	s_nop 1
	v_add_f32_dpp v252, v252, v252 row_half_mirror row_mask:0xf bank_mask:0xf
	s_nop 1
	v_add_f32_dpp v252, v252, v252 row_mirror row_mask:0xf bank_mask:0xf
	s_nop 1
	v_readlane_b32 s86, v252, 0
	v_readlane_b32 s87, v252, 16
	v_readlane_b32 s88, v252, 32
	v_readlane_b32 s89, v252, 48
	s_nop 1
	v_mov_b32_e32 v253, s86
	v_add_f32_e32 v253, s87, v253
	v_add_f32_e32 v253, s88, v253
	v_add_f32_e32 v253, s89, v253
	v_mov_b32_e32 v252, 0x3a000000
	v_fmaak_f32 v253, v253, v252, 0x3727c5ac
	v_rsq_f32_e32 v253, v253
	s_nop 1
	v_readfirstlane_b32 s85, v253
	s_add_u32 s12, s4, 0x1000000
	s_addc_u32 s13, s5, 0
	v_readlane_b32 s86, v241, 7
	v_readlane_b32 s87, v241, 8
	s_add_u32 s86, s86, 0x2000000
	s_addc_u32 s87, s87, 0
	s_add_u32 s88, s86, 0x1000
	s_addc_u32 s89, s87, 0
	ds_read_b64 v[252:253], v168
	ds_read_b64 v[254:255], v168 offset:8192
	ds_read_b64 v[88:89], v168 offset:512
	ds_read_b64 v[242:243], v168 offset:8704
	s_waitcnt lgkmcnt(2)
	v_mul_f32_e32 v64, s85, v64
	v_mul_f32_e32 v65, s85, v65
	v_fma_f32 v64, v64, v252, v254
	v_fma_f32 v65, v65, v253, v255
	ds_read_b64 v[252:253], v168 offset:1024
	ds_read_b64 v[254:255], v168 offset:9216
	s_waitcnt lgkmcnt(2)
	v_mul_f32_e32 v66, s85, v66
	v_mul_f32_e32 v67, s85, v67
	v_fma_f32 v66, v66, v88, v242
	v_fma_f32 v67, v67, v89, v243
	ds_read_b64 v[88:89], v168 offset:1536
	ds_read_b64 v[242:243], v168 offset:9728
	s_waitcnt lgkmcnt(2)
	v_mul_f32_e32 v68, s85, v68
	v_mul_f32_e32 v69, s85, v69
	v_fma_f32 v68, v68, v252, v254
	v_fma_f32 v69, v69, v253, v255
	ds_read_b64 v[252:253], v168 offset:2048
	ds_read_b64 v[254:255], v168 offset:10240
	s_waitcnt lgkmcnt(2)
	v_mul_f32_e32 v70, s85, v70
	v_mul_f32_e32 v71, s85, v71
	v_fma_f32 v70, v70, v88, v242
	v_fma_f32 v71, v71, v89, v243
	s_cmp_lg_u32 s90, 0
	s_cbranch_scc1 .Lln2_f32_18
	v_cvt_pk_bf16_f32 v64, v64, v65
	v_cvt_pk_bf16_f32 v65, v66, v67
	v_cvt_pk_bf16_f32 v66, v68, v69
	v_cvt_pk_bf16_f32 v67, v70, v71
	global_store_dwordx4 v90, v[64:67], s[12:13]
	s_branch .Lln2_st_19

.Lln2_st_25:
	s_waitcnt vmcnt(8)
	v_lshlrev_b32_e32 v64, 16, v48
	v_and_b32_e32 v65, 0xffff0000, v48
	v_and_b32_e32 v252, 0xffff0000, v32
	v_lshlrev_b32_e32 v32, 16, v32
	v_fmac_f32_e32 v64, 0x3fb504f3, v32
	v_fmac_f32_e32 v65, 0x3fb504f3, v252
	v_lshlrev_b32_e32 v66, 16, v49
	v_and_b32_e32 v67, 0xffff0000, v49
	v_and_b32_e32 v252, 0xffff0000, v33
	v_lshlrev_b32_e32 v33, 16, v33
	v_fmac_f32_e32 v66, 0x3fb504f3, v33
	v_fmac_f32_e32 v67, 0x3fb504f3, v252
	v_add_f32_e32 v252, v64, v65
	v_add_f32_e32 v253, v66, v67
	v_add_f32_e32 v254, v252, v253
	v_lshlrev_b32_e32 v68, 16, v50
	v_and_b32_e32 v69, 0xffff0000, v50
	v_and_b32_e32 v252, 0xffff0000, v34
	v_lshlrev_b32_e32 v34, 16, v34
	v_fmac_f32_e32 v68, 0x3fb504f3, v34
	v_fmac_f32_e32 v69, 0x3fb504f3, v252
	v_lshlrev_b32_e32 v70, 16, v51
	v_and_b32_e32 v71, 0xffff0000, v51
	v_and_b32_e32 v252, 0xffff0000, v35
	v_lshlrev_b32_e32 v35, 16, v35
	v_fmac_f32_e32 v70, 0x3fb504f3, v35
	v_fmac_f32_e32 v71, 0x3fb504f3, v252
	v_add_f32_e32 v252, v68, v69
	v_add_f32_e32 v253, v70, v71
	v_add_f32_e32 v252, v252, v253
	v_add_f32_e32 v254, v254, v252
	v_lshlrev_b32_e32 v72, 16, v52
	v_and_b32_e32 v73, 0xffff0000, v52
	v_and_b32_e32 v252, 0xffff0000, v36
	v_lshlrev_b32_e32 v36, 16, v36
	v_fmac_f32_e32 v72, 0x3fb504f3, v36
	v_fmac_f32_e32 v73, 0x3fb504f3, v252
	v_lshlrev_b32_e32 v74, 16, v53
	v_and_b32_e32 v75, 0xffff0000, v53
	v_and_b32_e32 v252, 0xffff0000, v37
	v_lshlrev_b32_e32 v37, 16, v37
	v_fmac_f32_e32 v74, 0x3fb504f3, v37
	v_fmac_f32_e32 v75, 0x3fb504f3, v252
	v_add_f32_e32 v252, v72, v73
	v_add_f32_e32 v253, v74, v75
	v_add_f32_e32 v252, v252, v253
	v_add_f32_e32 v254, v254, v252
	v_lshlrev_b32_e32 v76, 16, v54
	v_and_b32_e32 v77, 0xffff0000, v54
	v_and_b32_e32 v252, 0xffff0000, v38
	v_lshlrev_b32_e32 v38, 16, v38
	v_fmac_f32_e32 v76, 0x3fb504f3, v38
	v_fmac_f32_e32 v77, 0x3fb504f3, v252
	v_lshlrev_b32_e32 v78, 16, v55
	v_and_b32_e32 v79, 0xffff0000, v55
	v_and_b32_e32 v252, 0xffff0000, v39
	v_lshlrev_b32_e32 v39, 16, v39
	v_fmac_f32_e32 v78, 0x3fb504f3, v39
	v_fmac_f32_e32 v79, 0x3fb504f3, v252
	v_add_f32_e32 v252, v76, v77
	v_add_f32_e32 v253, v78, v79
	v_add_f32_e32 v252, v252, v253
	v_add_f32_e32 v254, v254, v252
	v_lshlrev_b32_e32 v80, 16, v56
	v_and_b32_e32 v81, 0xffff0000, v56
	v_and_b32_e32 v252, 0xffff0000, v40
	v_lshlrev_b32_e32 v40, 16, v40
	v_fmac_f32_e32 v80, 0x3fb504f3, v40
	v_fmac_f32_e32 v81, 0x3fb504f3, v252
	v_lshlrev_b32_e32 v82, 16, v57
	v_and_b32_e32 v83, 0xffff0000, v57
	v_and_b32_e32 v252, 0xffff0000, v41
	v_lshlrev_b32_e32 v41, 16, v41
	v_fmac_f32_e32 v82, 0x3fb504f3, v41
	v_fmac_f32_e32 v83, 0x3fb504f3, v252
	v_add_f32_e32 v252, v80, v81
	v_add_f32_e32 v253, v82, v83
	v_add_f32_e32 v252, v252, v253
	v_add_f32_e32 v254, v254, v252
	v_lshlrev_b32_e32 v84, 16, v58
	v_and_b32_e32 v85, 0xffff0000, v58
	v_and_b32_e32 v252, 0xffff0000, v42
	v_lshlrev_b32_e32 v42, 16, v42
	v_fmac_f32_e32 v84, 0x3fb504f3, v42
	v_fmac_f32_e32 v85, 0x3fb504f3, v252
	v_lshlrev_b32_e32 v86, 16, v59
	v_and_b32_e32 v87, 0xffff0000, v59
	v_and_b32_e32 v252, 0xffff0000, v43
	v_lshlrev_b32_e32 v43, 16, v43
	v_fmac_f32_e32 v86, 0x3fb504f3, v43
	v_fmac_f32_e32 v87, 0x3fb504f3, v252
	v_add_f32_e32 v252, v84, v85
	v_add_f32_e32 v253, v86, v87
	v_add_f32_e32 v252, v252, v253
	v_add_f32_e32 v254, v254, v252
	v_lshlrev_b32_e32 v244, 16, v60
	v_and_b32_e32 v245, 0xffff0000, v60
	v_and_b32_e32 v252, 0xffff0000, v44
	v_lshlrev_b32_e32 v44, 16, v44
	v_fmac_f32_e32 v244, 0x3fb504f3, v44
	v_fmac_f32_e32 v245, 0x3fb504f3, v252
	v_lshlrev_b32_e32 v246, 16, v61
	v_and_b32_e32 v247, 0xffff0000, v61
	v_and_b32_e32 v252, 0xffff0000, v45
	v_lshlrev_b32_e32 v45, 16, v45
	v_fmac_f32_e32 v246, 0x3fb504f3, v45
	v_fmac_f32_e32 v247, 0x3fb504f3, v252
	v_add_f32_e32 v252, v244, v245
	v_add_f32_e32 v253, v246, v247
	v_add_f32_e32 v252, v252, v253
	v_add_f32_e32 v254, v254, v252
	v_lshlrev_b32_e32 v248, 16, v62
	v_and_b32_e32 v249, 0xffff0000, v62
	v_and_b32_e32 v252, 0xffff0000, v46
	v_lshlrev_b32_e32 v46, 16, v46
	v_fmac_f32_e32 v248, 0x3fb504f3, v46
	v_fmac_f32_e32 v249, 0x3fb504f3, v252
	v_lshlrev_b32_e32 v250, 16, v63
	v_and_b32_e32 v251, 0xffff0000, v63
	v_and_b32_e32 v252, 0xffff0000, v47
	v_lshlrev_b32_e32 v47, 16, v47
	v_fmac_f32_e32 v250, 0x3fb504f3, v47
	v_fmac_f32_e32 v251, 0x3fb504f3, v252
	v_add_f32_e32 v252, v248, v249
	v_add_f32_e32 v253, v250, v251
	v_add_f32_e32 v252, v252, v253
	v_add_f32_e32 v254, v254, v252
	s_cmp_lt_u32 s84, 4
	s_cbranch_scc0 .Lln2_nos_26
	v_readlane_b32 s91, v241, 0
	s_lshl_b32 s30, s91, 14
	v_subrev_u32_e32 v88, s30, v90
	s_add_u32 s12, s8, 0x400000
	s_addc_u32 s13, s9, 0
	global_load_dwordx4 v[32:35], v88, s[12:13]
	global_load_dwordx4 v[36:39], v88, s[12:13] offset:1024
	global_load_dwordx4 v[40:43], v88, s[12:13] offset:2048
	global_load_dwordx4 v[44:47], v88, s[12:13] offset:3072
	s_add_u32 s12, s8, 0x800000
	s_addc_u32 s13, s9, 0
	global_load_dwordx4 v[48:51], v88, s[12:13]
	global_load_dwordx4 v[52:55], v88, s[12:13] offset:1024
	global_load_dwordx4 v[56:59], v88, s[12:13] offset:2048
	global_load_dwordx4 v[60:63], v88, s[12:13] offset:3072
.Lln2_nos_26:
	s_nop 1
	v_add_f32_dpp v252, v254, v254 quad_perm:[1,0,3,2] row_mask:0xf bank_mask:0xf
	s_nop 1
	v_add_f32_dpp v252, v252, v252 quad_perm:[2,3,0,1] row_mask:0xf bank_mask:0xf
	s_nop 1
	v_add_f32_dpp v252, v252, v252 row_half_mirror row_mask:0xf bank_mask:0xf
	s_nop 1
	v_add_f32_dpp v252, v252, v252 row_mirror row_mask:0xf bank_mask:0xf
	s_nop 1
	v_readlane_b32 s86, v252, 0
	v_readlane_b32 s87, v252, 16
	v_readlane_b32 s88, v252, 32
	v_readlane_b32 s89, v252, 48
	s_nop 1
	v_mov_b32_e32 v253, s86
	v_add_f32_e32 v253, s87, v253
	v_add_f32_e32 v253, s88, v253
	v_add_f32_e32 v253, s89, v253
	v_mul_f32_e32 v253, 0x3a000000, v253
	s_nop 0
	v_readfirstlane_b32 s85, v253
	s_nop 1
	v_subrev_f32_e32 v64, s85, v64
	v_subrev_f32_e32 v65, s85, v65
	v_subrev_f32_e32 v66, s85, v66
	v_subrev_f32_e32 v67, s85, v67
	v_subrev_f32_e32 v68, s85, v68
	v_subrev_f32_e32 v69, s85, v69
	v_subrev_f32_e32 v70, s85, v70
	v_subrev_f32_e32 v71, s85, v71
	v_mul_f32_e32 v252, v64, v64
	v_fmac_f32_e32 v252, v65, v65
	v_mul_f32_e32 v253, v66, v66
	v_fmac_f32_e32 v253, v67, v67
	v_add_f32_e32 v254, v252, v253
	v_mul_f32_e32 v252, v68, v68
	v_fmac_f32_e32 v252, v69, v69
	v_mul_f32_e32 v253, v70, v70
	v_fmac_f32_e32 v253, v71, v71
	v_add_f32_e32 v252, v252, v253
	v_add_f32_e32 v254, v254, v252
	v_subrev_f32_e32 v72, s85, v72
	v_subrev_f32_e32 v73, s85, v73
	v_subrev_f32_e32 v74, s85, v74
	v_subrev_f32_e32 v75, s85, v75
	v_subrev_f32_e32 v76, s85, v76
	v_subrev_f32_e32 v77, s85, v77
	v_subrev_f32_e32 v78, s85, v78
	v_subrev_f32_e32 v79, s85, v79
	v_mul_f32_e32 v252, v72, v72
	v_fmac_f32_e32 v252, v73, v73
	v_mul_f32_e32 v253, v74, v74
	v_fmac_f32_e32 v253, v75, v75
	v_add_f32_e32 v252, v252, v253
	v_add_f32_e32 v254, v254, v252
	v_mul_f32_e32 v252, v76, v76
	v_fmac_f32_e32 v252, v77, v77
	v_mul_f32_e32 v253, v78, v78
	v_fmac_f32_e32 v253, v79, v79
	v_add_f32_e32 v252, v252, v253
	v_add_f32_e32 v254, v254, v252
	v_subrev_f32_e32 v80, s85, v80
	v_subrev_f32_e32 v81, s85, v81
	v_subrev_f32_e32 v82, s85, v82
	v_subrev_f32_e32 v83, s85, v83
	v_subrev_f32_e32 v84, s85, v84
	v_subrev_f32_e32 v85, s85, v85
	v_subrev_f32_e32 v86, s85, v86
	v_subrev_f32_e32 v87, s85, v87
	v_mul_f32_e32 v252, v80, v80
	v_fmac_f32_e32 v252, v81, v81
	v_mul_f32_e32 v253, v82, v82
	v_fmac_f32_e32 v253, v83, v83
	v_add_f32_e32 v252, v252, v253
	v_add_f32_e32 v254, v254, v252
	v_mul_f32_e32 v252, v84, v84
	v_fmac_f32_e32 v252, v85, v85
	v_mul_f32_e32 v253, v86, v86
	v_fmac_f32_e32 v253, v87, v87
	v_add_f32_e32 v252, v252, v253
	v_add_f32_e32 v254, v254, v252
	v_subrev_f32_e32 v244, s85, v244
	v_subrev_f32_e32 v245, s85, v245
	v_subrev_f32_e32 v246, s85, v246
	v_subrev_f32_e32 v247, s85, v247
	v_subrev_f32_e32 v248, s85, v248
	v_subrev_f32_e32 v249, s85, v249
	v_subrev_f32_e32 v250, s85, v250
	v_subrev_f32_e32 v251, s85, v251
	v_mul_f32_e32 v252, v244, v244
	v_fmac_f32_e32 v252, v245, v245
	v_mul_f32_e32 v253, v246, v246
	v_fmac_f32_e32 v253, v247, v247
	v_add_f32_e32 v252, v252, v253
	v_add_f32_e32 v254, v254, v252
	v_mul_f32_e32 v252, v248, v248
	v_fmac_f32_e32 v252, v249, v249
	v_mul_f32_e32 v253, v250, v250
	v_fmac_f32_e32 v253, v251, v251
	v_add_f32_e32 v252, v252, v253
	v_add_f32_e32 v254, v254, v252
	s_nop 1
	v_add_f32_dpp v252, v254, v254 quad_perm:[1,0,3,2] row_mask:0xf bank_mask:0xf
	s_nop 1
	v_add_f32_dpp v252, v252, v252 quad_perm:[2,3,0,1] row_mask:0xf bank_mask:0xf
	s_nop 1
	v_add_f32_dpp v252, v252, v252 row_half_mirror row_mask:0xf bank_mask:0xf
	s_nop 1
	v_add_f32_dpp v252, v252, v252 row_mirror row_mask:0xf bank_mask:0xf
	s_nop 1
	v_readlane_b32 s86, v252, 0
	v_readlane_b32 s87, v252, 16
	v_readlane_b32 s88, v252, 32
	v_readlane_b32 s89, v252, 48
	s_nop 1
	v_mov_b32_e32 v253, s86
	v_add_f32_e32 v253, s87, v253
	v_add_f32_e32 v253, s88, v253
	v_add_f32_e32 v253, s89, v253
	v_mov_b32_e32 v252, 0x3a000000
	v_fmaak_f32 v253, v253, v252, 0x3727c5ac
	v_rsq_f32_e32 v253, v253
	s_nop 1
	v_readfirstlane_b32 s85, v253
	s_add_u32 s12, s4, 0x1800000
	s_addc_u32 s13, s5, 0
	v_readlane_b32 s86, v241, 7
	v_readlane_b32 s87, v241, 8
	s_add_u32 s86, s86, 0x3000000
	s_addc_u32 s87, s87, 0
	s_add_u32 s88, s86, 0x1000
	s_addc_u32 s89, s87, 0
	ds_read_b64 v[252:253], v168
	ds_read_b64 v[254:255], v168 offset:8192
	ds_read_b64 v[88:89], v168 offset:512
	ds_read_b64 v[242:243], v168 offset:8704
	s_waitcnt lgkmcnt(2)
	v_mul_f32_e32 v64, s85, v64
	v_mul_f32_e32 v65, s85, v65
	v_fma_f32 v64, v64, v252, v254
	v_fma_f32 v65, v65, v253, v255
	ds_read_b64 v[252:253], v168 offset:1024
	ds_read_b64 v[254:255], v168 offset:9216
	s_waitcnt lgkmcnt(2)
	v_mul_f32_e32 v66, s85, v66
	v_mul_f32_e32 v67, s85, v67
	v_fma_f32 v66, v66, v88, v242
	v_fma_f32 v67, v67, v89, v243
	ds_read_b64 v[88:89], v168 offset:1536
	ds_read_b64 v[242:243], v168 offset:9728
	s_waitcnt lgkmcnt(2)
	v_mul_f32_e32 v68, s85, v68
	v_mul_f32_e32 v69, s85, v69
	v_fma_f32 v68, v68, v252, v254
	v_fma_f32 v69, v69, v253, v255
	ds_read_b64 v[252:253], v168 offset:2048
	ds_read_b64 v[254:255], v168 offset:10240
	s_waitcnt lgkmcnt(2)
	v_mul_f32_e32 v70, s85, v70
	v_mul_f32_e32 v71, s85, v71
	v_fma_f32 v70, v70, v88, v242
	v_fma_f32 v71, v71, v89, v243
	s_cmp_lg_u32 s90, 0
	s_cbranch_scc1 .Lln2_f32_27
	v_cvt_pk_bf16_f32 v64, v64, v65
	v_cvt_pk_bf16_f32 v65, v66, v67
	v_cvt_pk_bf16_f32 v66, v68, v69
	v_cvt_pk_bf16_f32 v67, v70, v71
	global_store_dwordx4 v90, v[64:67], s[12:13]
	s_branch .Lln2_st_28

.Lln2_st_34:
	s_cmp_lt_u32 s84, 4
	s_cbranch_scc0 .Lln2_done
	v_readlane_b32 s91, v241, 0
	s_lshl_b32 s30, s91, 14
	v_subrev_u32_e32 v90, s30, v90
	s_waitcnt vmcnt(12)
	v_lshlrev_b32_e32 v64, 16, v16
	v_and_b32_e32 v65, 0xffff0000, v16
	v_lshlrev_b32_e32 v66, 16, v17
	v_and_b32_e32 v67, 0xffff0000, v17
	v_lshlrev_b32_e32 v68, 16, v18
	v_and_b32_e32 v69, 0xffff0000, v18
	v_lshlrev_b32_e32 v70, 16, v19
	v_and_b32_e32 v71, 0xffff0000, v19
	v_lshlrev_b32_e32 v72, 16, v20
	v_and_b32_e32 v73, 0xffff0000, v20
	v_lshlrev_b32_e32 v74, 16, v21
	v_and_b32_e32 v75, 0xffff0000, v21
	v_lshlrev_b32_e32 v76, 16, v22
	v_and_b32_e32 v77, 0xffff0000, v22
	v_lshlrev_b32_e32 v78, 16, v23
	v_and_b32_e32 v79, 0xffff0000, v23
	v_lshlrev_b32_e32 v80, 16, v24
	v_and_b32_e32 v81, 0xffff0000, v24
	v_lshlrev_b32_e32 v82, 16, v25
	v_and_b32_e32 v83, 0xffff0000, v25
	v_lshlrev_b32_e32 v84, 16, v26
	v_and_b32_e32 v85, 0xffff0000, v26
	v_lshlrev_b32_e32 v86, 16, v27
	v_and_b32_e32 v87, 0xffff0000, v27
	v_lshlrev_b32_e32 v244, 16, v28
	v_and_b32_e32 v245, 0xffff0000, v28
	v_lshlrev_b32_e32 v246, 16, v29
	v_and_b32_e32 v247, 0xffff0000, v29
	v_lshlrev_b32_e32 v248, 16, v30
	v_and_b32_e32 v249, 0xffff0000, v30
	v_lshlrev_b32_e32 v250, 16, v31
	v_and_b32_e32 v251, 0xffff0000, v31
	s_add_u32 s12, s8, 0xc00000
	s_addc_u32 s13, s9, 0
	global_load_dwordx4 v[16:19], v90, s[12:13]
	global_load_dwordx4 v[20:23], v90, s[12:13] offset:1024
	global_load_dwordx4 v[24:27], v90, s[12:13] offset:2048
	global_load_dwordx4 v[28:31], v90, s[12:13] offset:3072
	s_waitcnt vmcnt(12)
	v_lshlrev_b32_e32 v252, 16, v32
	v_and_b32_e32 v253, 0xffff0000, v32
	v_add_f32_e32 v64, v64, v252
	v_add_f32_e32 v65, v65, v253
	v_lshlrev_b32_e32 v252, 16, v33
	v_and_b32_e32 v253, 0xffff0000, v33
	v_add_f32_e32 v66, v66, v252
	v_add_f32_e32 v67, v67, v253
	v_lshlrev_b32_e32 v252, 16, v34
	v_and_b32_e32 v253, 0xffff0000, v34
	v_add_f32_e32 v68, v68, v252
	v_add_f32_e32 v69, v69, v253
	v_lshlrev_b32_e32 v252, 16, v35
	v_and_b32_e32 v253, 0xffff0000, v35
	v_add_f32_e32 v70, v70, v252
	v_add_f32_e32 v71, v71, v253
	v_lshlrev_b32_e32 v252, 16, v36
	v_and_b32_e32 v253, 0xffff0000, v36
	v_add_f32_e32 v72, v72, v252
	v_add_f32_e32 v73, v73, v253
	v_lshlrev_b32_e32 v252, 16, v37
	v_and_b32_e32 v253, 0xffff0000, v37
	v_add_f32_e32 v74, v74, v252
	v_add_f32_e32 v75, v75, v253
	v_lshlrev_b32_e32 v252, 16, v38
	v_and_b32_e32 v253, 0xffff0000, v38
	v_add_f32_e32 v76, v76, v252
	v_add_f32_e32 v77, v77, v253
	v_lshlrev_b32_e32 v252, 16, v39
	v_and_b32_e32 v253, 0xffff0000, v39
	v_add_f32_e32 v78, v78, v252
	v_add_f32_e32 v79, v79, v253
	v_lshlrev_b32_e32 v252, 16, v40
	v_and_b32_e32 v253, 0xffff0000, v40
	v_add_f32_e32 v80, v80, v252
	v_add_f32_e32 v81, v81, v253
	v_lshlrev_b32_e32 v252, 16, v41
	v_and_b32_e32 v253, 0xffff0000, v41
	v_add_f32_e32 v82, v82, v252
	v_add_f32_e32 v83, v83, v253
	v_lshlrev_b32_e32 v252, 16, v42
	v_and_b32_e32 v253, 0xffff0000, v42
	v_add_f32_e32 v84, v84, v252
	v_add_f32_e32 v85, v85, v253
	v_lshlrev_b32_e32 v252, 16, v43
	v_and_b32_e32 v253, 0xffff0000, v43
	v_add_f32_e32 v86, v86, v252
	v_add_f32_e32 v87, v87, v253
	v_lshlrev_b32_e32 v252, 16, v44
	v_and_b32_e32 v253, 0xffff0000, v44
	v_add_f32_e32 v244, v244, v252
	v_add_f32_e32 v245, v245, v253
	v_lshlrev_b32_e32 v252, 16, v45
	v_and_b32_e32 v253, 0xffff0000, v45
	v_add_f32_e32 v246, v246, v252
	v_add_f32_e32 v247, v247, v253
	v_lshlrev_b32_e32 v252, 16, v46
	v_and_b32_e32 v253, 0xffff0000, v46
	v_add_f32_e32 v248, v248, v252
	v_add_f32_e32 v249, v249, v253
	v_lshlrev_b32_e32 v252, 16, v47
	v_and_b32_e32 v253, 0xffff0000, v47
	v_add_f32_e32 v250, v250, v252
	v_add_f32_e32 v251, v251, v253
	s_add_u32 s12, s8, 0x1000000
	s_addc_u32 s13, s9, 0
	global_load_dwordx4 v[32:35], v90, s[12:13]
	global_load_dwordx4 v[36:39], v90, s[12:13] offset:1024
	global_load_dwordx4 v[40:43], v90, s[12:13] offset:2048
	global_load_dwordx4 v[44:47], v90, s[12:13] offset:3072
	s_waitcnt vmcnt(8)
	v_lshlrev_b32_e32 v252, 16, v48
	v_and_b32_e32 v253, 0xffff0000, v48
	v_add_f32_e32 v64, v64, v252
	v_add_f32_e32 v65, v65, v253
	v_lshlrev_b32_e32 v252, 16, v49
	v_and_b32_e32 v253, 0xffff0000, v49
	v_add_f32_e32 v66, v66, v252
	v_add_f32_e32 v67, v67, v253
	v_lshlrev_b32_e32 v252, 16, v50
	v_and_b32_e32 v253, 0xffff0000, v50
	v_add_f32_e32 v68, v68, v252
	v_add_f32_e32 v69, v69, v253
	v_lshlrev_b32_e32 v252, 16, v51
	v_and_b32_e32 v253, 0xffff0000, v51
	v_add_f32_e32 v70, v70, v252
	v_add_f32_e32 v71, v71, v253
	v_lshlrev_b32_e32 v252, 16, v52
	v_and_b32_e32 v253, 0xffff0000, v52
	v_add_f32_e32 v72, v72, v252
	v_add_f32_e32 v73, v73, v253
	v_lshlrev_b32_e32 v252, 16, v53
	v_and_b32_e32 v253, 0xffff0000, v53
	v_add_f32_e32 v74, v74, v252
	v_add_f32_e32 v75, v75, v253
	v_lshlrev_b32_e32 v252, 16, v54
	v_and_b32_e32 v253, 0xffff0000, v54
	v_add_f32_e32 v76, v76, v252
	v_add_f32_e32 v77, v77, v253
	v_lshlrev_b32_e32 v252, 16, v55
	v_and_b32_e32 v253, 0xffff0000, v55
	v_add_f32_e32 v78, v78, v252
	v_add_f32_e32 v79, v79, v253
	v_lshlrev_b32_e32 v252, 16, v56
	v_and_b32_e32 v253, 0xffff0000, v56
	v_add_f32_e32 v80, v80, v252
	v_add_f32_e32 v81, v81, v253
	v_lshlrev_b32_e32 v252, 16, v57
	v_and_b32_e32 v253, 0xffff0000, v57
	v_add_f32_e32 v82, v82, v252
	v_add_f32_e32 v83, v83, v253
	v_lshlrev_b32_e32 v252, 16, v58
	v_and_b32_e32 v253, 0xffff0000, v58
	v_add_f32_e32 v84, v84, v252
	v_add_f32_e32 v85, v85, v253
	v_lshlrev_b32_e32 v252, 16, v59
	v_and_b32_e32 v253, 0xffff0000, v59
	v_add_f32_e32 v86, v86, v252
	v_add_f32_e32 v87, v87, v253
	v_lshlrev_b32_e32 v252, 16, v60
	v_and_b32_e32 v253, 0xffff0000, v60
	v_add_f32_e32 v244, v244, v252
	v_add_f32_e32 v245, v245, v253
	v_lshlrev_b32_e32 v252, 16, v61
	v_and_b32_e32 v253, 0xffff0000, v61
	v_add_f32_e32 v246, v246, v252
	v_add_f32_e32 v247, v247, v253
	v_lshlrev_b32_e32 v252, 16, v62
	v_and_b32_e32 v253, 0xffff0000, v62
	v_add_f32_e32 v248, v248, v252
	v_add_f32_e32 v249, v249, v253
	v_lshlrev_b32_e32 v252, 16, v63
	v_and_b32_e32 v253, 0xffff0000, v63
	v_add_f32_e32 v250, v250, v252
	v_add_f32_e32 v251, v251, v253
	s_add_u32 s12, s8, 0x1400000
	s_addc_u32 s13, s9, 0
	global_load_dwordx4 v[48:51], v90, s[12:13]
	global_load_dwordx4 v[52:55], v90, s[12:13] offset:1024
	global_load_dwordx4 v[56:59], v90, s[12:13] offset:2048
	global_load_dwordx4 v[60:63], v90, s[12:13] offset:3072
	s_waitcnt vmcnt(8)
	v_lshlrev_b32_e32 v252, 16, v16
	v_and_b32_e32 v253, 0xffff0000, v16
	v_add_f32_e32 v64, v64, v252
	v_add_f32_e32 v65, v65, v253
	v_lshlrev_b32_e32 v252, 16, v17
	v_and_b32_e32 v253, 0xffff0000, v17
	v_add_f32_e32 v66, v66, v252
	v_add_f32_e32 v67, v67, v253
	v_lshlrev_b32_e32 v252, 16, v18
	v_and_b32_e32 v253, 0xffff0000, v18
	v_add_f32_e32 v68, v68, v252
	v_add_f32_e32 v69, v69, v253
	v_lshlrev_b32_e32 v252, 16, v19
	v_and_b32_e32 v253, 0xffff0000, v19
	v_add_f32_e32 v70, v70, v252
	v_add_f32_e32 v71, v71, v253
	v_lshlrev_b32_e32 v252, 16, v20
	v_and_b32_e32 v253, 0xffff0000, v20
	v_add_f32_e32 v72, v72, v252
	v_add_f32_e32 v73, v73, v253
	v_lshlrev_b32_e32 v252, 16, v21
	v_and_b32_e32 v253, 0xffff0000, v21
	v_add_f32_e32 v74, v74, v252
	v_add_f32_e32 v75, v75, v253
	v_lshlrev_b32_e32 v252, 16, v22
	v_and_b32_e32 v253, 0xffff0000, v22
	v_add_f32_e32 v76, v76, v252
	v_add_f32_e32 v77, v77, v253
	v_lshlrev_b32_e32 v252, 16, v23
	v_and_b32_e32 v253, 0xffff0000, v23
	v_add_f32_e32 v78, v78, v252
	v_add_f32_e32 v79, v79, v253
	v_lshlrev_b32_e32 v252, 16, v24
	v_and_b32_e32 v253, 0xffff0000, v24
	v_add_f32_e32 v80, v80, v252
	v_add_f32_e32 v81, v81, v253
	v_lshlrev_b32_e32 v252, 16, v25
	v_and_b32_e32 v253, 0xffff0000, v25
	v_add_f32_e32 v82, v82, v252
	v_add_f32_e32 v83, v83, v253
	v_lshlrev_b32_e32 v252, 16, v26
	v_and_b32_e32 v253, 0xffff0000, v26
	v_add_f32_e32 v84, v84, v252
	v_add_f32_e32 v85, v85, v253
	v_lshlrev_b32_e32 v252, 16, v27
	v_and_b32_e32 v253, 0xffff0000, v27
	v_add_f32_e32 v86, v86, v252
	v_add_f32_e32 v87, v87, v253
	v_lshlrev_b32_e32 v252, 16, v28
	v_and_b32_e32 v253, 0xffff0000, v28
	v_add_f32_e32 v244, v244, v252
	v_add_f32_e32 v245, v245, v253
	v_lshlrev_b32_e32 v252, 16, v29
	v_and_b32_e32 v253, 0xffff0000, v29
	v_add_f32_e32 v246, v246, v252
	v_add_f32_e32 v247, v247, v253
	v_lshlrev_b32_e32 v252, 16, v30
	v_and_b32_e32 v253, 0xffff0000, v30
	v_add_f32_e32 v248, v248, v252
	v_add_f32_e32 v249, v249, v253
	v_lshlrev_b32_e32 v252, 16, v31
	v_and_b32_e32 v253, 0xffff0000, v31
	v_add_f32_e32 v250, v250, v252
	v_add_f32_e32 v251, v251, v253
	s_add_u32 s12, s8, 0x1800000
	s_addc_u32 s13, s9, 0
	global_load_dwordx4 v[16:19], v90, s[12:13]
	global_load_dwordx4 v[20:23], v90, s[12:13] offset:1024
	global_load_dwordx4 v[24:27], v90, s[12:13] offset:2048
	global_load_dwordx4 v[28:31], v90, s[12:13] offset:3072
	s_waitcnt vmcnt(8)
	v_lshlrev_b32_e32 v252, 16, v32
	v_and_b32_e32 v253, 0xffff0000, v32
	v_add_f32_e32 v64, v64, v252
	v_add_f32_e32 v65, v65, v253
	v_lshlrev_b32_e32 v252, 16, v33
	v_and_b32_e32 v253, 0xffff0000, v33
	v_add_f32_e32 v66, v66, v252
	v_add_f32_e32 v67, v67, v253
	v_lshlrev_b32_e32 v252, 16, v34
	v_and_b32_e32 v253, 0xffff0000, v34
	v_add_f32_e32 v68, v68, v252
	v_add_f32_e32 v69, v69, v253
	v_lshlrev_b32_e32 v252, 16, v35
	v_and_b32_e32 v253, 0xffff0000, v35
	v_add_f32_e32 v70, v70, v252
	v_add_f32_e32 v71, v71, v253
	v_lshlrev_b32_e32 v252, 16, v36
	v_and_b32_e32 v253, 0xffff0000, v36
	v_add_f32_e32 v72, v72, v252
	v_add_f32_e32 v73, v73, v253
	v_lshlrev_b32_e32 v252, 16, v37
	v_and_b32_e32 v253, 0xffff0000, v37
	v_add_f32_e32 v74, v74, v252
	v_add_f32_e32 v75, v75, v253
	v_lshlrev_b32_e32 v252, 16, v38
	v_and_b32_e32 v253, 0xffff0000, v38
	v_add_f32_e32 v76, v76, v252
	v_add_f32_e32 v77, v77, v253
	v_lshlrev_b32_e32 v252, 16, v39
	v_and_b32_e32 v253, 0xffff0000, v39
	v_add_f32_e32 v78, v78, v252
	v_add_f32_e32 v79, v79, v253
	v_lshlrev_b32_e32 v252, 16, v40
	v_and_b32_e32 v253, 0xffff0000, v40
	v_add_f32_e32 v80, v80, v252
	v_add_f32_e32 v81, v81, v253
	v_lshlrev_b32_e32 v252, 16, v41
	v_and_b32_e32 v253, 0xffff0000, v41
	v_add_f32_e32 v82, v82, v252
	v_add_f32_e32 v83, v83, v253
	v_lshlrev_b32_e32 v252, 16, v42
	v_and_b32_e32 v253, 0xffff0000, v42
	v_add_f32_e32 v84, v84, v252
	v_add_f32_e32 v85, v85, v253
	v_lshlrev_b32_e32 v252, 16, v43
	v_and_b32_e32 v253, 0xffff0000, v43
	v_add_f32_e32 v86, v86, v252
	v_add_f32_e32 v87, v87, v253
	v_lshlrev_b32_e32 v252, 16, v44
	v_and_b32_e32 v253, 0xffff0000, v44
	v_add_f32_e32 v244, v244, v252
	v_add_f32_e32 v245, v245, v253
	v_lshlrev_b32_e32 v252, 16, v45
	v_and_b32_e32 v253, 0xffff0000, v45
	v_add_f32_e32 v246, v246, v252
	v_add_f32_e32 v247, v247, v253
	v_lshlrev_b32_e32 v252, 16, v46
	v_and_b32_e32 v253, 0xffff0000, v46
	v_add_f32_e32 v248, v248, v252
	v_add_f32_e32 v249, v249, v253
	v_lshlrev_b32_e32 v252, 16, v47
	v_and_b32_e32 v253, 0xffff0000, v47
	v_add_f32_e32 v250, v250, v252
	v_add_f32_e32 v251, v251, v253
	s_add_u32 s12, s8, 0x1c00000
	s_addc_u32 s13, s9, 0
	global_load_dwordx4 v[32:35], v90, s[12:13]
	global_load_dwordx4 v[36:39], v90, s[12:13] offset:1024
	global_load_dwordx4 v[40:43], v90, s[12:13] offset:2048
	global_load_dwordx4 v[44:47], v90, s[12:13] offset:3072
	s_waitcnt vmcnt(8)
	v_lshlrev_b32_e32 v252, 16, v48
	v_and_b32_e32 v253, 0xffff0000, v48
	v_add_f32_e32 v64, v64, v252
	v_add_f32_e32 v65, v65, v253
	v_lshlrev_b32_e32 v252, 16, v49
	v_and_b32_e32 v253, 0xffff0000, v49
	v_add_f32_e32 v66, v66, v252
	v_add_f32_e32 v67, v67, v253
	v_lshlrev_b32_e32 v252, 16, v50
	v_and_b32_e32 v253, 0xffff0000, v50
	v_add_f32_e32 v68, v68, v252
	v_add_f32_e32 v69, v69, v253
	v_lshlrev_b32_e32 v252, 16, v51
	v_and_b32_e32 v253, 0xffff0000, v51
	v_add_f32_e32 v70, v70, v252
	v_add_f32_e32 v71, v71, v253
	v_lshlrev_b32_e32 v252, 16, v52
	v_and_b32_e32 v253, 0xffff0000, v52
	v_add_f32_e32 v72, v72, v252
	v_add_f32_e32 v73, v73, v253
	v_lshlrev_b32_e32 v252, 16, v53
	v_and_b32_e32 v253, 0xffff0000, v53
	v_add_f32_e32 v74, v74, v252
	v_add_f32_e32 v75, v75, v253
	v_lshlrev_b32_e32 v252, 16, v54
	v_and_b32_e32 v253, 0xffff0000, v54
	v_add_f32_e32 v76, v76, v252
	v_add_f32_e32 v77, v77, v253
	v_lshlrev_b32_e32 v252, 16, v55
	v_and_b32_e32 v253, 0xffff0000, v55
	v_add_f32_e32 v78, v78, v252
	v_add_f32_e32 v79, v79, v253
	v_lshlrev_b32_e32 v252, 16, v56
	v_and_b32_e32 v253, 0xffff0000, v56
	v_add_f32_e32 v80, v80, v252
	v_add_f32_e32 v81, v81, v253
	v_lshlrev_b32_e32 v252, 16, v57
	v_and_b32_e32 v253, 0xffff0000, v57
	v_add_f32_e32 v82, v82, v252
	v_add_f32_e32 v83, v83, v253
	v_lshlrev_b32_e32 v252, 16, v58
	v_and_b32_e32 v253, 0xffff0000, v58
	v_add_f32_e32 v84, v84, v252
	v_add_f32_e32 v85, v85, v253
	v_lshlrev_b32_e32 v252, 16, v59
	v_and_b32_e32 v253, 0xffff0000, v59
	v_add_f32_e32 v86, v86, v252
	v_add_f32_e32 v87, v87, v253
	v_lshlrev_b32_e32 v252, 16, v60
	v_and_b32_e32 v253, 0xffff0000, v60
	v_add_f32_e32 v244, v244, v252
	v_add_f32_e32 v245, v245, v253
	v_lshlrev_b32_e32 v252, 16, v61
	v_and_b32_e32 v253, 0xffff0000, v61
	v_add_f32_e32 v246, v246, v252
	v_add_f32_e32 v247, v247, v253
	v_lshlrev_b32_e32 v252, 16, v62
	v_and_b32_e32 v253, 0xffff0000, v62
	v_add_f32_e32 v248, v248, v252
	v_add_f32_e32 v249, v249, v253
	v_lshlrev_b32_e32 v252, 16, v63
	v_and_b32_e32 v253, 0xffff0000, v63
	v_add_f32_e32 v250, v250, v252
	v_add_f32_e32 v251, v251, v253
	s_waitcnt vmcnt(4)
	v_lshlrev_b32_e32 v252, 16, v16
	v_and_b32_e32 v253, 0xffff0000, v16
	v_add_f32_e32 v64, v64, v252
	v_add_f32_e32 v65, v65, v253
	v_lshlrev_b32_e32 v252, 16, v17
	v_and_b32_e32 v253, 0xffff0000, v17
	v_add_f32_e32 v66, v66, v252
	v_add_f32_e32 v67, v67, v253
	v_lshlrev_b32_e32 v252, 16, v18
	v_and_b32_e32 v253, 0xffff0000, v18
	v_add_f32_e32 v68, v68, v252
	v_add_f32_e32 v69, v69, v253
	v_lshlrev_b32_e32 v252, 16, v19
	v_and_b32_e32 v253, 0xffff0000, v19
	v_add_f32_e32 v70, v70, v252
	v_add_f32_e32 v71, v71, v253
	v_lshlrev_b32_e32 v252, 16, v20
	v_and_b32_e32 v253, 0xffff0000, v20
	v_add_f32_e32 v72, v72, v252
	v_add_f32_e32 v73, v73, v253
	v_lshlrev_b32_e32 v252, 16, v21
	v_and_b32_e32 v253, 0xffff0000, v21
	v_add_f32_e32 v74, v74, v252
	v_add_f32_e32 v75, v75, v253
	v_lshlrev_b32_e32 v252, 16, v22
	v_and_b32_e32 v253, 0xffff0000, v22
	v_add_f32_e32 v76, v76, v252
	v_add_f32_e32 v77, v77, v253
	v_lshlrev_b32_e32 v252, 16, v23
	v_and_b32_e32 v253, 0xffff0000, v23
	v_add_f32_e32 v78, v78, v252
	v_add_f32_e32 v79, v79, v253
	v_lshlrev_b32_e32 v252, 16, v24
	v_and_b32_e32 v253, 0xffff0000, v24
	v_add_f32_e32 v80, v80, v252
	v_add_f32_e32 v81, v81, v253
	v_lshlrev_b32_e32 v252, 16, v25
	v_and_b32_e32 v253, 0xffff0000, v25
	v_add_f32_e32 v82, v82, v252
	v_add_f32_e32 v83, v83, v253
	v_lshlrev_b32_e32 v252, 16, v26
	v_and_b32_e32 v253, 0xffff0000, v26
	v_add_f32_e32 v84, v84, v252
	v_add_f32_e32 v85, v85, v253
	v_lshlrev_b32_e32 v252, 16, v27
	v_and_b32_e32 v253, 0xffff0000, v27
	v_add_f32_e32 v86, v86, v252
	v_add_f32_e32 v87, v87, v253
	v_lshlrev_b32_e32 v252, 16, v28
	v_and_b32_e32 v253, 0xffff0000, v28
	v_add_f32_e32 v244, v244, v252
	v_add_f32_e32 v245, v245, v253
	v_lshlrev_b32_e32 v252, 16, v29
	v_and_b32_e32 v253, 0xffff0000, v29
	v_add_f32_e32 v246, v246, v252
	v_add_f32_e32 v247, v247, v253
	v_lshlrev_b32_e32 v252, 16, v30
	v_and_b32_e32 v253, 0xffff0000, v30
	v_add_f32_e32 v248, v248, v252
	v_add_f32_e32 v249, v249, v253
	v_lshlrev_b32_e32 v252, 16, v31
	v_and_b32_e32 v253, 0xffff0000, v31
	v_add_f32_e32 v250, v250, v252
	v_add_f32_e32 v251, v251, v253
	s_waitcnt vmcnt(0)
	v_lshlrev_b32_e32 v252, 16, v32
	v_and_b32_e32 v253, 0xffff0000, v32
	v_add_f32_e32 v64, v64, v252
	v_add_f32_e32 v65, v65, v253
	v_lshlrev_b32_e32 v252, 16, v33
	v_and_b32_e32 v253, 0xffff0000, v33
	v_add_f32_e32 v66, v66, v252
	v_add_f32_e32 v67, v67, v253
	v_lshlrev_b32_e32 v252, 16, v34
	v_and_b32_e32 v253, 0xffff0000, v34
	v_add_f32_e32 v68, v68, v252
	v_add_f32_e32 v69, v69, v253
	v_lshlrev_b32_e32 v252, 16, v35
	v_and_b32_e32 v253, 0xffff0000, v35
	v_add_f32_e32 v70, v70, v252
	v_add_f32_e32 v71, v71, v253
	v_lshlrev_b32_e32 v252, 16, v36
	v_and_b32_e32 v253, 0xffff0000, v36
	v_add_f32_e32 v72, v72, v252
	v_add_f32_e32 v73, v73, v253
	v_lshlrev_b32_e32 v252, 16, v37
	v_and_b32_e32 v253, 0xffff0000, v37
	v_add_f32_e32 v74, v74, v252
	v_add_f32_e32 v75, v75, v253
	v_lshlrev_b32_e32 v252, 16, v38
	v_and_b32_e32 v253, 0xffff0000, v38
	v_add_f32_e32 v76, v76, v252
	v_add_f32_e32 v77, v77, v253
	v_lshlrev_b32_e32 v252, 16, v39
	v_and_b32_e32 v253, 0xffff0000, v39
	v_add_f32_e32 v78, v78, v252
	v_add_f32_e32 v79, v79, v253
	v_lshlrev_b32_e32 v252, 16, v40
	v_and_b32_e32 v253, 0xffff0000, v40
	v_add_f32_e32 v80, v80, v252
	v_add_f32_e32 v81, v81, v253
	v_lshlrev_b32_e32 v252, 16, v41
	v_and_b32_e32 v253, 0xffff0000, v41
	v_add_f32_e32 v82, v82, v252
	v_add_f32_e32 v83, v83, v253
	v_lshlrev_b32_e32 v252, 16, v42
	v_and_b32_e32 v253, 0xffff0000, v42
	v_add_f32_e32 v84, v84, v252
	v_add_f32_e32 v85, v85, v253
	v_lshlrev_b32_e32 v252, 16, v43
	v_and_b32_e32 v253, 0xffff0000, v43
	v_add_f32_e32 v86, v86, v252
	v_add_f32_e32 v87, v87, v253
	v_lshlrev_b32_e32 v252, 16, v44
	v_and_b32_e32 v253, 0xffff0000, v44
	v_add_f32_e32 v244, v244, v252
	v_add_f32_e32 v245, v245, v253
	v_lshlrev_b32_e32 v252, 16, v45
	v_and_b32_e32 v253, 0xffff0000, v45
	v_add_f32_e32 v246, v246, v252
	v_add_f32_e32 v247, v247, v253
	v_lshlrev_b32_e32 v252, 16, v46
	v_and_b32_e32 v253, 0xffff0000, v46
	v_add_f32_e32 v248, v248, v252
	v_add_f32_e32 v249, v249, v253
	v_lshlrev_b32_e32 v252, 16, v47
	v_and_b32_e32 v253, 0xffff0000, v47
	v_add_f32_e32 v250, v250, v252
	v_add_f32_e32 v251, v251, v253
	v_and_b32_e32 v252, 0xffff0000, v0
	v_lshlrev_b32_e32 v0, 16, v0
	v_fmac_f32_e32 v64, 0x3fb504f3, v0
	v_fmac_f32_e32 v65, 0x3fb504f3, v252
	v_and_b32_e32 v252, 0xffff0000, v1
	v_lshlrev_b32_e32 v1, 16, v1
	v_fmac_f32_e32 v66, 0x3fb504f3, v1
	v_fmac_f32_e32 v67, 0x3fb504f3, v252
	v_add_f32_e32 v252, v64, v65
	v_add_f32_e32 v253, v66, v67
	v_add_f32_e32 v254, v252, v253
	v_and_b32_e32 v252, 0xffff0000, v2
	v_lshlrev_b32_e32 v2, 16, v2
	v_fmac_f32_e32 v68, 0x3fb504f3, v2
	v_fmac_f32_e32 v69, 0x3fb504f3, v252
	v_and_b32_e32 v252, 0xffff0000, v3
	v_lshlrev_b32_e32 v3, 16, v3
	v_fmac_f32_e32 v70, 0x3fb504f3, v3
	v_fmac_f32_e32 v71, 0x3fb504f3, v252
	v_add_f32_e32 v252, v68, v69
	v_add_f32_e32 v253, v70, v71
	v_add_f32_e32 v252, v252, v253
	v_add_f32_e32 v254, v254, v252
	v_and_b32_e32 v252, 0xffff0000, v4
	v_lshlrev_b32_e32 v4, 16, v4
	v_fmac_f32_e32 v72, 0x3fb504f3, v4
	v_fmac_f32_e32 v73, 0x3fb504f3, v252
	v_and_b32_e32 v252, 0xffff0000, v5
	v_lshlrev_b32_e32 v5, 16, v5
	v_fmac_f32_e32 v74, 0x3fb504f3, v5
	v_fmac_f32_e32 v75, 0x3fb504f3, v252
	v_add_f32_e32 v252, v72, v73
	v_add_f32_e32 v253, v74, v75
	v_add_f32_e32 v252, v252, v253
	v_add_f32_e32 v254, v254, v252
	v_and_b32_e32 v252, 0xffff0000, v6
	v_lshlrev_b32_e32 v6, 16, v6
	v_fmac_f32_e32 v76, 0x3fb504f3, v6
	v_fmac_f32_e32 v77, 0x3fb504f3, v252
	v_and_b32_e32 v252, 0xffff0000, v7
	v_lshlrev_b32_e32 v7, 16, v7
	v_fmac_f32_e32 v78, 0x3fb504f3, v7
	v_fmac_f32_e32 v79, 0x3fb504f3, v252
	v_add_f32_e32 v252, v76, v77
	v_add_f32_e32 v253, v78, v79
	v_add_f32_e32 v252, v252, v253
	v_add_f32_e32 v254, v254, v252
	v_and_b32_e32 v252, 0xffff0000, v8
	v_lshlrev_b32_e32 v8, 16, v8
	v_fmac_f32_e32 v80, 0x3fb504f3, v8
	v_fmac_f32_e32 v81, 0x3fb504f3, v252
	v_and_b32_e32 v252, 0xffff0000, v9
	v_lshlrev_b32_e32 v9, 16, v9
	v_fmac_f32_e32 v82, 0x3fb504f3, v9
	v_fmac_f32_e32 v83, 0x3fb504f3, v252
	v_add_f32_e32 v252, v80, v81
	v_add_f32_e32 v253, v82, v83
	v_add_f32_e32 v252, v252, v253
	v_add_f32_e32 v254, v254, v252
	v_and_b32_e32 v252, 0xffff0000, v10
	v_lshlrev_b32_e32 v10, 16, v10
	v_fmac_f32_e32 v84, 0x3fb504f3, v10
	v_fmac_f32_e32 v85, 0x3fb504f3, v252
	v_and_b32_e32 v252, 0xffff0000, v11
	v_lshlrev_b32_e32 v11, 16, v11
	v_fmac_f32_e32 v86, 0x3fb504f3, v11
	v_fmac_f32_e32 v87, 0x3fb504f3, v252
	v_add_f32_e32 v252, v84, v85
	v_add_f32_e32 v253, v86, v87
	v_add_f32_e32 v252, v252, v253
	v_add_f32_e32 v254, v254, v252
	v_and_b32_e32 v252, 0xffff0000, v12
	v_lshlrev_b32_e32 v12, 16, v12
	v_fmac_f32_e32 v244, 0x3fb504f3, v12
	v_fmac_f32_e32 v245, 0x3fb504f3, v252
	v_and_b32_e32 v252, 0xffff0000, v13
	v_lshlrev_b32_e32 v13, 16, v13
	v_fmac_f32_e32 v246, 0x3fb504f3, v13
	v_fmac_f32_e32 v247, 0x3fb504f3, v252
	v_add_f32_e32 v252, v244, v245
	v_add_f32_e32 v253, v246, v247
	v_add_f32_e32 v252, v252, v253
	v_add_f32_e32 v254, v254, v252
	v_and_b32_e32 v252, 0xffff0000, v14
	v_lshlrev_b32_e32 v14, 16, v14
	v_fmac_f32_e32 v248, 0x3fb504f3, v14
	v_fmac_f32_e32 v249, 0x3fb504f3, v252
	v_and_b32_e32 v252, 0xffff0000, v15
	v_lshlrev_b32_e32 v15, 16, v15
	v_fmac_f32_e32 v250, 0x3fb504f3, v15
	v_fmac_f32_e32 v251, 0x3fb504f3, v252
	v_add_f32_e32 v252, v248, v249
	v_add_f32_e32 v253, v250, v251
	v_add_f32_e32 v252, v252, v253
	v_add_f32_e32 v254, v254, v252
	s_nop 1
	v_add_f32_dpp v252, v254, v254 quad_perm:[1,0,3,2] row_mask:0xf bank_mask:0xf
	s_nop 1
	v_add_f32_dpp v252, v252, v252 quad_perm:[2,3,0,1] row_mask:0xf bank_mask:0xf
	s_nop 1
	v_add_f32_dpp v252, v252, v252 row_half_mirror row_mask:0xf bank_mask:0xf
	s_nop 1
	v_add_f32_dpp v252, v252, v252 row_mirror row_mask:0xf bank_mask:0xf
	s_nop 1
	v_readlane_b32 s86, v252, 0
	v_readlane_b32 s87, v252, 16
	v_readlane_b32 s88, v252, 32
	v_readlane_b32 s89, v252, 48
	s_nop 1
	v_mov_b32_e32 v253, s86
	v_add_f32_e32 v253, s87, v253
	v_add_f32_e32 v253, s88, v253
	v_add_f32_e32 v253, s89, v253
	v_mul_f32_e32 v253, 0x3a000000, v253
	s_nop 0
	v_readfirstlane_b32 s85, v253
	s_nop 1
	v_subrev_f32_e32 v64, s85, v64
	v_subrev_f32_e32 v65, s85, v65
	v_subrev_f32_e32 v66, s85, v66
	v_subrev_f32_e32 v67, s85, v67
	v_subrev_f32_e32 v68, s85, v68
	v_subrev_f32_e32 v69, s85, v69
	v_subrev_f32_e32 v70, s85, v70
	v_subrev_f32_e32 v71, s85, v71
	v_mul_f32_e32 v252, v64, v64
	v_fmac_f32_e32 v252, v65, v65
	v_mul_f32_e32 v253, v66, v66
	v_fmac_f32_e32 v253, v67, v67
	v_add_f32_e32 v254, v252, v253
	v_mul_f32_e32 v252, v68, v68
	v_fmac_f32_e32 v252, v69, v69
	v_mul_f32_e32 v253, v70, v70
	v_fmac_f32_e32 v253, v71, v71
	v_add_f32_e32 v252, v252, v253
	v_add_f32_e32 v254, v254, v252
	v_subrev_f32_e32 v72, s85, v72
	v_subrev_f32_e32 v73, s85, v73
	v_subrev_f32_e32 v74, s85, v74
	v_subrev_f32_e32 v75, s85, v75
	v_subrev_f32_e32 v76, s85, v76
	v_subrev_f32_e32 v77, s85, v77
	v_subrev_f32_e32 v78, s85, v78
	v_subrev_f32_e32 v79, s85, v79
	v_mul_f32_e32 v252, v72, v72
	v_fmac_f32_e32 v252, v73, v73
	v_mul_f32_e32 v253, v74, v74
	v_fmac_f32_e32 v253, v75, v75
	v_add_f32_e32 v252, v252, v253
	v_add_f32_e32 v254, v254, v252
	v_mul_f32_e32 v252, v76, v76
	v_fmac_f32_e32 v252, v77, v77
	v_mul_f32_e32 v253, v78, v78
	v_fmac_f32_e32 v253, v79, v79
	v_add_f32_e32 v252, v252, v253
	v_add_f32_e32 v254, v254, v252
	v_subrev_f32_e32 v80, s85, v80
	v_subrev_f32_e32 v81, s85, v81
	v_subrev_f32_e32 v82, s85, v82
	v_subrev_f32_e32 v83, s85, v83
	v_subrev_f32_e32 v84, s85, v84
	v_subrev_f32_e32 v85, s85, v85
	v_subrev_f32_e32 v86, s85, v86
	v_subrev_f32_e32 v87, s85, v87
	v_mul_f32_e32 v252, v80, v80
	v_fmac_f32_e32 v252, v81, v81
	v_mul_f32_e32 v253, v82, v82
	v_fmac_f32_e32 v253, v83, v83
	v_add_f32_e32 v252, v252, v253
	v_add_f32_e32 v254, v254, v252
	v_mul_f32_e32 v252, v84, v84
	v_fmac_f32_e32 v252, v85, v85
	v_mul_f32_e32 v253, v86, v86
	v_fmac_f32_e32 v253, v87, v87
	v_add_f32_e32 v252, v252, v253
	v_add_f32_e32 v254, v254, v252
	v_subrev_f32_e32 v244, s85, v244
	v_subrev_f32_e32 v245, s85, v245
	v_subrev_f32_e32 v246, s85, v246
	v_subrev_f32_e32 v247, s85, v247
	v_subrev_f32_e32 v248, s85, v248
	v_subrev_f32_e32 v249, s85, v249
	v_subrev_f32_e32 v250, s85, v250
	v_subrev_f32_e32 v251, s85, v251
	v_mul_f32_e32 v252, v244, v244
	v_fmac_f32_e32 v252, v245, v245
	v_mul_f32_e32 v253, v246, v246
	v_fmac_f32_e32 v253, v247, v247
	v_add_f32_e32 v252, v252, v253
	v_add_f32_e32 v254, v254, v252
	v_mul_f32_e32 v252, v248, v248
	v_fmac_f32_e32 v252, v249, v249
	v_mul_f32_e32 v253, v250, v250
	v_fmac_f32_e32 v253, v251, v251
	v_add_f32_e32 v252, v252, v253
	v_add_f32_e32 v254, v254, v252
	s_nop 1
	v_add_f32_dpp v252, v254, v254 quad_perm:[1,0,3,2] row_mask:0xf bank_mask:0xf
	s_nop 1
	v_add_f32_dpp v252, v252, v252 quad_perm:[2,3,0,1] row_mask:0xf bank_mask:0xf
	s_nop 1
	v_add_f32_dpp v252, v252, v252 row_half_mirror row_mask:0xf bank_mask:0xf
	s_nop 1
	v_add_f32_dpp v252, v252, v252 row_mirror row_mask:0xf bank_mask:0xf
	s_nop 1
	v_readlane_b32 s86, v252, 0
	v_readlane_b32 s87, v252, 16
	v_readlane_b32 s88, v252, 32
	v_readlane_b32 s89, v252, 48
	s_nop 1
	v_mov_b32_e32 v253, s86
	v_add_f32_e32 v253, s87, v253
	v_add_f32_e32 v253, s88, v253
	v_add_f32_e32 v253, s89, v253
	v_mov_b32_e32 v252, 0x3a000000
	v_fmaak_f32 v253, v253, v252, 0x3727c5ac
	v_rsq_f32_e32 v253, v253
	s_nop 1
	v_readfirstlane_b32 s85, v253
	s_add_u32 s12, s4, 0x2000000
	s_addc_u32 s13, s5, 0
	v_readlane_b32 s86, v241, 7
	v_readlane_b32 s87, v241, 8
	s_add_u32 s86, s86, 0x4000000
	s_addc_u32 s87, s87, 0
	s_add_u32 s88, s86, 0x1000
	s_addc_u32 s89, s87, 0
	ds_read_b64 v[252:253], v168
	ds_read_b64 v[254:255], v168 offset:8192
	ds_read_b64 v[88:89], v168 offset:512
	ds_read_b64 v[242:243], v168 offset:8704
	s_waitcnt lgkmcnt(2)
	v_mul_f32_e32 v64, s85, v64
	v_mul_f32_e32 v65, s85, v65
	v_fma_f32 v64, v64, v252, v254
	v_fma_f32 v65, v65, v253, v255
	ds_read_b64 v[252:253], v168 offset:1024
	ds_read_b64 v[254:255], v168 offset:9216
	s_waitcnt lgkmcnt(2)
	v_mul_f32_e32 v66, s85, v66
	v_mul_f32_e32 v67, s85, v67
	v_fma_f32 v66, v66, v88, v242
	v_fma_f32 v67, v67, v89, v243
	ds_read_b64 v[88:89], v168 offset:1536
	ds_read_b64 v[242:243], v168 offset:9728
	s_waitcnt lgkmcnt(2)
	v_mul_f32_e32 v68, s85, v68
	v_mul_f32_e32 v69, s85, v69
	v_fma_f32 v68, v68, v252, v254
	v_fma_f32 v69, v69, v253, v255
	ds_read_b64 v[252:253], v168 offset:2048
	ds_read_b64 v[254:255], v168 offset:10240
	s_waitcnt lgkmcnt(2)
	v_mul_f32_e32 v70, s85, v70
	v_mul_f32_e32 v71, s85, v71
	v_fma_f32 v70, v70, v88, v242
	v_fma_f32 v71, v71, v89, v243
	s_cmp_lg_u32 s90, 0
	s_cbranch_scc1 .Lln2_f32_35
	v_cvt_pk_bf16_f32 v64, v64, v65
	v_cvt_pk_bf16_f32 v65, v66, v67
	v_cvt_pk_bf16_f32 v66, v68, v69
	v_cvt_pk_bf16_f32 v67, v70, v71
	global_store_dwordx4 v90, v[64:67], s[12:13]
	s_branch .Lln2_st_36

.Lln2_st_42:
	s_branch .Lln2_done

	.amdhsa_kernel _Z6mk_fwd1P
		.amdhsa_group_segment_fixed_size 0
		.amdhsa_private_segment_fixed_size 0
		.amdhsa_kernarg_size 496
		.amdhsa_user_sgpr_count 2
		.amdhsa_user_sgpr_dispatch_ptr 0
		.amdhsa_user_sgpr_queue_ptr 0
		.amdhsa_user_sgpr_kernarg_segment_ptr 1
		.amdhsa_user_sgpr_dispatch_id 0
		.amdhsa_user_sgpr_kernarg_preload_length 0
		.amdhsa_user_sgpr_kernarg_preload_offset 0
		.amdhsa_user_sgpr_private_segment_size 0
		.amdhsa_uses_dynamic_stack 0
		.amdhsa_enable_private_segment 0
		.amdhsa_system_sgpr_workgroup_id_x 1
		.amdhsa_system_sgpr_workgroup_id_y 0
		.amdhsa_system_sgpr_workgroup_id_z 0
		.amdhsa_system_sgpr_workgroup_info 0
		.amdhsa_system_vgpr_workitem_id 2
		.amdhsa_next_free_vgpr 256
		.amdhsa_next_free_sgpr 100
		.amdhsa_accum_offset 256
		.amdhsa_reserve_vcc 1
		.amdhsa_float_round_mode_32 0
		.amdhsa_float_round_mode_16_64 0
		.amdhsa_float_denorm_mode_32 3
		.amdhsa_float_denorm_mode_16_64 3
		.amdhsa_dx10_clamp 1
		.amdhsa_ieee_mode 1
		.amdhsa_fp16_overflow 0
		.amdhsa_tg_split 0
		.amdhsa_exception_fp_ieee_invalid_op 0
		.amdhsa_exception_fp_denorm_src 0
		.amdhsa_exception_fp_ieee_div_zero 0
		.amdhsa_exception_fp_ieee_overflow 0
		.amdhsa_exception_fp_ieee_underflow 0
		.amdhsa_exception_fp_ieee_inexact 0
		.amdhsa_exception_int_div_zero 0
	.end_amdhsa_kernel

amdhsa.kernels:
  - .agpr_count:     0
    .args:
      - .offset:         0
        .size:           240
        .value_kind:     by_value
      - .offset:         240
        .size:           4
        .value_kind:     hidden_block_count_x
      - .offset:         244
        .size:           4
        .value_kind:     hidden_block_count_y
      - .offset:         248
        .size:           4
        .value_kind:     hidden_block_count_z
      - .offset:         252
        .size:           2
        .value_kind:     hidden_group_size_x
      - .offset:         254
        .size:           2
        .value_kind:     hidden_group_size_y
      - .offset:         256
        .size:           2
        .value_kind:     hidden_group_size_z
      - .offset:         258
        .size:           2
        .value_kind:     hidden_remainder_x
      - .offset:         260
        .size:           2
        .value_kind:     hidden_remainder_y
      - .offset:         262
        .size:           2
        .value_kind:     hidden_remainder_z
      - .offset:         280
        .size:           8
        .value_kind:     hidden_global_offset_x
      - .offset:         288
        .size:           8
        .value_kind:     hidden_global_offset_y
      - .offset:         296
        .size:           8
        .value_kind:     hidden_global_offset_z
      - .offset:         304
        .size:           2
        .value_kind:     hidden_grid_dims
      - .offset:         328
        .size:           8
        .value_kind:     hidden_multigrid_sync_arg
      - .offset:         360
        .size:           4
        .value_kind:     hidden_dynamic_lds_size
    .group_segment_fixed_size: 0
    .kernarg_segment_align: 8
    .kernarg_segment_size: 496
    .language:       OpenCL C
    .language_version:
      - 2
      - 0
    .max_flat_workgroup_size: 512
    .name:           _Z6mk_fwd1P
    .private_segment_fixed_size: 0
    .sgpr_count:     106
    .sgpr_spill_count: 201
    .symbol:         _Z6mk_fwd1P.kd
    .uniform_work_group_size: 1
    .uses_dynamic_stack: false
    .vgpr_count:     256
    .vgpr_spill_count: 0
    .wavefront_size: 64
